# scan consumer and producer loop heads placed on 64-byte boundaries (plus 8-byte alignment of all hand-written 8-byte instructions)
# baseline (speedup 1.0000x reference)
.LBB0_56:
	s_and_b64 s[4:5], s[42:43], exec
	s_mov_b32 s4, 0x1caf0000
	s_cselect_b32 s4, s4, 0x14af0000
	s_add_u32 s4, s30, s4
	s_addc_u32 s5, s31, 0
	s_lshl_b32 s6, s37, 1
	v_lshl_add_u32 v0, s64, 4, v58
	s_add_u32 s4, s4, s6
	s_addc_u32 s5, s5, 0
	v_ashrrev_i32_e32 v1, 31, v0
	s_waitcnt lgkmcnt(0)
	s_barrier
	v_lshl_add_u64 v[0:1], v[0:1], 1, s[4:5]
	s_and_b64 s[4:5], s[42:43], exec
	s_movk_i32 s4, 0x4000
	s_mov_b32 s28, 0
	s_cselect_b32 s85, 0, -1
	s_cselect_b32 s84, s4, 0xffffc000
	s_waitcnt vmcnt(0)
	v_mov_b32_e32 v6, 0
	v_mov_b32_e32 v4, v78
	v_mov_b32_e32 v5, v15
	v_mov_b32_e32 v7, 0
	v_mov_b32_e32 v8, 0
	v_mov_b32_e32 v9, 0
	v_lshlrev_b32_e32 v74, 4, v58
	v_add_u32_e32 v74, 0x22000, v74
	s_mov_b64 s[100:101], 0
	v_mov_b32_e32 v10, v59
	v_mov_b32_e32 v11, v74
	ds_read_b128 v[66:69], v11 offset:0
	ds_read_b128 v[20:23], v10 offset:256
	ds_read_b128 v[28:31], v10 offset:768
	ds_read_b128 v[24:27], v10 offset:512
	ds_read_b128 v[36:39], v10 offset:1280
	ds_read_b128 v[44:47], v10 offset:1792
	ds_read_b128 v[40:43], v10 offset:1536
	s_nop 0
	s_nop 0
	s_nop 0
.Lscan_cons_chunk:
	v_cndmask_b32_e64 v2, v4, v5, s[42:43]
	v_add_lshl_u32 v2, v2, s80, 10
	v_mov_b32_e64 v3, v180
	s_add_i32 s28, s28, 0x10000
	v_lshl_add_u64 v[2:3], v[0:1], 0, v[2:3]
	v_add_u32_e64 v5, 64, v5
	v_subrev_u32_e64 v4, 64, v4
	s_waitcnt lgkmcnt(0)
	s_nop 0
	ds_read_b128 v[88:91], v10 offset:2304
	ds_read_b128 v[96:99], v10 offset:2816
	ds_read_b128 v[92:95], v10 offset:2560
	v_fma_mix_f32 v12, v6, v20, v180 op_sel_hi:[0,1,0]
	v_fma_mix_f32 v12, v7, v20, v12 op_sel:[0,1,0] op_sel_hi:[0,1,0]
	v_fma_mix_f32 v12, v8, v21, v12 op_sel_hi:[0,1,0]
	v_fma_mix_f32 v12, v9, v21, v12 op_sel:[0,1,0] op_sel_hi:[0,1,0]
	s_nop 1
	s_nop 0
	v_add_f32_dpp v12, v12, v12 row_ror:1 row_mask:0xf bank_mask:0xf bound_ctrl:1
	s_nop 1
	s_nop 0
	v_add_f32_dpp v12, v12, v12 row_ror:2 row_mask:0xf bank_mask:0xf bound_ctrl:1
	v_pk_fma_f32 v[48:49], v[28:29], v[66:67], v[6:7] op_sel_hi:[1,0,1]
	v_pk_fma_f32 v[50:51], v[30:31], v[66:67], v[8:9] op_sel_hi:[1,0,1]
	v_add_f32_dpp v12, v12, v12 row_ror:4 row_mask:0xf bank_mask:0xf bound_ctrl:1
	v_add_f32_dpp v130, v130, v130 row_ror:8 row_mask:0xf bank_mask:0xc
	v_add_f32_dpp v130, v122, v122 row_ror:8 row_mask:0xf bank_mask:0x3
	v_add_f32_dpp v131, v131, v131 row_ror:8 row_mask:0xf bank_mask:0xc
	v_add_f32_dpp v12, v12, v12 row_ror:8 row_mask:0xf bank_mask:0xf bound_ctrl:1
	v_pk_fma_f32 v[6:7], v[24:25], v[12:13], v[48:49] op_sel_hi:[1,0,1] neg_lo:[1,0,0] neg_hi:[1,0,0]
	v_pk_fma_f32 v[8:9], v[26:27], v[12:13], v[50:51] op_sel_hi:[1,0,1] neg_lo:[1,0,0] neg_hi:[1,0,0]
	ds_read_b128 v[110:113], v10 offset:3328
	ds_read_b128 v[106:109], v10 offset:3072
	ds_read_b128 v[118:121], v10 offset:3840
	ds_read_b128 v[114:117], v10 offset:3584
	ds_read_b128 v[70:73], v11 offset:256
	v_fma_mix_f32 v12, v6, v36, v180 op_sel_hi:[0,1,0]
	v_fma_mix_f32 v12, v7, v36, v12 op_sel:[0,1,0] op_sel_hi:[0,1,0]
	v_fma_mix_f32 v12, v8, v37, v12 op_sel_hi:[0,1,0]
	v_fma_mix_f32 v12, v9, v37, v12 op_sel:[0,1,0] op_sel_hi:[0,1,0]
	v_fma_mix_f32 v52, v6, v22, v180 op_sel_hi:[0,1,0]
	v_fma_mix_f32 v52, v7, v22, v52 op_sel:[0,1,0] op_sel_hi:[0,1,0]
	v_add_f32_dpp v12, v12, v12 row_ror:1 row_mask:0xf bank_mask:0xf bound_ctrl:1
	v_fma_mix_f32 v52, v8, v23, v52 op_sel_hi:[0,1,0]
	v_fma_mix_f32 v52, v9, v23, v52 op_sel:[0,1,0] op_sel_hi:[0,1,0]
	v_add_f32_dpp v12, v12, v12 row_ror:2 row_mask:0xf bank_mask:0xf bound_ctrl:1
	v_pk_fma_f32 v[48:49], v[44:45], v[66:67], v[6:7] op_sel:[0,1,0]
	v_pk_fma_f32 v[50:51], v[46:47], v[66:67], v[8:9] op_sel:[0,1,0]
	v_add_f32_dpp v12, v12, v12 row_ror:4 row_mask:0xf bank_mask:0xf bound_ctrl:1
	v_add_f32_dpp v131, v123, v123 row_ror:8 row_mask:0xf bank_mask:0x3
	v_add_f32_dpp v132, v132, v132 row_ror:8 row_mask:0xf bank_mask:0xc
	v_add_f32_dpp v132, v124, v124 row_ror:8 row_mask:0xf bank_mask:0x3
	v_add_f32_dpp v12, v12, v12 row_ror:8 row_mask:0xf bank_mask:0xf bound_ctrl:1
	v_pk_fma_f32 v[6:7], v[40:41], v[12:13], v[48:49] op_sel_hi:[1,0,1] neg_lo:[1,0,0] neg_hi:[1,0,0]
	v_pk_fma_f32 v[8:9], v[42:43], v[12:13], v[50:51] op_sel_hi:[1,0,1] neg_lo:[1,0,0] neg_hi:[1,0,0]
	s_waitcnt lgkmcnt(1)
	s_nop 0
	ds_read_b128 v[20:23], v10 offset:4352
	ds_read_b128 v[28:31], v10 offset:4864
	ds_read_b128 v[24:27], v10 offset:4608
	v_fma_mix_f32 v12, v6, v88, v180 op_sel_hi:[0,1,0]
	v_fma_mix_f32 v12, v7, v88, v12 op_sel:[0,1,0] op_sel_hi:[0,1,0]
	v_fma_mix_f32 v12, v8, v89, v12 op_sel_hi:[0,1,0]
	v_fma_mix_f32 v12, v9, v89, v12 op_sel:[0,1,0] op_sel_hi:[0,1,0]
	v_fma_mix_f32 v53, v6, v38, v180 op_sel_hi:[0,1,0]
	v_fma_mix_f32 v53, v7, v38, v53 op_sel:[0,1,0] op_sel_hi:[0,1,0]
	v_add_f32_dpp v12, v12, v12 row_ror:1 row_mask:0xf bank_mask:0xf bound_ctrl:1
	v_fma_mix_f32 v53, v8, v39, v53 op_sel_hi:[0,1,0]
	v_fma_mix_f32 v53, v9, v39, v53 op_sel:[0,1,0] op_sel_hi:[0,1,0]
	v_add_f32_dpp v12, v12, v12 row_ror:2 row_mask:0xf bank_mask:0xf bound_ctrl:1
	v_pk_fma_f32 v[48:49], v[96:97], v[68:69], v[6:7] op_sel_hi:[1,0,1]
	v_pk_fma_f32 v[50:51], v[98:99], v[68:69], v[8:9] op_sel_hi:[1,0,1]
	v_add_f32_dpp v12, v12, v12 row_ror:4 row_mask:0xf bank_mask:0xf bound_ctrl:1
	v_add_f32_dpp v133, v133, v133 row_ror:8 row_mask:0xf bank_mask:0xc
	v_add_f32_dpp v133, v125, v125 row_ror:8 row_mask:0xf bank_mask:0x3
	v_add_f32_dpp v134, v134, v134 row_ror:8 row_mask:0xf bank_mask:0xc
	v_add_f32_dpp v12, v12, v12 row_ror:8 row_mask:0xf bank_mask:0xf bound_ctrl:1
	v_pk_fma_f32 v[6:7], v[92:93], v[12:13], v[48:49] op_sel_hi:[1,0,1] neg_lo:[1,0,0] neg_hi:[1,0,0]
	v_pk_fma_f32 v[8:9], v[94:95], v[12:13], v[50:51] op_sel_hi:[1,0,1] neg_lo:[1,0,0] neg_hi:[1,0,0]
	ds_read_b128 v[36:39], v10 offset:5376
	ds_read_b128 v[44:47], v10 offset:5888
	ds_read_b128 v[40:43], v10 offset:5632
	v_fma_mix_f32 v12, v6, v110, v180 op_sel_hi:[0,1,0]
	v_fma_mix_f32 v12, v7, v110, v12 op_sel:[0,1,0] op_sel_hi:[0,1,0]
	v_fma_mix_f32 v12, v8, v111, v12 op_sel_hi:[0,1,0]
	v_fma_mix_f32 v12, v9, v111, v12 op_sel:[0,1,0] op_sel_hi:[0,1,0]
	v_fma_mix_f32 v54, v6, v90, v180 op_sel_hi:[0,1,0]
	v_fma_mix_f32 v54, v7, v90, v54 op_sel:[0,1,0] op_sel_hi:[0,1,0]
	v_add_f32_dpp v12, v12, v12 row_ror:1 row_mask:0xf bank_mask:0xf bound_ctrl:1
	v_fma_mix_f32 v54, v8, v91, v54 op_sel_hi:[0,1,0]
	v_fma_mix_f32 v54, v9, v91, v54 op_sel:[0,1,0] op_sel_hi:[0,1,0]
	v_add_f32_dpp v12, v12, v12 row_ror:2 row_mask:0xf bank_mask:0xf bound_ctrl:1
	v_pk_fma_f32 v[48:49], v[118:119], v[68:69], v[6:7] op_sel:[0,1,0]
	v_pk_fma_f32 v[50:51], v[120:121], v[68:69], v[8:9] op_sel:[0,1,0]
	v_add_f32_dpp v12, v12, v12 row_ror:4 row_mask:0xf bank_mask:0xf bound_ctrl:1
	v_add_f32_dpp v134, v126, v126 row_ror:8 row_mask:0xf bank_mask:0x3
	v_add_f32_dpp v135, v135, v135 row_ror:8 row_mask:0xf bank_mask:0xc
	v_add_f32_dpp v135, v127, v127 row_ror:8 row_mask:0xf bank_mask:0x3
	v_add_f32_dpp v12, v12, v12 row_ror:8 row_mask:0xf bank_mask:0xf bound_ctrl:1
	v_pk_fma_f32 v[6:7], v[114:115], v[12:13], v[48:49] op_sel_hi:[1,0,1] neg_lo:[1,0,0] neg_hi:[1,0,0]
	v_pk_fma_f32 v[8:9], v[116:117], v[12:13], v[50:51] op_sel_hi:[1,0,1] neg_lo:[1,0,0] neg_hi:[1,0,0]
	v_pk_mul_f32 v[6:7], v[6:7], v[106:107]
	v_pk_mul_f32 v[8:9], v[8:9], v[108:109]
	s_waitcnt lgkmcnt(0)
	s_nop 0
	ds_read_b128 v[88:91], v10 offset:6400
	ds_read_b128 v[96:99], v10 offset:6912
	ds_read_b128 v[92:95], v10 offset:6656
	v_fma_mix_f32 v12, v6, v20, v180 op_sel_hi:[0,1,0]
	v_fma_mix_f32 v12, v7, v20, v12 op_sel:[0,1,0] op_sel_hi:[0,1,0]
	v_fma_mix_f32 v12, v8, v21, v12 op_sel_hi:[0,1,0]
	v_fma_mix_f32 v12, v9, v21, v12 op_sel:[0,1,0] op_sel_hi:[0,1,0]
	v_fma_mix_f32 v55, v6, v112, v180 op_sel_hi:[0,1,0]
	v_fma_mix_f32 v55, v7, v112, v55 op_sel:[0,1,0] op_sel_hi:[0,1,0]
	v_add_f32_dpp v12, v12, v12 row_ror:1 row_mask:0xf bank_mask:0xf bound_ctrl:1
	v_fma_mix_f32 v55, v8, v113, v55 op_sel_hi:[0,1,0]
	v_fma_mix_f32 v55, v9, v113, v55 op_sel:[0,1,0] op_sel_hi:[0,1,0]
	v_add_f32_dpp v12, v12, v12 row_ror:2 row_mask:0xf bank_mask:0xf bound_ctrl:1
	v_pk_fma_f32 v[48:49], v[28:29], v[70:71], v[6:7] op_sel_hi:[1,0,1]
	v_pk_fma_f32 v[50:51], v[30:31], v[70:71], v[8:9] op_sel_hi:[1,0,1]
	v_add_f32_dpp v12, v12, v12 row_ror:4 row_mask:0xf bank_mask:0xf bound_ctrl:1
	v_add_f32_dpp v136, v136, v136 row_ror:8 row_mask:0xf bank_mask:0xc
	v_add_f32_dpp v136, v128, v128 row_ror:8 row_mask:0xf bank_mask:0x3
	v_add_f32_dpp v12, v12, v12 row_ror:8 row_mask:0xf bank_mask:0xf bound_ctrl:1
	v_pk_fma_f32 v[6:7], v[24:25], v[12:13], v[48:49] op_sel_hi:[1,0,1] neg_lo:[1,0,0] neg_hi:[1,0,0]
	v_pk_fma_f32 v[8:9], v[26:27], v[12:13], v[50:51] op_sel_hi:[1,0,1] neg_lo:[1,0,0] neg_hi:[1,0,0]
	ds_read_b128 v[110:113], v10 offset:7424
	ds_read_b128 v[106:109], v10 offset:7168
	ds_read_b128 v[118:121], v10 offset:7936
	ds_read_b128 v[114:117], v10 offset:7680
	ds_read_b128 v[66:69], v11 offset:512
	v_fma_mix_f32 v12, v6, v36, v180 op_sel_hi:[0,1,0]
	v_fma_mix_f32 v12, v7, v36, v12 op_sel:[0,1,0] op_sel_hi:[0,1,0]
	v_fma_mix_f32 v12, v8, v37, v12 op_sel_hi:[0,1,0]
	v_fma_mix_f32 v12, v9, v37, v12 op_sel:[0,1,0] op_sel_hi:[0,1,0]
	v_fma_mix_f32 v56, v6, v22, v180 op_sel_hi:[0,1,0]
	v_fma_mix_f32 v56, v7, v22, v56 op_sel:[0,1,0] op_sel_hi:[0,1,0]
	v_add_f32_dpp v12, v12, v12 row_ror:1 row_mask:0xf bank_mask:0xf bound_ctrl:1
	v_fma_mix_f32 v56, v8, v23, v56 op_sel_hi:[0,1,0]
	v_fma_mix_f32 v56, v9, v23, v56 op_sel:[0,1,0] op_sel_hi:[0,1,0]
	v_add_f32_dpp v12, v12, v12 row_ror:2 row_mask:0xf bank_mask:0xf bound_ctrl:1
	v_pk_fma_f32 v[48:49], v[44:45], v[70:71], v[6:7] op_sel:[0,1,0]
	v_pk_fma_f32 v[50:51], v[46:47], v[70:71], v[8:9] op_sel:[0,1,0]
	v_add_f32_dpp v12, v12, v12 row_ror:4 row_mask:0xf bank_mask:0xf bound_ctrl:1
	v_add_f32_dpp v137, v137, v137 row_ror:8 row_mask:0xf bank_mask:0xc
	v_add_f32_dpp v137, v129, v129 row_ror:8 row_mask:0xf bank_mask:0x3
	v_add_f32_dpp v12, v12, v12 row_ror:8 row_mask:0xf bank_mask:0xf bound_ctrl:1
	v_pk_fma_f32 v[6:7], v[40:41], v[12:13], v[48:49] op_sel_hi:[1,0,1] neg_lo:[1,0,0] neg_hi:[1,0,0]
	v_pk_fma_f32 v[8:9], v[42:43], v[12:13], v[50:51] op_sel_hi:[1,0,1] neg_lo:[1,0,0] neg_hi:[1,0,0]
	s_waitcnt lgkmcnt(1)
	s_nop 0
	ds_read_b128 v[20:23], v10 offset:8448
	ds_read_b128 v[28:31], v10 offset:8960
	ds_read_b128 v[24:27], v10 offset:8704
	v_fma_mix_f32 v12, v6, v88, v180 op_sel_hi:[0,1,0]
	v_fma_mix_f32 v12, v7, v88, v12 op_sel:[0,1,0] op_sel_hi:[0,1,0]
	v_fma_mix_f32 v12, v8, v89, v12 op_sel_hi:[0,1,0]
	v_fma_mix_f32 v12, v9, v89, v12 op_sel:[0,1,0] op_sel_hi:[0,1,0]
	v_fma_mix_f32 v57, v6, v38, v180 op_sel_hi:[0,1,0]
	v_fma_mix_f32 v57, v7, v38, v57 op_sel:[0,1,0] op_sel_hi:[0,1,0]
	v_add_f32_dpp v12, v12, v12 row_ror:1 row_mask:0xf bank_mask:0xf bound_ctrl:1
	v_fma_mix_f32 v57, v8, v39, v57 op_sel_hi:[0,1,0]
	v_fma_mix_f32 v57, v9, v39, v57 op_sel:[0,1,0] op_sel_hi:[0,1,0]
	v_add_f32_dpp v12, v12, v12 row_ror:2 row_mask:0xf bank_mask:0xf bound_ctrl:1
	v_pk_fma_f32 v[48:49], v[96:97], v[72:73], v[6:7] op_sel_hi:[1,0,1]
	v_pk_fma_f32 v[50:51], v[98:99], v[72:73], v[8:9] op_sel_hi:[1,0,1]
	v_add_f32_dpp v12, v12, v12 row_ror:4 row_mask:0xf bank_mask:0xf bound_ctrl:1
	v_add_f32_dpp v134, v134, v134 row_ror:4 row_mask:0xf bank_mask:0xa
	v_add_f32_dpp v134, v130, v130 row_ror:12 row_mask:0xf bank_mask:0x5
	v_add_f32_dpp v135, v135, v135 row_ror:4 row_mask:0xf bank_mask:0xa
	v_add_f32_dpp v12, v12, v12 row_ror:8 row_mask:0xf bank_mask:0xf bound_ctrl:1
	v_pk_fma_f32 v[6:7], v[92:93], v[12:13], v[48:49] op_sel_hi:[1,0,1] neg_lo:[1,0,0] neg_hi:[1,0,0]
	v_pk_fma_f32 v[8:9], v[94:95], v[12:13], v[50:51] op_sel_hi:[1,0,1] neg_lo:[1,0,0] neg_hi:[1,0,0]
	ds_read_b128 v[36:39], v10 offset:9472
	ds_read_b128 v[44:47], v10 offset:9984
	ds_read_b128 v[40:43], v10 offset:9728
	v_fma_mix_f32 v12, v6, v110, v180 op_sel_hi:[0,1,0]
	v_fma_mix_f32 v12, v7, v110, v12 op_sel:[0,1,0] op_sel_hi:[0,1,0]
	v_fma_mix_f32 v12, v8, v111, v12 op_sel_hi:[0,1,0]
	v_fma_mix_f32 v12, v9, v111, v12 op_sel:[0,1,0] op_sel_hi:[0,1,0]
	v_fma_mix_f32 v81, v6, v90, v180 op_sel_hi:[0,1,0]
	v_fma_mix_f32 v81, v7, v90, v81 op_sel:[0,1,0] op_sel_hi:[0,1,0]
	v_add_f32_dpp v12, v12, v12 row_ror:1 row_mask:0xf bank_mask:0xf bound_ctrl:1
	v_fma_mix_f32 v81, v8, v91, v81 op_sel_hi:[0,1,0]
	v_fma_mix_f32 v81, v9, v91, v81 op_sel:[0,1,0] op_sel_hi:[0,1,0]
	v_add_f32_dpp v12, v12, v12 row_ror:2 row_mask:0xf bank_mask:0xf bound_ctrl:1
	v_pk_fma_f32 v[48:49], v[118:119], v[72:73], v[6:7] op_sel:[0,1,0]
	v_pk_fma_f32 v[50:51], v[120:121], v[72:73], v[8:9] op_sel:[0,1,0]
	v_add_f32_dpp v12, v12, v12 row_ror:4 row_mask:0xf bank_mask:0xf bound_ctrl:1
	v_add_f32_dpp v135, v131, v131 row_ror:12 row_mask:0xf bank_mask:0x5
	v_add_f32_dpp v136, v136, v136 row_ror:4 row_mask:0xf bank_mask:0xa
	v_add_f32_dpp v136, v132, v132 row_ror:12 row_mask:0xf bank_mask:0x5
	v_add_f32_dpp v12, v12, v12 row_ror:8 row_mask:0xf bank_mask:0xf bound_ctrl:1
	v_pk_fma_f32 v[6:7], v[114:115], v[12:13], v[48:49] op_sel_hi:[1,0,1] neg_lo:[1,0,0] neg_hi:[1,0,0]
	v_pk_fma_f32 v[8:9], v[116:117], v[12:13], v[50:51] op_sel_hi:[1,0,1] neg_lo:[1,0,0] neg_hi:[1,0,0]
	v_pk_mul_f32 v[6:7], v[6:7], v[106:107]
	v_pk_mul_f32 v[8:9], v[8:9], v[108:109]
	s_waitcnt lgkmcnt(0)
	s_nop 0
	ds_read_b128 v[88:91], v10 offset:10496
	ds_read_b128 v[96:99], v10 offset:11008
	ds_read_b128 v[92:95], v10 offset:10752
	v_fma_mix_f32 v12, v6, v20, v180 op_sel_hi:[0,1,0]
	v_fma_mix_f32 v12, v7, v20, v12 op_sel:[0,1,0] op_sel_hi:[0,1,0]
	v_fma_mix_f32 v12, v8, v21, v12 op_sel_hi:[0,1,0]
	v_fma_mix_f32 v12, v9, v21, v12 op_sel:[0,1,0] op_sel_hi:[0,1,0]
	v_fma_mix_f32 v82, v6, v112, v180 op_sel_hi:[0,1,0]
	v_fma_mix_f32 v82, v7, v112, v82 op_sel:[0,1,0] op_sel_hi:[0,1,0]
	v_add_f32_dpp v12, v12, v12 row_ror:1 row_mask:0xf bank_mask:0xf bound_ctrl:1
	v_fma_mix_f32 v82, v8, v113, v82 op_sel_hi:[0,1,0]
	v_fma_mix_f32 v82, v9, v113, v82 op_sel:[0,1,0] op_sel_hi:[0,1,0]
	v_add_f32_dpp v12, v12, v12 row_ror:2 row_mask:0xf bank_mask:0xf bound_ctrl:1
	v_pk_fma_f32 v[48:49], v[28:29], v[66:67], v[6:7] op_sel_hi:[1,0,1]
	v_pk_fma_f32 v[50:51], v[30:31], v[66:67], v[8:9] op_sel_hi:[1,0,1]
	v_add_f32_dpp v12, v12, v12 row_ror:4 row_mask:0xf bank_mask:0xf bound_ctrl:1
	v_add_f32_dpp v137, v137, v137 row_ror:4 row_mask:0xf bank_mask:0xa
	v_add_f32_dpp v137, v133, v133 row_ror:12 row_mask:0xf bank_mask:0x5
	v_add_f32_dpp v12, v12, v12 row_ror:8 row_mask:0xf bank_mask:0xf bound_ctrl:1
	v_pk_fma_f32 v[6:7], v[24:25], v[12:13], v[48:49] op_sel_hi:[1,0,1] neg_lo:[1,0,0] neg_hi:[1,0,0]
	v_pk_fma_f32 v[8:9], v[26:27], v[12:13], v[50:51] op_sel_hi:[1,0,1] neg_lo:[1,0,0] neg_hi:[1,0,0]
	ds_read_b128 v[110:113], v10 offset:11520
	ds_read_b128 v[106:109], v10 offset:11264
	ds_read_b128 v[118:121], v10 offset:12032
	ds_read_b128 v[114:117], v10 offset:11776
	ds_read_b128 v[70:73], v11 offset:768
	v_fma_mix_f32 v12, v6, v36, v180 op_sel_hi:[0,1,0]
	v_fma_mix_f32 v12, v7, v36, v12 op_sel:[0,1,0] op_sel_hi:[0,1,0]
	v_fma_mix_f32 v12, v8, v37, v12 op_sel_hi:[0,1,0]
	v_fma_mix_f32 v12, v9, v37, v12 op_sel:[0,1,0] op_sel_hi:[0,1,0]
	v_fma_mix_f32 v83, v6, v22, v180 op_sel_hi:[0,1,0]
	v_fma_mix_f32 v83, v7, v22, v83 op_sel:[0,1,0] op_sel_hi:[0,1,0]
	v_add_f32_dpp v12, v12, v12 row_ror:1 row_mask:0xf bank_mask:0xf bound_ctrl:1
	v_fma_mix_f32 v83, v8, v23, v83 op_sel_hi:[0,1,0]
	v_fma_mix_f32 v83, v9, v23, v83 op_sel:[0,1,0] op_sel_hi:[0,1,0]
	v_add_f32_dpp v12, v12, v12 row_ror:2 row_mask:0xf bank_mask:0xf bound_ctrl:1
	v_pk_fma_f32 v[48:49], v[44:45], v[66:67], v[6:7] op_sel:[0,1,0]
	v_pk_fma_f32 v[50:51], v[46:47], v[66:67], v[8:9] op_sel:[0,1,0]
	v_add_f32_dpp v12, v12, v12 row_ror:4 row_mask:0xf bank_mask:0xf bound_ctrl:1
	v_cndmask_b32_e64 v62, v136, v134, s[38:39]
	v_cndmask_b32_e64 v63, v134, v136, s[38:39]
	v_add_f32_dpp v12, v12, v12 row_ror:8 row_mask:0xf bank_mask:0xf bound_ctrl:1
	v_pk_fma_f32 v[6:7], v[40:41], v[12:13], v[48:49] op_sel_hi:[1,0,1] neg_lo:[1,0,0] neg_hi:[1,0,0]
	v_pk_fma_f32 v[8:9], v[42:43], v[12:13], v[50:51] op_sel_hi:[1,0,1] neg_lo:[1,0,0] neg_hi:[1,0,0]
	s_waitcnt lgkmcnt(1)
	s_nop 0
	ds_read_b128 v[20:23], v10 offset:12544
	ds_read_b128 v[28:31], v10 offset:13056
	ds_read_b128 v[24:27], v10 offset:12800
	v_fma_mix_f32 v12, v6, v88, v180 op_sel_hi:[0,1,0]
	v_fma_mix_f32 v12, v7, v88, v12 op_sel:[0,1,0] op_sel_hi:[0,1,0]
	v_fma_mix_f32 v12, v8, v89, v12 op_sel_hi:[0,1,0]
	v_fma_mix_f32 v12, v9, v89, v12 op_sel:[0,1,0] op_sel_hi:[0,1,0]
	v_fma_mix_f32 v100, v6, v38, v180 op_sel_hi:[0,1,0]
	v_fma_mix_f32 v100, v7, v38, v100 op_sel:[0,1,0] op_sel_hi:[0,1,0]
	v_add_f32_dpp v12, v12, v12 row_ror:1 row_mask:0xf bank_mask:0xf bound_ctrl:1
	v_fma_mix_f32 v100, v8, v39, v100 op_sel_hi:[0,1,0]
	v_fma_mix_f32 v100, v9, v39, v100 op_sel:[0,1,0] op_sel_hi:[0,1,0]
	v_add_f32_dpp v12, v12, v12 row_ror:2 row_mask:0xf bank_mask:0xf bound_ctrl:1
	v_pk_fma_f32 v[48:49], v[96:97], v[68:69], v[6:7] op_sel_hi:[1,0,1]
	v_pk_fma_f32 v[50:51], v[98:99], v[68:69], v[8:9] op_sel_hi:[1,0,1]
	v_add_f32_dpp v12, v12, v12 row_ror:4 row_mask:0xf bank_mask:0xf bound_ctrl:1
	v_cndmask_b32_e64 v64, v137, v135, s[38:39]
	v_cndmask_b32_e64 v65, v135, v137, s[38:39]
	v_add_f32_dpp v12, v12, v12 row_ror:8 row_mask:0xf bank_mask:0xf bound_ctrl:1
	v_pk_fma_f32 v[6:7], v[92:93], v[12:13], v[48:49] op_sel_hi:[1,0,1] neg_lo:[1,0,0] neg_hi:[1,0,0]
	v_pk_fma_f32 v[8:9], v[94:95], v[12:13], v[50:51] op_sel_hi:[1,0,1] neg_lo:[1,0,0] neg_hi:[1,0,0]
	ds_read_b128 v[36:39], v10 offset:13568
	ds_read_b128 v[44:47], v10 offset:14080
	ds_read_b128 v[40:43], v10 offset:13824
	v_fma_mix_f32 v12, v6, v110, v180 op_sel_hi:[0,1,0]
	v_fma_mix_f32 v12, v7, v110, v12 op_sel:[0,1,0] op_sel_hi:[0,1,0]
	v_fma_mix_f32 v12, v8, v111, v12 op_sel_hi:[0,1,0]
	v_fma_mix_f32 v12, v9, v111, v12 op_sel:[0,1,0] op_sel_hi:[0,1,0]
	v_fma_mix_f32 v101, v6, v90, v180 op_sel_hi:[0,1,0]
	v_fma_mix_f32 v101, v7, v90, v101 op_sel:[0,1,0] op_sel_hi:[0,1,0]
	v_add_f32_dpp v12, v12, v12 row_ror:1 row_mask:0xf bank_mask:0xf bound_ctrl:1
	v_fma_mix_f32 v101, v8, v91, v101 op_sel_hi:[0,1,0]
	v_fma_mix_f32 v101, v9, v91, v101 op_sel:[0,1,0] op_sel_hi:[0,1,0]
	v_add_f32_dpp v12, v12, v12 row_ror:2 row_mask:0xf bank_mask:0xf bound_ctrl:1
	v_pk_fma_f32 v[48:49], v[118:119], v[68:69], v[6:7] op_sel:[0,1,0]
	v_pk_fma_f32 v[50:51], v[120:121], v[68:69], v[8:9] op_sel:[0,1,0]
	v_add_f32_dpp v12, v12, v12 row_ror:4 row_mask:0xf bank_mask:0xf bound_ctrl:1
	v_add_f32_dpp v62, v63, v62 quad_perm:[2,3,0,1] row_mask:0xf bank_mask:0xf bound_ctrl:1
	v_add_f32_dpp v63, v65, v64 quad_perm:[2,3,0,1] row_mask:0xf bank_mask:0xf bound_ctrl:1
	v_add_f32_dpp v12, v12, v12 row_ror:8 row_mask:0xf bank_mask:0xf bound_ctrl:1
	v_pk_fma_f32 v[6:7], v[114:115], v[12:13], v[48:49] op_sel_hi:[1,0,1] neg_lo:[1,0,0] neg_hi:[1,0,0]
	v_pk_fma_f32 v[8:9], v[116:117], v[12:13], v[50:51] op_sel_hi:[1,0,1] neg_lo:[1,0,0] neg_hi:[1,0,0]
	v_pk_mul_f32 v[6:7], v[6:7], v[106:107]
	v_pk_mul_f32 v[8:9], v[8:9], v[108:109]
	s_waitcnt lgkmcnt(0)
	s_nop 0
	ds_read_b128 v[88:91], v10 offset:14592
	ds_read_b128 v[96:99], v10 offset:15104
	ds_read_b128 v[92:95], v10 offset:14848
	v_fma_mix_f32 v12, v6, v20, v180 op_sel_hi:[0,1,0]
	v_fma_mix_f32 v12, v7, v20, v12 op_sel:[0,1,0] op_sel_hi:[0,1,0]
	v_fma_mix_f32 v12, v8, v21, v12 op_sel_hi:[0,1,0]
	v_fma_mix_f32 v12, v9, v21, v12 op_sel:[0,1,0] op_sel_hi:[0,1,0]
	v_fma_mix_f32 v102, v6, v112, v180 op_sel_hi:[0,1,0]
	v_fma_mix_f32 v102, v7, v112, v102 op_sel:[0,1,0] op_sel_hi:[0,1,0]
	v_add_f32_dpp v12, v12, v12 row_ror:1 row_mask:0xf bank_mask:0xf bound_ctrl:1
	v_fma_mix_f32 v102, v8, v113, v102 op_sel_hi:[0,1,0]
	v_fma_mix_f32 v102, v9, v113, v102 op_sel:[0,1,0] op_sel_hi:[0,1,0]
	v_add_f32_dpp v12, v12, v12 row_ror:2 row_mask:0xf bank_mask:0xf bound_ctrl:1
	v_pk_fma_f32 v[48:49], v[28:29], v[70:71], v[6:7] op_sel_hi:[1,0,1]
	v_pk_fma_f32 v[50:51], v[30:31], v[70:71], v[8:9] op_sel_hi:[1,0,1]
	v_add_f32_dpp v12, v12, v12 row_ror:4 row_mask:0xf bank_mask:0xf bound_ctrl:1
	v_cndmask_b32_e64 v65, v63, v62, s[40:41]
	v_cndmask_b32_e64 v62, v62, v63, s[40:41]
	v_add_f32_dpp v12, v12, v12 row_ror:8 row_mask:0xf bank_mask:0xf bound_ctrl:1
	v_pk_fma_f32 v[6:7], v[24:25], v[12:13], v[48:49] op_sel_hi:[1,0,1] neg_lo:[1,0,0] neg_hi:[1,0,0]
	v_pk_fma_f32 v[8:9], v[26:27], v[12:13], v[50:51] op_sel_hi:[1,0,1] neg_lo:[1,0,0] neg_hi:[1,0,0]
	ds_read_b128 v[110:113], v10 offset:15616
	ds_read_b128 v[106:109], v10 offset:15360
	ds_read_b128 v[118:121], v10 offset:16128
	ds_read_b128 v[114:117], v10 offset:15872
	ds_read_b128 v[66:69], v11 offset:1024
	v_fma_mix_f32 v12, v6, v36, v180 op_sel_hi:[0,1,0]
	v_fma_mix_f32 v12, v7, v36, v12 op_sel:[0,1,0] op_sel_hi:[0,1,0]
	v_fma_mix_f32 v12, v8, v37, v12 op_sel_hi:[0,1,0]
	v_fma_mix_f32 v12, v9, v37, v12 op_sel:[0,1,0] op_sel_hi:[0,1,0]
	v_fma_mix_f32 v103, v6, v22, v180 op_sel_hi:[0,1,0]
	v_fma_mix_f32 v103, v7, v22, v103 op_sel:[0,1,0] op_sel_hi:[0,1,0]
	v_add_f32_dpp v12, v12, v12 row_ror:1 row_mask:0xf bank_mask:0xf bound_ctrl:1
	v_fma_mix_f32 v103, v8, v23, v103 op_sel_hi:[0,1,0]
	v_fma_mix_f32 v103, v9, v23, v103 op_sel:[0,1,0] op_sel_hi:[0,1,0]
	v_add_f32_dpp v12, v12, v12 row_ror:2 row_mask:0xf bank_mask:0xf bound_ctrl:1
	v_pk_fma_f32 v[48:49], v[44:45], v[70:71], v[6:7] op_sel:[0,1,0]
	v_pk_fma_f32 v[50:51], v[46:47], v[70:71], v[8:9] op_sel:[0,1,0]
	v_add_f32_dpp v12, v12, v12 row_ror:4 row_mask:0xf bank_mask:0xf bound_ctrl:1
	v_add_f32_dpp v62, v62, v65 quad_perm:[1,0,3,2] row_mask:0xf bank_mask:0xf bound_ctrl:1
	v_cvt_pk_bf16_f32 v62, v62, v62
	v_add_f32_dpp v12, v12, v12 row_ror:8 row_mask:0xf bank_mask:0xf bound_ctrl:1
	v_pk_fma_f32 v[6:7], v[40:41], v[12:13], v[48:49] op_sel_hi:[1,0,1] neg_lo:[1,0,0] neg_hi:[1,0,0]
	v_pk_fma_f32 v[8:9], v[42:43], v[12:13], v[50:51] op_sel_hi:[1,0,1] neg_lo:[1,0,0] neg_hi:[1,0,0]
	s_waitcnt lgkmcnt(1)
	s_nop 0
	ds_read_b128 v[20:23], v10 offset:16640
	ds_read_b128 v[28:31], v10 offset:17152
	ds_read_b128 v[24:27], v10 offset:16896
	v_fma_mix_f32 v12, v6, v88, v180 op_sel_hi:[0,1,0]
	v_fma_mix_f32 v12, v7, v88, v12 op_sel:[0,1,0] op_sel_hi:[0,1,0]
	v_fma_mix_f32 v12, v8, v89, v12 op_sel_hi:[0,1,0]
	v_fma_mix_f32 v12, v9, v89, v12 op_sel:[0,1,0] op_sel_hi:[0,1,0]
	v_fma_mix_f32 v104, v6, v38, v180 op_sel_hi:[0,1,0]
	v_fma_mix_f32 v104, v7, v38, v104 op_sel:[0,1,0] op_sel_hi:[0,1,0]
	v_add_f32_dpp v12, v12, v12 row_ror:1 row_mask:0xf bank_mask:0xf bound_ctrl:1
	v_fma_mix_f32 v104, v8, v39, v104 op_sel_hi:[0,1,0]
	v_fma_mix_f32 v104, v9, v39, v104 op_sel:[0,1,0] op_sel_hi:[0,1,0]
	v_add_f32_dpp v12, v12, v12 row_ror:2 row_mask:0xf bank_mask:0xf bound_ctrl:1
	v_pk_fma_f32 v[48:49], v[96:97], v[72:73], v[6:7] op_sel_hi:[1,0,1]
	v_pk_fma_f32 v[50:51], v[98:99], v[72:73], v[8:9] op_sel_hi:[1,0,1]
	v_add_f32_dpp v12, v12, v12 row_ror:4 row_mask:0xf bank_mask:0xf bound_ctrl:1
	s_mov_b64 exec, s[100:101]
	s_nop 0
	global_store_short v[170:171], v62, off
	s_mov_b64 exec, -1
	s_nop 0
	v_add_f32_dpp v12, v12, v12 row_ror:8 row_mask:0xf bank_mask:0xf bound_ctrl:1
	v_pk_fma_f32 v[6:7], v[92:93], v[12:13], v[48:49] op_sel_hi:[1,0,1] neg_lo:[1,0,0] neg_hi:[1,0,0]
	v_pk_fma_f32 v[8:9], v[94:95], v[12:13], v[50:51] op_sel_hi:[1,0,1] neg_lo:[1,0,0] neg_hi:[1,0,0]
	ds_read_b128 v[36:39], v10 offset:17664
	ds_read_b128 v[44:47], v10 offset:18176
	ds_read_b128 v[40:43], v10 offset:17920
	v_fma_mix_f32 v12, v6, v110, v180 op_sel_hi:[0,1,0]
	v_fma_mix_f32 v12, v7, v110, v12 op_sel:[0,1,0] op_sel_hi:[0,1,0]
	v_fma_mix_f32 v12, v8, v111, v12 op_sel_hi:[0,1,0]
	v_fma_mix_f32 v12, v9, v111, v12 op_sel:[0,1,0] op_sel_hi:[0,1,0]
	v_fma_mix_f32 v105, v6, v90, v180 op_sel_hi:[0,1,0]
	v_fma_mix_f32 v105, v7, v90, v105 op_sel:[0,1,0] op_sel_hi:[0,1,0]
	v_add_f32_dpp v12, v12, v12 row_ror:1 row_mask:0xf bank_mask:0xf bound_ctrl:1
	v_fma_mix_f32 v105, v8, v91, v105 op_sel_hi:[0,1,0]
	v_fma_mix_f32 v105, v9, v91, v105 op_sel:[0,1,0] op_sel_hi:[0,1,0]
	v_add_f32_dpp v12, v12, v12 row_ror:2 row_mask:0xf bank_mask:0xf bound_ctrl:1
	v_pk_fma_f32 v[48:49], v[118:119], v[72:73], v[6:7] op_sel:[0,1,0]
	v_pk_fma_f32 v[50:51], v[120:121], v[72:73], v[8:9] op_sel:[0,1,0]
	v_add_f32_dpp v12, v12, v12 row_ror:4 row_mask:0xf bank_mask:0xf bound_ctrl:1
	s_nop 1
	s_nop 0
	v_add_f32_dpp v12, v12, v12 row_ror:8 row_mask:0xf bank_mask:0xf bound_ctrl:1
	v_pk_fma_f32 v[6:7], v[114:115], v[12:13], v[48:49] op_sel_hi:[1,0,1] neg_lo:[1,0,0] neg_hi:[1,0,0]
	v_pk_fma_f32 v[8:9], v[116:117], v[12:13], v[50:51] op_sel_hi:[1,0,1] neg_lo:[1,0,0] neg_hi:[1,0,0]
	v_pk_mul_f32 v[6:7], v[6:7], v[106:107]
	v_pk_mul_f32 v[8:9], v[8:9], v[108:109]
	s_waitcnt lgkmcnt(0)
	s_nop 0
	ds_read_b128 v[88:91], v10 offset:18688
	ds_read_b128 v[96:99], v10 offset:19200
	ds_read_b128 v[92:95], v10 offset:18944
	v_fma_mix_f32 v12, v6, v20, v180 op_sel_hi:[0,1,0]
	v_fma_mix_f32 v12, v7, v20, v12 op_sel:[0,1,0] op_sel_hi:[0,1,0]
	v_fma_mix_f32 v12, v8, v21, v12 op_sel_hi:[0,1,0]
	v_fma_mix_f32 v12, v9, v21, v12 op_sel:[0,1,0] op_sel_hi:[0,1,0]
	v_fma_mix_f32 v61, v6, v112, v180 op_sel_hi:[0,1,0]
	v_fma_mix_f32 v61, v7, v112, v61 op_sel:[0,1,0] op_sel_hi:[0,1,0]
	v_add_f32_dpp v12, v12, v12 row_ror:1 row_mask:0xf bank_mask:0xf bound_ctrl:1
	v_fma_mix_f32 v61, v8, v113, v61 op_sel_hi:[0,1,0]
	v_fma_mix_f32 v61, v9, v113, v61 op_sel:[0,1,0] op_sel_hi:[0,1,0]
	v_add_f32_dpp v12, v12, v12 row_ror:2 row_mask:0xf bank_mask:0xf bound_ctrl:1
	v_pk_fma_f32 v[48:49], v[28:29], v[66:67], v[6:7] op_sel_hi:[1,0,1]
	v_pk_fma_f32 v[50:51], v[30:31], v[66:67], v[8:9] op_sel_hi:[1,0,1]
	v_add_f32_dpp v12, v12, v12 row_ror:4 row_mask:0xf bank_mask:0xf bound_ctrl:1
	s_nop 1
	s_nop 0
	v_add_f32_dpp v12, v12, v12 row_ror:8 row_mask:0xf bank_mask:0xf bound_ctrl:1
	v_pk_fma_f32 v[6:7], v[24:25], v[12:13], v[48:49] op_sel_hi:[1,0,1] neg_lo:[1,0,0] neg_hi:[1,0,0]
	v_pk_fma_f32 v[8:9], v[26:27], v[12:13], v[50:51] op_sel_hi:[1,0,1] neg_lo:[1,0,0] neg_hi:[1,0,0]
	ds_read_b128 v[110:113], v10 offset:19712
	ds_read_b128 v[106:109], v10 offset:19456
	ds_read_b128 v[118:121], v10 offset:20224
	ds_read_b128 v[114:117], v10 offset:19968
	ds_read_b128 v[70:73], v11 offset:1280
	v_fma_mix_f32 v12, v6, v36, v180 op_sel_hi:[0,1,0]
	v_fma_mix_f32 v12, v7, v36, v12 op_sel:[0,1,0] op_sel_hi:[0,1,0]
	v_fma_mix_f32 v12, v8, v37, v12 op_sel_hi:[0,1,0]
	v_fma_mix_f32 v12, v9, v37, v12 op_sel:[0,1,0] op_sel_hi:[0,1,0]
	v_fma_mix_f32 v122, v6, v22, v180 op_sel_hi:[0,1,0]
	v_fma_mix_f32 v122, v7, v22, v122 op_sel:[0,1,0] op_sel_hi:[0,1,0]
	v_add_f32_dpp v12, v12, v12 row_ror:1 row_mask:0xf bank_mask:0xf bound_ctrl:1
	v_fma_mix_f32 v122, v8, v23, v122 op_sel_hi:[0,1,0]
	v_fma_mix_f32 v122, v9, v23, v122 op_sel:[0,1,0] op_sel_hi:[0,1,0]
	v_add_f32_dpp v12, v12, v12 row_ror:2 row_mask:0xf bank_mask:0xf bound_ctrl:1
	v_pk_fma_f32 v[48:49], v[44:45], v[66:67], v[6:7] op_sel:[0,1,0]
	v_pk_fma_f32 v[50:51], v[46:47], v[66:67], v[8:9] op_sel:[0,1,0]
	v_add_f32_dpp v12, v12, v12 row_ror:4 row_mask:0xf bank_mask:0xf bound_ctrl:1
	v_add_f32_dpp v83, v83, v83 row_ror:8 row_mask:0xf bank_mask:0xc
	v_add_f32_dpp v83, v52, v52 row_ror:8 row_mask:0xf bank_mask:0x3
	v_add_f32_dpp v100, v100, v100 row_ror:8 row_mask:0xf bank_mask:0xc
	v_add_f32_dpp v12, v12, v12 row_ror:8 row_mask:0xf bank_mask:0xf bound_ctrl:1
	v_pk_fma_f32 v[6:7], v[40:41], v[12:13], v[48:49] op_sel_hi:[1,0,1] neg_lo:[1,0,0] neg_hi:[1,0,0]
	v_pk_fma_f32 v[8:9], v[42:43], v[12:13], v[50:51] op_sel_hi:[1,0,1] neg_lo:[1,0,0] neg_hi:[1,0,0]
	s_waitcnt lgkmcnt(1)
	s_nop 0
	ds_read_b128 v[20:23], v10 offset:20736
	ds_read_b128 v[28:31], v10 offset:21248
	ds_read_b128 v[24:27], v10 offset:20992
	v_fma_mix_f32 v12, v6, v88, v180 op_sel_hi:[0,1,0]
	v_fma_mix_f32 v12, v7, v88, v12 op_sel:[0,1,0] op_sel_hi:[0,1,0]
	v_fma_mix_f32 v12, v8, v89, v12 op_sel_hi:[0,1,0]
	v_fma_mix_f32 v12, v9, v89, v12 op_sel:[0,1,0] op_sel_hi:[0,1,0]
	v_fma_mix_f32 v123, v6, v38, v180 op_sel_hi:[0,1,0]
	v_fma_mix_f32 v123, v7, v38, v123 op_sel:[0,1,0] op_sel_hi:[0,1,0]
	v_add_f32_dpp v12, v12, v12 row_ror:1 row_mask:0xf bank_mask:0xf bound_ctrl:1
	v_fma_mix_f32 v123, v8, v39, v123 op_sel_hi:[0,1,0]
	v_fma_mix_f32 v123, v9, v39, v123 op_sel:[0,1,0] op_sel_hi:[0,1,0]
	v_add_f32_dpp v12, v12, v12 row_ror:2 row_mask:0xf bank_mask:0xf bound_ctrl:1
	v_pk_fma_f32 v[48:49], v[96:97], v[68:69], v[6:7] op_sel_hi:[1,0,1]
	v_pk_fma_f32 v[50:51], v[98:99], v[68:69], v[8:9] op_sel_hi:[1,0,1]
	v_add_f32_dpp v12, v12, v12 row_ror:4 row_mask:0xf bank_mask:0xf bound_ctrl:1
	v_add_f32_dpp v100, v53, v53 row_ror:8 row_mask:0xf bank_mask:0x3
	v_add_f32_dpp v101, v101, v101 row_ror:8 row_mask:0xf bank_mask:0xc
	v_add_f32_dpp v101, v54, v54 row_ror:8 row_mask:0xf bank_mask:0x3
	v_add_f32_dpp v12, v12, v12 row_ror:8 row_mask:0xf bank_mask:0xf bound_ctrl:1
	v_pk_fma_f32 v[6:7], v[92:93], v[12:13], v[48:49] op_sel_hi:[1,0,1] neg_lo:[1,0,0] neg_hi:[1,0,0]
	v_pk_fma_f32 v[8:9], v[94:95], v[12:13], v[50:51] op_sel_hi:[1,0,1] neg_lo:[1,0,0] neg_hi:[1,0,0]
	ds_read_b128 v[36:39], v10 offset:21760
	ds_read_b128 v[44:47], v10 offset:22272
	ds_read_b128 v[40:43], v10 offset:22016
	v_fma_mix_f32 v12, v6, v110, v180 op_sel_hi:[0,1,0]
	v_fma_mix_f32 v12, v7, v110, v12 op_sel:[0,1,0] op_sel_hi:[0,1,0]
	v_fma_mix_f32 v12, v8, v111, v12 op_sel_hi:[0,1,0]
	v_fma_mix_f32 v12, v9, v111, v12 op_sel:[0,1,0] op_sel_hi:[0,1,0]
	v_fma_mix_f32 v124, v6, v90, v180 op_sel_hi:[0,1,0]
	v_fma_mix_f32 v124, v7, v90, v124 op_sel:[0,1,0] op_sel_hi:[0,1,0]
	v_add_f32_dpp v12, v12, v12 row_ror:1 row_mask:0xf bank_mask:0xf bound_ctrl:1
	v_fma_mix_f32 v124, v8, v91, v124 op_sel_hi:[0,1,0]
	v_fma_mix_f32 v124, v9, v91, v124 op_sel:[0,1,0] op_sel_hi:[0,1,0]
	v_add_f32_dpp v12, v12, v12 row_ror:2 row_mask:0xf bank_mask:0xf bound_ctrl:1
	v_pk_fma_f32 v[48:49], v[118:119], v[68:69], v[6:7] op_sel:[0,1,0]
	v_pk_fma_f32 v[50:51], v[120:121], v[68:69], v[8:9] op_sel:[0,1,0]
	v_add_f32_dpp v12, v12, v12 row_ror:4 row_mask:0xf bank_mask:0xf bound_ctrl:1
	v_add_f32_dpp v102, v102, v102 row_ror:8 row_mask:0xf bank_mask:0xc
	v_add_f32_dpp v102, v55, v55 row_ror:8 row_mask:0xf bank_mask:0x3
	v_add_f32_dpp v103, v103, v103 row_ror:8 row_mask:0xf bank_mask:0xc
	v_add_f32_dpp v12, v12, v12 row_ror:8 row_mask:0xf bank_mask:0xf bound_ctrl:1
	v_pk_fma_f32 v[6:7], v[114:115], v[12:13], v[48:49] op_sel_hi:[1,0,1] neg_lo:[1,0,0] neg_hi:[1,0,0]
	v_pk_fma_f32 v[8:9], v[116:117], v[12:13], v[50:51] op_sel_hi:[1,0,1] neg_lo:[1,0,0] neg_hi:[1,0,0]
	v_pk_mul_f32 v[6:7], v[6:7], v[106:107]
	v_pk_mul_f32 v[8:9], v[8:9], v[108:109]
	s_waitcnt lgkmcnt(0)
	s_nop 0
	ds_read_b128 v[88:91], v10 offset:22784
	ds_read_b128 v[96:99], v10 offset:23296
	ds_read_b128 v[92:95], v10 offset:23040
	v_fma_mix_f32 v12, v6, v20, v180 op_sel_hi:[0,1,0]
	v_fma_mix_f32 v12, v7, v20, v12 op_sel:[0,1,0] op_sel_hi:[0,1,0]
	v_fma_mix_f32 v12, v8, v21, v12 op_sel_hi:[0,1,0]
	v_fma_mix_f32 v12, v9, v21, v12 op_sel:[0,1,0] op_sel_hi:[0,1,0]
	v_fma_mix_f32 v125, v6, v112, v180 op_sel_hi:[0,1,0]
	v_fma_mix_f32 v125, v7, v112, v125 op_sel:[0,1,0] op_sel_hi:[0,1,0]
	v_add_f32_dpp v12, v12, v12 row_ror:1 row_mask:0xf bank_mask:0xf bound_ctrl:1
	v_fma_mix_f32 v125, v8, v113, v125 op_sel_hi:[0,1,0]
	v_fma_mix_f32 v125, v9, v113, v125 op_sel:[0,1,0] op_sel_hi:[0,1,0]
	v_add_f32_dpp v12, v12, v12 row_ror:2 row_mask:0xf bank_mask:0xf bound_ctrl:1
	v_pk_fma_f32 v[48:49], v[28:29], v[70:71], v[6:7] op_sel_hi:[1,0,1]
	v_pk_fma_f32 v[50:51], v[30:31], v[70:71], v[8:9] op_sel_hi:[1,0,1]
	v_add_f32_dpp v12, v12, v12 row_ror:4 row_mask:0xf bank_mask:0xf bound_ctrl:1
	v_add_f32_dpp v103, v56, v56 row_ror:8 row_mask:0xf bank_mask:0x3
	v_add_f32_dpp v104, v104, v104 row_ror:8 row_mask:0xf bank_mask:0xc
	v_add_f32_dpp v104, v57, v57 row_ror:8 row_mask:0xf bank_mask:0x3
	v_add_f32_dpp v12, v12, v12 row_ror:8 row_mask:0xf bank_mask:0xf bound_ctrl:1
	v_pk_fma_f32 v[6:7], v[24:25], v[12:13], v[48:49] op_sel_hi:[1,0,1] neg_lo:[1,0,0] neg_hi:[1,0,0]
	v_pk_fma_f32 v[8:9], v[26:27], v[12:13], v[50:51] op_sel_hi:[1,0,1] neg_lo:[1,0,0] neg_hi:[1,0,0]
	ds_read_b128 v[110:113], v10 offset:23808
	ds_read_b128 v[106:109], v10 offset:23552
	ds_read_b128 v[118:121], v10 offset:24320
	ds_read_b128 v[114:117], v10 offset:24064
	ds_read_b128 v[66:69], v11 offset:1536
	v_fma_mix_f32 v12, v6, v36, v180 op_sel_hi:[0,1,0]
	v_fma_mix_f32 v12, v7, v36, v12 op_sel:[0,1,0] op_sel_hi:[0,1,0]
	v_fma_mix_f32 v12, v8, v37, v12 op_sel_hi:[0,1,0]
	v_fma_mix_f32 v12, v9, v37, v12 op_sel:[0,1,0] op_sel_hi:[0,1,0]
	v_fma_mix_f32 v126, v6, v22, v180 op_sel_hi:[0,1,0]
	v_fma_mix_f32 v126, v7, v22, v126 op_sel:[0,1,0] op_sel_hi:[0,1,0]
	v_add_f32_dpp v12, v12, v12 row_ror:1 row_mask:0xf bank_mask:0xf bound_ctrl:1
	v_fma_mix_f32 v126, v8, v23, v126 op_sel_hi:[0,1,0]
	v_fma_mix_f32 v126, v9, v23, v126 op_sel:[0,1,0] op_sel_hi:[0,1,0]
	v_add_f32_dpp v12, v12, v12 row_ror:2 row_mask:0xf bank_mask:0xf bound_ctrl:1
	v_pk_fma_f32 v[48:49], v[44:45], v[70:71], v[6:7] op_sel:[0,1,0]
	v_pk_fma_f32 v[50:51], v[46:47], v[70:71], v[8:9] op_sel:[0,1,0]
	v_add_f32_dpp v12, v12, v12 row_ror:4 row_mask:0xf bank_mask:0xf bound_ctrl:1
	v_add_f32_dpp v105, v105, v105 row_ror:8 row_mask:0xf bank_mask:0xc
	v_add_f32_dpp v105, v81, v81 row_ror:8 row_mask:0xf bank_mask:0x3
	v_add_f32_dpp v12, v12, v12 row_ror:8 row_mask:0xf bank_mask:0xf bound_ctrl:1
	v_pk_fma_f32 v[6:7], v[40:41], v[12:13], v[48:49] op_sel_hi:[1,0,1] neg_lo:[1,0,0] neg_hi:[1,0,0]
	v_pk_fma_f32 v[8:9], v[42:43], v[12:13], v[50:51] op_sel_hi:[1,0,1] neg_lo:[1,0,0] neg_hi:[1,0,0]
	s_waitcnt lgkmcnt(1)
	s_nop 0
	ds_read_b128 v[20:23], v10 offset:24832
	ds_read_b128 v[28:31], v10 offset:25344
	ds_read_b128 v[24:27], v10 offset:25088
	v_fma_mix_f32 v12, v6, v88, v180 op_sel_hi:[0,1,0]
	v_fma_mix_f32 v12, v7, v88, v12 op_sel:[0,1,0] op_sel_hi:[0,1,0]
	v_fma_mix_f32 v12, v8, v89, v12 op_sel_hi:[0,1,0]
	v_fma_mix_f32 v12, v9, v89, v12 op_sel:[0,1,0] op_sel_hi:[0,1,0]
	v_fma_mix_f32 v127, v6, v38, v180 op_sel_hi:[0,1,0]
	v_fma_mix_f32 v127, v7, v38, v127 op_sel:[0,1,0] op_sel_hi:[0,1,0]
	v_add_f32_dpp v12, v12, v12 row_ror:1 row_mask:0xf bank_mask:0xf bound_ctrl:1
	v_fma_mix_f32 v127, v8, v39, v127 op_sel_hi:[0,1,0]
	v_fma_mix_f32 v127, v9, v39, v127 op_sel:[0,1,0] op_sel_hi:[0,1,0]
	v_add_f32_dpp v12, v12, v12 row_ror:2 row_mask:0xf bank_mask:0xf bound_ctrl:1
	v_pk_fma_f32 v[48:49], v[96:97], v[72:73], v[6:7] op_sel_hi:[1,0,1]
	v_pk_fma_f32 v[50:51], v[98:99], v[72:73], v[8:9] op_sel_hi:[1,0,1]
	v_add_f32_dpp v12, v12, v12 row_ror:4 row_mask:0xf bank_mask:0xf bound_ctrl:1
	v_add_f32_dpp v61, v61, v61 row_ror:8 row_mask:0xf bank_mask:0xc
	v_add_f32_dpp v61, v82, v82 row_ror:8 row_mask:0xf bank_mask:0x3
	v_add_f32_dpp v12, v12, v12 row_ror:8 row_mask:0xf bank_mask:0xf bound_ctrl:1
	v_pk_fma_f32 v[6:7], v[92:93], v[12:13], v[48:49] op_sel_hi:[1,0,1] neg_lo:[1,0,0] neg_hi:[1,0,0]
	v_pk_fma_f32 v[8:9], v[94:95], v[12:13], v[50:51] op_sel_hi:[1,0,1] neg_lo:[1,0,0] neg_hi:[1,0,0]
	ds_read_b128 v[36:39], v10 offset:25856
	ds_read_b128 v[44:47], v10 offset:26368
	ds_read_b128 v[40:43], v10 offset:26112
	v_fma_mix_f32 v12, v6, v110, v180 op_sel_hi:[0,1,0]
	v_fma_mix_f32 v12, v7, v110, v12 op_sel:[0,1,0] op_sel_hi:[0,1,0]
	v_fma_mix_f32 v12, v8, v111, v12 op_sel_hi:[0,1,0]
	v_fma_mix_f32 v12, v9, v111, v12 op_sel:[0,1,0] op_sel_hi:[0,1,0]
	v_fma_mix_f32 v128, v6, v90, v180 op_sel_hi:[0,1,0]
	v_fma_mix_f32 v128, v7, v90, v128 op_sel:[0,1,0] op_sel_hi:[0,1,0]
	v_add_f32_dpp v12, v12, v12 row_ror:1 row_mask:0xf bank_mask:0xf bound_ctrl:1
	v_fma_mix_f32 v128, v8, v91, v128 op_sel_hi:[0,1,0]
	v_fma_mix_f32 v128, v9, v91, v128 op_sel:[0,1,0] op_sel_hi:[0,1,0]
	v_add_f32_dpp v12, v12, v12 row_ror:2 row_mask:0xf bank_mask:0xf bound_ctrl:1
	v_pk_fma_f32 v[48:49], v[118:119], v[72:73], v[6:7] op_sel:[0,1,0]
	v_pk_fma_f32 v[50:51], v[120:121], v[72:73], v[8:9] op_sel:[0,1,0]
	v_add_f32_dpp v12, v12, v12 row_ror:4 row_mask:0xf bank_mask:0xf bound_ctrl:1
	v_add_f32_dpp v103, v103, v103 row_ror:4 row_mask:0xf bank_mask:0xa
	v_add_f32_dpp v103, v83, v83 row_ror:12 row_mask:0xf bank_mask:0x5
	v_add_f32_dpp v104, v104, v104 row_ror:4 row_mask:0xf bank_mask:0xa
	v_add_f32_dpp v12, v12, v12 row_ror:8 row_mask:0xf bank_mask:0xf bound_ctrl:1
	v_pk_fma_f32 v[6:7], v[114:115], v[12:13], v[48:49] op_sel_hi:[1,0,1] neg_lo:[1,0,0] neg_hi:[1,0,0]
	v_pk_fma_f32 v[8:9], v[116:117], v[12:13], v[50:51] op_sel_hi:[1,0,1] neg_lo:[1,0,0] neg_hi:[1,0,0]
	v_pk_mul_f32 v[6:7], v[6:7], v[106:107]
	v_pk_mul_f32 v[8:9], v[8:9], v[108:109]
	s_waitcnt lgkmcnt(0)
	s_nop 0
	ds_read_b128 v[88:91], v10 offset:26880
	ds_read_b128 v[96:99], v10 offset:27392
	ds_read_b128 v[92:95], v10 offset:27136
	v_fma_mix_f32 v12, v6, v20, v180 op_sel_hi:[0,1,0]
	v_fma_mix_f32 v12, v7, v20, v12 op_sel:[0,1,0] op_sel_hi:[0,1,0]
	v_fma_mix_f32 v12, v8, v21, v12 op_sel_hi:[0,1,0]
	v_fma_mix_f32 v12, v9, v21, v12 op_sel:[0,1,0] op_sel_hi:[0,1,0]
	v_fma_mix_f32 v129, v6, v112, v180 op_sel_hi:[0,1,0]
	v_fma_mix_f32 v129, v7, v112, v129 op_sel:[0,1,0] op_sel_hi:[0,1,0]
	v_add_f32_dpp v12, v12, v12 row_ror:1 row_mask:0xf bank_mask:0xf bound_ctrl:1
	v_fma_mix_f32 v129, v8, v113, v129 op_sel_hi:[0,1,0]
	v_fma_mix_f32 v129, v9, v113, v129 op_sel:[0,1,0] op_sel_hi:[0,1,0]
	v_add_f32_dpp v12, v12, v12 row_ror:2 row_mask:0xf bank_mask:0xf bound_ctrl:1
	v_pk_fma_f32 v[48:49], v[28:29], v[66:67], v[6:7] op_sel_hi:[1,0,1]
	v_pk_fma_f32 v[50:51], v[30:31], v[66:67], v[8:9] op_sel_hi:[1,0,1]
	v_add_f32_dpp v12, v12, v12 row_ror:4 row_mask:0xf bank_mask:0xf bound_ctrl:1
	v_add_f32_dpp v104, v100, v100 row_ror:12 row_mask:0xf bank_mask:0x5
	v_add_f32_dpp v105, v105, v105 row_ror:4 row_mask:0xf bank_mask:0xa
	v_add_f32_dpp v105, v101, v101 row_ror:12 row_mask:0xf bank_mask:0x5
	v_add_f32_dpp v12, v12, v12 row_ror:8 row_mask:0xf bank_mask:0xf bound_ctrl:1
	v_pk_fma_f32 v[6:7], v[24:25], v[12:13], v[48:49] op_sel_hi:[1,0,1] neg_lo:[1,0,0] neg_hi:[1,0,0]
	v_pk_fma_f32 v[8:9], v[26:27], v[12:13], v[50:51] op_sel_hi:[1,0,1] neg_lo:[1,0,0] neg_hi:[1,0,0]
	ds_read_b128 v[110:113], v10 offset:27904
	ds_read_b128 v[106:109], v10 offset:27648
	ds_read_b128 v[118:121], v10 offset:28416
	ds_read_b128 v[114:117], v10 offset:28160
	ds_read_b128 v[70:73], v11 offset:1792
	v_fma_mix_f32 v12, v6, v36, v180 op_sel_hi:[0,1,0]
	v_fma_mix_f32 v12, v7, v36, v12 op_sel:[0,1,0] op_sel_hi:[0,1,0]
	v_fma_mix_f32 v12, v8, v37, v12 op_sel_hi:[0,1,0]
	v_fma_mix_f32 v12, v9, v37, v12 op_sel:[0,1,0] op_sel_hi:[0,1,0]
	v_fma_mix_f32 v130, v6, v22, v180 op_sel_hi:[0,1,0]
	v_fma_mix_f32 v130, v7, v22, v130 op_sel:[0,1,0] op_sel_hi:[0,1,0]
	v_add_f32_dpp v12, v12, v12 row_ror:1 row_mask:0xf bank_mask:0xf bound_ctrl:1
	v_fma_mix_f32 v130, v8, v23, v130 op_sel_hi:[0,1,0]
	v_fma_mix_f32 v130, v9, v23, v130 op_sel:[0,1,0] op_sel_hi:[0,1,0]
	v_add_f32_dpp v12, v12, v12 row_ror:2 row_mask:0xf bank_mask:0xf bound_ctrl:1
	v_pk_fma_f32 v[48:49], v[44:45], v[66:67], v[6:7] op_sel:[0,1,0]
	v_pk_fma_f32 v[50:51], v[46:47], v[66:67], v[8:9] op_sel:[0,1,0]
	v_add_f32_dpp v12, v12, v12 row_ror:4 row_mask:0xf bank_mask:0xf bound_ctrl:1
	v_add_f32_dpp v61, v61, v61 row_ror:4 row_mask:0xf bank_mask:0xa
	v_add_f32_dpp v61, v102, v102 row_ror:12 row_mask:0xf bank_mask:0x5
	v_add_f32_dpp v12, v12, v12 row_ror:8 row_mask:0xf bank_mask:0xf bound_ctrl:1
	v_pk_fma_f32 v[6:7], v[40:41], v[12:13], v[48:49] op_sel_hi:[1,0,1] neg_lo:[1,0,0] neg_hi:[1,0,0]
	v_pk_fma_f32 v[8:9], v[42:43], v[12:13], v[50:51] op_sel_hi:[1,0,1] neg_lo:[1,0,0] neg_hi:[1,0,0]
	s_waitcnt lgkmcnt(1)
	s_nop 0
	ds_read_b128 v[20:23], v10 offset:28928
	ds_read_b128 v[28:31], v10 offset:29440
	ds_read_b128 v[24:27], v10 offset:29184
	v_fma_mix_f32 v12, v6, v88, v180 op_sel_hi:[0,1,0]
	v_fma_mix_f32 v12, v7, v88, v12 op_sel:[0,1,0] op_sel_hi:[0,1,0]
	v_fma_mix_f32 v12, v8, v89, v12 op_sel_hi:[0,1,0]
	v_fma_mix_f32 v12, v9, v89, v12 op_sel:[0,1,0] op_sel_hi:[0,1,0]
	v_fma_mix_f32 v131, v6, v38, v180 op_sel_hi:[0,1,0]
	v_fma_mix_f32 v131, v7, v38, v131 op_sel:[0,1,0] op_sel_hi:[0,1,0]
	v_add_f32_dpp v12, v12, v12 row_ror:1 row_mask:0xf bank_mask:0xf bound_ctrl:1
	v_fma_mix_f32 v131, v8, v39, v131 op_sel_hi:[0,1,0]
	v_fma_mix_f32 v131, v9, v39, v131 op_sel:[0,1,0] op_sel_hi:[0,1,0]
	v_add_f32_dpp v12, v12, v12 row_ror:2 row_mask:0xf bank_mask:0xf bound_ctrl:1
	v_pk_fma_f32 v[48:49], v[96:97], v[68:69], v[6:7] op_sel_hi:[1,0,1]
	v_pk_fma_f32 v[50:51], v[98:99], v[68:69], v[8:9] op_sel_hi:[1,0,1]
	v_add_f32_dpp v12, v12, v12 row_ror:4 row_mask:0xf bank_mask:0xf bound_ctrl:1
	v_cndmask_b32_e64 v62, v105, v103, s[38:39]
	v_cndmask_b32_e64 v63, v103, v105, s[38:39]
	v_add_f32_dpp v12, v12, v12 row_ror:8 row_mask:0xf bank_mask:0xf bound_ctrl:1
	v_pk_fma_f32 v[6:7], v[92:93], v[12:13], v[48:49] op_sel_hi:[1,0,1] neg_lo:[1,0,0] neg_hi:[1,0,0]
	v_pk_fma_f32 v[8:9], v[94:95], v[12:13], v[50:51] op_sel_hi:[1,0,1] neg_lo:[1,0,0] neg_hi:[1,0,0]
	ds_read_b128 v[36:39], v10 offset:29952
	ds_read_b128 v[44:47], v10 offset:30464
	ds_read_b128 v[40:43], v10 offset:30208
	v_fma_mix_f32 v12, v6, v110, v180 op_sel_hi:[0,1,0]
	v_fma_mix_f32 v12, v7, v110, v12 op_sel:[0,1,0] op_sel_hi:[0,1,0]
	v_fma_mix_f32 v12, v8, v111, v12 op_sel_hi:[0,1,0]
	v_fma_mix_f32 v12, v9, v111, v12 op_sel:[0,1,0] op_sel_hi:[0,1,0]
	v_fma_mix_f32 v132, v6, v90, v180 op_sel_hi:[0,1,0]
	v_fma_mix_f32 v132, v7, v90, v132 op_sel:[0,1,0] op_sel_hi:[0,1,0]
	v_add_f32_dpp v12, v12, v12 row_ror:1 row_mask:0xf bank_mask:0xf bound_ctrl:1
	v_fma_mix_f32 v132, v8, v91, v132 op_sel_hi:[0,1,0]
	v_fma_mix_f32 v132, v9, v91, v132 op_sel:[0,1,0] op_sel_hi:[0,1,0]
	v_add_f32_dpp v12, v12, v12 row_ror:2 row_mask:0xf bank_mask:0xf bound_ctrl:1
	v_pk_fma_f32 v[48:49], v[118:119], v[68:69], v[6:7] op_sel:[0,1,0]
	v_pk_fma_f32 v[50:51], v[120:121], v[68:69], v[8:9] op_sel:[0,1,0]
	v_add_f32_dpp v12, v12, v12 row_ror:4 row_mask:0xf bank_mask:0xf bound_ctrl:1
	v_cndmask_b32_e64 v64, v61, v104, s[38:39]
	v_cndmask_b32_e64 v65, v104, v61, s[38:39]
	v_add_f32_dpp v12, v12, v12 row_ror:8 row_mask:0xf bank_mask:0xf bound_ctrl:1
	v_pk_fma_f32 v[6:7], v[114:115], v[12:13], v[48:49] op_sel_hi:[1,0,1] neg_lo:[1,0,0] neg_hi:[1,0,0]
	v_pk_fma_f32 v[8:9], v[116:117], v[12:13], v[50:51] op_sel_hi:[1,0,1] neg_lo:[1,0,0] neg_hi:[1,0,0]
	v_pk_mul_f32 v[6:7], v[6:7], v[106:107]
	v_pk_mul_f32 v[8:9], v[8:9], v[108:109]
	s_waitcnt lgkmcnt(0)
	s_nop 0
	ds_read_b128 v[88:91], v10 offset:30976
	ds_read_b128 v[96:99], v10 offset:31488
	ds_read_b128 v[92:95], v10 offset:31232
	v_fma_mix_f32 v12, v6, v20, v180 op_sel_hi:[0,1,0]
	v_fma_mix_f32 v12, v7, v20, v12 op_sel:[0,1,0] op_sel_hi:[0,1,0]
	v_fma_mix_f32 v12, v8, v21, v12 op_sel_hi:[0,1,0]
	v_fma_mix_f32 v12, v9, v21, v12 op_sel:[0,1,0] op_sel_hi:[0,1,0]
	v_fma_mix_f32 v133, v6, v112, v180 op_sel_hi:[0,1,0]
	v_fma_mix_f32 v133, v7, v112, v133 op_sel:[0,1,0] op_sel_hi:[0,1,0]
	v_add_f32_dpp v12, v12, v12 row_ror:1 row_mask:0xf bank_mask:0xf bound_ctrl:1
	v_fma_mix_f32 v133, v8, v113, v133 op_sel_hi:[0,1,0]
	v_fma_mix_f32 v133, v9, v113, v133 op_sel:[0,1,0] op_sel_hi:[0,1,0]
	v_add_f32_dpp v12, v12, v12 row_ror:2 row_mask:0xf bank_mask:0xf bound_ctrl:1
	v_pk_fma_f32 v[48:49], v[28:29], v[70:71], v[6:7] op_sel_hi:[1,0,1]
	v_pk_fma_f32 v[50:51], v[30:31], v[70:71], v[8:9] op_sel_hi:[1,0,1]
	v_add_f32_dpp v12, v12, v12 row_ror:4 row_mask:0xf bank_mask:0xf bound_ctrl:1
	v_add_f32_dpp v62, v63, v62 quad_perm:[2,3,0,1] row_mask:0xf bank_mask:0xf bound_ctrl:1
	v_add_f32_dpp v63, v65, v64 quad_perm:[2,3,0,1] row_mask:0xf bank_mask:0xf bound_ctrl:1
	v_add_f32_dpp v12, v12, v12 row_ror:8 row_mask:0xf bank_mask:0xf bound_ctrl:1
	v_pk_fma_f32 v[6:7], v[24:25], v[12:13], v[48:49] op_sel_hi:[1,0,1] neg_lo:[1,0,0] neg_hi:[1,0,0]
	v_pk_fma_f32 v[8:9], v[26:27], v[12:13], v[50:51] op_sel_hi:[1,0,1] neg_lo:[1,0,0] neg_hi:[1,0,0]
	ds_read_b128 v[110:113], v10 offset:32000
	ds_read_b128 v[106:109], v10 offset:31744
	ds_read_b128 v[118:121], v10 offset:32512
	ds_read_b128 v[114:117], v10 offset:32256
	ds_read_b128 v[66:69], v11 offset:2048
	v_fma_mix_f32 v12, v6, v36, v180 op_sel_hi:[0,1,0]
	v_fma_mix_f32 v12, v7, v36, v12 op_sel:[0,1,0] op_sel_hi:[0,1,0]
	v_fma_mix_f32 v12, v8, v37, v12 op_sel_hi:[0,1,0]
	v_fma_mix_f32 v12, v9, v37, v12 op_sel:[0,1,0] op_sel_hi:[0,1,0]
	v_fma_mix_f32 v134, v6, v22, v180 op_sel_hi:[0,1,0]
	v_fma_mix_f32 v134, v7, v22, v134 op_sel:[0,1,0] op_sel_hi:[0,1,0]
	v_add_f32_dpp v12, v12, v12 row_ror:1 row_mask:0xf bank_mask:0xf bound_ctrl:1
	v_fma_mix_f32 v134, v8, v23, v134 op_sel_hi:[0,1,0]
	v_fma_mix_f32 v134, v9, v23, v134 op_sel:[0,1,0] op_sel_hi:[0,1,0]
	v_add_f32_dpp v12, v12, v12 row_ror:2 row_mask:0xf bank_mask:0xf bound_ctrl:1
	v_pk_fma_f32 v[48:49], v[44:45], v[70:71], v[6:7] op_sel:[0,1,0]
	v_pk_fma_f32 v[50:51], v[46:47], v[70:71], v[8:9] op_sel:[0,1,0]
	v_add_f32_dpp v12, v12, v12 row_ror:4 row_mask:0xf bank_mask:0xf bound_ctrl:1
	v_cndmask_b32_e64 v65, v63, v62, s[40:41]
	v_cndmask_b32_e64 v62, v62, v63, s[40:41]
	v_add_f32_dpp v12, v12, v12 row_ror:8 row_mask:0xf bank_mask:0xf bound_ctrl:1
	v_pk_fma_f32 v[6:7], v[40:41], v[12:13], v[48:49] op_sel_hi:[1,0,1] neg_lo:[1,0,0] neg_hi:[1,0,0]
	v_pk_fma_f32 v[8:9], v[42:43], v[12:13], v[50:51] op_sel_hi:[1,0,1] neg_lo:[1,0,0] neg_hi:[1,0,0]
	s_waitcnt lgkmcnt(1)
	s_nop 0
	ds_read_b128 v[20:23], v10 offset:33024
	ds_read_b128 v[28:31], v10 offset:33536
	ds_read_b128 v[24:27], v10 offset:33280
	v_fma_mix_f32 v12, v6, v88, v180 op_sel_hi:[0,1,0]
	v_fma_mix_f32 v12, v7, v88, v12 op_sel:[0,1,0] op_sel_hi:[0,1,0]
	v_fma_mix_f32 v12, v8, v89, v12 op_sel_hi:[0,1,0]
	v_fma_mix_f32 v12, v9, v89, v12 op_sel:[0,1,0] op_sel_hi:[0,1,0]
	v_fma_mix_f32 v135, v6, v38, v180 op_sel_hi:[0,1,0]
	v_fma_mix_f32 v135, v7, v38, v135 op_sel:[0,1,0] op_sel_hi:[0,1,0]
	v_add_f32_dpp v12, v12, v12 row_ror:1 row_mask:0xf bank_mask:0xf bound_ctrl:1
	v_fma_mix_f32 v135, v8, v39, v135 op_sel_hi:[0,1,0]
	v_fma_mix_f32 v135, v9, v39, v135 op_sel:[0,1,0] op_sel_hi:[0,1,0]
	v_add_f32_dpp v12, v12, v12 row_ror:2 row_mask:0xf bank_mask:0xf bound_ctrl:1
	v_pk_fma_f32 v[48:49], v[96:97], v[72:73], v[6:7] op_sel_hi:[1,0,1]
	v_pk_fma_f32 v[50:51], v[98:99], v[72:73], v[8:9] op_sel_hi:[1,0,1]
	v_add_f32_dpp v12, v12, v12 row_ror:4 row_mask:0xf bank_mask:0xf bound_ctrl:1
	v_add_f32_dpp v62, v62, v65 quad_perm:[1,0,3,2] row_mask:0xf bank_mask:0xf bound_ctrl:1
	v_cvt_pk_bf16_f32 v62, v62, v62
	v_add_f32_dpp v12, v12, v12 row_ror:8 row_mask:0xf bank_mask:0xf bound_ctrl:1
	v_pk_fma_f32 v[6:7], v[92:93], v[12:13], v[48:49] op_sel_hi:[1,0,1] neg_lo:[1,0,0] neg_hi:[1,0,0]
	v_pk_fma_f32 v[8:9], v[94:95], v[12:13], v[50:51] op_sel_hi:[1,0,1] neg_lo:[1,0,0] neg_hi:[1,0,0]
	ds_read_b128 v[36:39], v10 offset:34048
	ds_read_b128 v[44:47], v10 offset:34560
	ds_read_b128 v[40:43], v10 offset:34304
	v_fma_mix_f32 v12, v6, v110, v180 op_sel_hi:[0,1,0]
	v_fma_mix_f32 v12, v7, v110, v12 op_sel:[0,1,0] op_sel_hi:[0,1,0]
	v_fma_mix_f32 v12, v8, v111, v12 op_sel_hi:[0,1,0]
	v_fma_mix_f32 v12, v9, v111, v12 op_sel:[0,1,0] op_sel_hi:[0,1,0]
	v_fma_mix_f32 v136, v6, v90, v180 op_sel_hi:[0,1,0]
	v_fma_mix_f32 v136, v7, v90, v136 op_sel:[0,1,0] op_sel_hi:[0,1,0]
	v_add_f32_dpp v12, v12, v12 row_ror:1 row_mask:0xf bank_mask:0xf bound_ctrl:1
	v_fma_mix_f32 v136, v8, v91, v136 op_sel_hi:[0,1,0]
	v_fma_mix_f32 v136, v9, v91, v136 op_sel:[0,1,0] op_sel_hi:[0,1,0]
	v_add_f32_dpp v12, v12, v12 row_ror:2 row_mask:0xf bank_mask:0xf bound_ctrl:1
	v_pk_fma_f32 v[48:49], v[118:119], v[72:73], v[6:7] op_sel:[0,1,0]
	v_pk_fma_f32 v[50:51], v[120:121], v[72:73], v[8:9] op_sel:[0,1,0]
	v_add_f32_dpp v12, v12, v12 row_ror:4 row_mask:0xf bank_mask:0xf bound_ctrl:1
	global_store_short v[2:3], v62, off
	v_lshl_add_u64 v[2:3], v[2:3], 0, s[84:85]
	v_add_f32_dpp v12, v12, v12 row_ror:8 row_mask:0xf bank_mask:0xf bound_ctrl:1
	v_pk_fma_f32 v[6:7], v[114:115], v[12:13], v[48:49] op_sel_hi:[1,0,1] neg_lo:[1,0,0] neg_hi:[1,0,0]
	v_pk_fma_f32 v[8:9], v[116:117], v[12:13], v[50:51] op_sel_hi:[1,0,1] neg_lo:[1,0,0] neg_hi:[1,0,0]
	v_pk_mul_f32 v[6:7], v[6:7], v[106:107]
	v_pk_mul_f32 v[8:9], v[8:9], v[108:109]
	s_waitcnt lgkmcnt(0)
	s_nop 0
	ds_read_b128 v[88:91], v10 offset:35072
	ds_read_b128 v[96:99], v10 offset:35584
	ds_read_b128 v[92:95], v10 offset:35328
	v_fma_mix_f32 v12, v6, v20, v180 op_sel_hi:[0,1,0]
	v_fma_mix_f32 v12, v7, v20, v12 op_sel:[0,1,0] op_sel_hi:[0,1,0]
	v_fma_mix_f32 v12, v8, v21, v12 op_sel_hi:[0,1,0]
	v_fma_mix_f32 v12, v9, v21, v12 op_sel:[0,1,0] op_sel_hi:[0,1,0]
	v_fma_mix_f32 v137, v6, v112, v180 op_sel_hi:[0,1,0]
	v_fma_mix_f32 v137, v7, v112, v137 op_sel:[0,1,0] op_sel_hi:[0,1,0]
	v_add_f32_dpp v12, v12, v12 row_ror:1 row_mask:0xf bank_mask:0xf bound_ctrl:1
	v_fma_mix_f32 v137, v8, v113, v137 op_sel_hi:[0,1,0]
	v_fma_mix_f32 v137, v9, v113, v137 op_sel:[0,1,0] op_sel_hi:[0,1,0]
	v_add_f32_dpp v12, v12, v12 row_ror:2 row_mask:0xf bank_mask:0xf bound_ctrl:1
	v_pk_fma_f32 v[48:49], v[28:29], v[66:67], v[6:7] op_sel_hi:[1,0,1]
	v_pk_fma_f32 v[50:51], v[30:31], v[66:67], v[8:9] op_sel_hi:[1,0,1]
	v_add_f32_dpp v12, v12, v12 row_ror:4 row_mask:0xf bank_mask:0xf bound_ctrl:1
	s_nop 1
	s_nop 0
	v_add_f32_dpp v12, v12, v12 row_ror:8 row_mask:0xf bank_mask:0xf bound_ctrl:1
	v_pk_fma_f32 v[6:7], v[24:25], v[12:13], v[48:49] op_sel_hi:[1,0,1] neg_lo:[1,0,0] neg_hi:[1,0,0]
	v_pk_fma_f32 v[8:9], v[26:27], v[12:13], v[50:51] op_sel_hi:[1,0,1] neg_lo:[1,0,0] neg_hi:[1,0,0]
	ds_read_b128 v[110:113], v10 offset:36096
	ds_read_b128 v[106:109], v10 offset:35840
	ds_read_b128 v[118:121], v10 offset:36608
	ds_read_b128 v[114:117], v10 offset:36352
	ds_read_b128 v[70:73], v11 offset:2304
	v_fma_mix_f32 v12, v6, v36, v180 op_sel_hi:[0,1,0]
	v_fma_mix_f32 v12, v7, v36, v12 op_sel:[0,1,0] op_sel_hi:[0,1,0]
	v_fma_mix_f32 v12, v8, v37, v12 op_sel_hi:[0,1,0]
	v_fma_mix_f32 v12, v9, v37, v12 op_sel:[0,1,0] op_sel_hi:[0,1,0]
	v_fma_mix_f32 v52, v6, v22, v180 op_sel_hi:[0,1,0]
	v_fma_mix_f32 v52, v7, v22, v52 op_sel:[0,1,0] op_sel_hi:[0,1,0]
	v_add_f32_dpp v12, v12, v12 row_ror:1 row_mask:0xf bank_mask:0xf bound_ctrl:1
	v_fma_mix_f32 v52, v8, v23, v52 op_sel_hi:[0,1,0]
	v_fma_mix_f32 v52, v9, v23, v52 op_sel:[0,1,0] op_sel_hi:[0,1,0]
	v_add_f32_dpp v12, v12, v12 row_ror:2 row_mask:0xf bank_mask:0xf bound_ctrl:1
	v_pk_fma_f32 v[48:49], v[44:45], v[66:67], v[6:7] op_sel:[0,1,0]
	v_pk_fma_f32 v[50:51], v[46:47], v[66:67], v[8:9] op_sel:[0,1,0]
	v_add_f32_dpp v12, v12, v12 row_ror:4 row_mask:0xf bank_mask:0xf bound_ctrl:1
	v_add_f32_dpp v130, v130, v130 row_ror:8 row_mask:0xf bank_mask:0xc
	v_add_f32_dpp v130, v122, v122 row_ror:8 row_mask:0xf bank_mask:0x3
	v_add_f32_dpp v131, v131, v131 row_ror:8 row_mask:0xf bank_mask:0xc
	v_add_f32_dpp v12, v12, v12 row_ror:8 row_mask:0xf bank_mask:0xf bound_ctrl:1
	v_pk_fma_f32 v[6:7], v[40:41], v[12:13], v[48:49] op_sel_hi:[1,0,1] neg_lo:[1,0,0] neg_hi:[1,0,0]
	v_pk_fma_f32 v[8:9], v[42:43], v[12:13], v[50:51] op_sel_hi:[1,0,1] neg_lo:[1,0,0] neg_hi:[1,0,0]
	s_waitcnt lgkmcnt(1)
	s_nop 0
	ds_read_b128 v[20:23], v10 offset:37120
	ds_read_b128 v[28:31], v10 offset:37632
	ds_read_b128 v[24:27], v10 offset:37376
	v_fma_mix_f32 v12, v6, v88, v180 op_sel_hi:[0,1,0]
	v_fma_mix_f32 v12, v7, v88, v12 op_sel:[0,1,0] op_sel_hi:[0,1,0]
	v_fma_mix_f32 v12, v8, v89, v12 op_sel_hi:[0,1,0]
	v_fma_mix_f32 v12, v9, v89, v12 op_sel:[0,1,0] op_sel_hi:[0,1,0]
	v_fma_mix_f32 v53, v6, v38, v180 op_sel_hi:[0,1,0]
	v_fma_mix_f32 v53, v7, v38, v53 op_sel:[0,1,0] op_sel_hi:[0,1,0]
	v_add_f32_dpp v12, v12, v12 row_ror:1 row_mask:0xf bank_mask:0xf bound_ctrl:1
	v_fma_mix_f32 v53, v8, v39, v53 op_sel_hi:[0,1,0]
	v_fma_mix_f32 v53, v9, v39, v53 op_sel:[0,1,0] op_sel_hi:[0,1,0]
	v_add_f32_dpp v12, v12, v12 row_ror:2 row_mask:0xf bank_mask:0xf bound_ctrl:1
	v_pk_fma_f32 v[48:49], v[96:97], v[68:69], v[6:7] op_sel_hi:[1,0,1]
	v_pk_fma_f32 v[50:51], v[98:99], v[68:69], v[8:9] op_sel_hi:[1,0,1]
	v_add_f32_dpp v12, v12, v12 row_ror:4 row_mask:0xf bank_mask:0xf bound_ctrl:1
	v_add_f32_dpp v131, v123, v123 row_ror:8 row_mask:0xf bank_mask:0x3
	v_add_f32_dpp v132, v132, v132 row_ror:8 row_mask:0xf bank_mask:0xc
	v_add_f32_dpp v132, v124, v124 row_ror:8 row_mask:0xf bank_mask:0x3
	v_add_f32_dpp v12, v12, v12 row_ror:8 row_mask:0xf bank_mask:0xf bound_ctrl:1
	v_pk_fma_f32 v[6:7], v[92:93], v[12:13], v[48:49] op_sel_hi:[1,0,1] neg_lo:[1,0,0] neg_hi:[1,0,0]
	v_pk_fma_f32 v[8:9], v[94:95], v[12:13], v[50:51] op_sel_hi:[1,0,1] neg_lo:[1,0,0] neg_hi:[1,0,0]
	ds_read_b128 v[36:39], v10 offset:38144
	ds_read_b128 v[44:47], v10 offset:38656
	ds_read_b128 v[40:43], v10 offset:38400
	v_fma_mix_f32 v12, v6, v110, v180 op_sel_hi:[0,1,0]
	v_fma_mix_f32 v12, v7, v110, v12 op_sel:[0,1,0] op_sel_hi:[0,1,0]
	v_fma_mix_f32 v12, v8, v111, v12 op_sel_hi:[0,1,0]
	v_fma_mix_f32 v12, v9, v111, v12 op_sel:[0,1,0] op_sel_hi:[0,1,0]
	v_fma_mix_f32 v54, v6, v90, v180 op_sel_hi:[0,1,0]
	v_fma_mix_f32 v54, v7, v90, v54 op_sel:[0,1,0] op_sel_hi:[0,1,0]
	v_add_f32_dpp v12, v12, v12 row_ror:1 row_mask:0xf bank_mask:0xf bound_ctrl:1
	v_fma_mix_f32 v54, v8, v91, v54 op_sel_hi:[0,1,0]
	v_fma_mix_f32 v54, v9, v91, v54 op_sel:[0,1,0] op_sel_hi:[0,1,0]
	v_add_f32_dpp v12, v12, v12 row_ror:2 row_mask:0xf bank_mask:0xf bound_ctrl:1
	v_pk_fma_f32 v[48:49], v[118:119], v[68:69], v[6:7] op_sel:[0,1,0]
	v_pk_fma_f32 v[50:51], v[120:121], v[68:69], v[8:9] op_sel:[0,1,0]
	v_add_f32_dpp v12, v12, v12 row_ror:4 row_mask:0xf bank_mask:0xf bound_ctrl:1
	v_add_f32_dpp v133, v133, v133 row_ror:8 row_mask:0xf bank_mask:0xc
	v_add_f32_dpp v133, v125, v125 row_ror:8 row_mask:0xf bank_mask:0x3
	v_add_f32_dpp v134, v134, v134 row_ror:8 row_mask:0xf bank_mask:0xc
	v_add_f32_dpp v12, v12, v12 row_ror:8 row_mask:0xf bank_mask:0xf bound_ctrl:1
	v_pk_fma_f32 v[6:7], v[114:115], v[12:13], v[48:49] op_sel_hi:[1,0,1] neg_lo:[1,0,0] neg_hi:[1,0,0]
	v_pk_fma_f32 v[8:9], v[116:117], v[12:13], v[50:51] op_sel_hi:[1,0,1] neg_lo:[1,0,0] neg_hi:[1,0,0]
	v_pk_mul_f32 v[6:7], v[6:7], v[106:107]
	v_pk_mul_f32 v[8:9], v[8:9], v[108:109]
	s_waitcnt lgkmcnt(0)
	s_nop 0
	ds_read_b128 v[88:91], v10 offset:39168
	ds_read_b128 v[96:99], v10 offset:39680
	ds_read_b128 v[92:95], v10 offset:39424
	v_fma_mix_f32 v12, v6, v20, v180 op_sel_hi:[0,1,0]
	v_fma_mix_f32 v12, v7, v20, v12 op_sel:[0,1,0] op_sel_hi:[0,1,0]
	v_fma_mix_f32 v12, v8, v21, v12 op_sel_hi:[0,1,0]
	v_fma_mix_f32 v12, v9, v21, v12 op_sel:[0,1,0] op_sel_hi:[0,1,0]
	v_fma_mix_f32 v55, v6, v112, v180 op_sel_hi:[0,1,0]
	v_fma_mix_f32 v55, v7, v112, v55 op_sel:[0,1,0] op_sel_hi:[0,1,0]
	v_add_f32_dpp v12, v12, v12 row_ror:1 row_mask:0xf bank_mask:0xf bound_ctrl:1
	v_fma_mix_f32 v55, v8, v113, v55 op_sel_hi:[0,1,0]
	v_fma_mix_f32 v55, v9, v113, v55 op_sel:[0,1,0] op_sel_hi:[0,1,0]
	v_add_f32_dpp v12, v12, v12 row_ror:2 row_mask:0xf bank_mask:0xf bound_ctrl:1
	v_pk_fma_f32 v[48:49], v[28:29], v[70:71], v[6:7] op_sel_hi:[1,0,1]
	v_pk_fma_f32 v[50:51], v[30:31], v[70:71], v[8:9] op_sel_hi:[1,0,1]
	v_add_f32_dpp v12, v12, v12 row_ror:4 row_mask:0xf bank_mask:0xf bound_ctrl:1
	v_add_f32_dpp v134, v126, v126 row_ror:8 row_mask:0xf bank_mask:0x3
	v_add_f32_dpp v135, v135, v135 row_ror:8 row_mask:0xf bank_mask:0xc
	v_add_f32_dpp v135, v127, v127 row_ror:8 row_mask:0xf bank_mask:0x3
	v_add_f32_dpp v12, v12, v12 row_ror:8 row_mask:0xf bank_mask:0xf bound_ctrl:1
	v_pk_fma_f32 v[6:7], v[24:25], v[12:13], v[48:49] op_sel_hi:[1,0,1] neg_lo:[1,0,0] neg_hi:[1,0,0]
	v_pk_fma_f32 v[8:9], v[26:27], v[12:13], v[50:51] op_sel_hi:[1,0,1] neg_lo:[1,0,0] neg_hi:[1,0,0]
	ds_read_b128 v[110:113], v10 offset:40192
	ds_read_b128 v[106:109], v10 offset:39936
	ds_read_b128 v[118:121], v10 offset:40704
	ds_read_b128 v[114:117], v10 offset:40448
	ds_read_b128 v[66:69], v11 offset:2560
	v_fma_mix_f32 v12, v6, v36, v180 op_sel_hi:[0,1,0]
	v_fma_mix_f32 v12, v7, v36, v12 op_sel:[0,1,0] op_sel_hi:[0,1,0]
	v_fma_mix_f32 v12, v8, v37, v12 op_sel_hi:[0,1,0]
	v_fma_mix_f32 v12, v9, v37, v12 op_sel:[0,1,0] op_sel_hi:[0,1,0]
	v_fma_mix_f32 v56, v6, v22, v180 op_sel_hi:[0,1,0]
	v_fma_mix_f32 v56, v7, v22, v56 op_sel:[0,1,0] op_sel_hi:[0,1,0]
	v_add_f32_dpp v12, v12, v12 row_ror:1 row_mask:0xf bank_mask:0xf bound_ctrl:1
	v_fma_mix_f32 v56, v8, v23, v56 op_sel_hi:[0,1,0]
	v_fma_mix_f32 v56, v9, v23, v56 op_sel:[0,1,0] op_sel_hi:[0,1,0]
	v_add_f32_dpp v12, v12, v12 row_ror:2 row_mask:0xf bank_mask:0xf bound_ctrl:1
	v_pk_fma_f32 v[48:49], v[44:45], v[70:71], v[6:7] op_sel:[0,1,0]
	v_pk_fma_f32 v[50:51], v[46:47], v[70:71], v[8:9] op_sel:[0,1,0]
	v_add_f32_dpp v12, v12, v12 row_ror:4 row_mask:0xf bank_mask:0xf bound_ctrl:1
	v_add_f32_dpp v136, v136, v136 row_ror:8 row_mask:0xf bank_mask:0xc
	v_add_f32_dpp v136, v128, v128 row_ror:8 row_mask:0xf bank_mask:0x3
	v_add_f32_dpp v12, v12, v12 row_ror:8 row_mask:0xf bank_mask:0xf bound_ctrl:1
	v_pk_fma_f32 v[6:7], v[40:41], v[12:13], v[48:49] op_sel_hi:[1,0,1] neg_lo:[1,0,0] neg_hi:[1,0,0]
	v_pk_fma_f32 v[8:9], v[42:43], v[12:13], v[50:51] op_sel_hi:[1,0,1] neg_lo:[1,0,0] neg_hi:[1,0,0]
	s_waitcnt lgkmcnt(1)
	s_nop 0
	ds_read_b128 v[20:23], v10 offset:41216
	ds_read_b128 v[28:31], v10 offset:41728
	ds_read_b128 v[24:27], v10 offset:41472
	v_fma_mix_f32 v12, v6, v88, v180 op_sel_hi:[0,1,0]
	v_fma_mix_f32 v12, v7, v88, v12 op_sel:[0,1,0] op_sel_hi:[0,1,0]
	v_fma_mix_f32 v12, v8, v89, v12 op_sel_hi:[0,1,0]
	v_fma_mix_f32 v12, v9, v89, v12 op_sel:[0,1,0] op_sel_hi:[0,1,0]
	v_fma_mix_f32 v57, v6, v38, v180 op_sel_hi:[0,1,0]
	v_fma_mix_f32 v57, v7, v38, v57 op_sel:[0,1,0] op_sel_hi:[0,1,0]
	v_add_f32_dpp v12, v12, v12 row_ror:1 row_mask:0xf bank_mask:0xf bound_ctrl:1
	v_fma_mix_f32 v57, v8, v39, v57 op_sel_hi:[0,1,0]
	v_fma_mix_f32 v57, v9, v39, v57 op_sel:[0,1,0] op_sel_hi:[0,1,0]
	v_add_f32_dpp v12, v12, v12 row_ror:2 row_mask:0xf bank_mask:0xf bound_ctrl:1
	v_pk_fma_f32 v[48:49], v[96:97], v[72:73], v[6:7] op_sel_hi:[1,0,1]
	v_pk_fma_f32 v[50:51], v[98:99], v[72:73], v[8:9] op_sel_hi:[1,0,1]
	v_add_f32_dpp v12, v12, v12 row_ror:4 row_mask:0xf bank_mask:0xf bound_ctrl:1
	v_add_f32_dpp v137, v137, v137 row_ror:8 row_mask:0xf bank_mask:0xc
	v_add_f32_dpp v137, v129, v129 row_ror:8 row_mask:0xf bank_mask:0x3
	v_add_f32_dpp v12, v12, v12 row_ror:8 row_mask:0xf bank_mask:0xf bound_ctrl:1
	v_pk_fma_f32 v[6:7], v[92:93], v[12:13], v[48:49] op_sel_hi:[1,0,1] neg_lo:[1,0,0] neg_hi:[1,0,0]
	v_pk_fma_f32 v[8:9], v[94:95], v[12:13], v[50:51] op_sel_hi:[1,0,1] neg_lo:[1,0,0] neg_hi:[1,0,0]
	ds_read_b128 v[36:39], v10 offset:42240
	ds_read_b128 v[44:47], v10 offset:42752
	ds_read_b128 v[40:43], v10 offset:42496
	v_fma_mix_f32 v12, v6, v110, v180 op_sel_hi:[0,1,0]
	v_fma_mix_f32 v12, v7, v110, v12 op_sel:[0,1,0] op_sel_hi:[0,1,0]
	v_fma_mix_f32 v12, v8, v111, v12 op_sel_hi:[0,1,0]
	v_fma_mix_f32 v12, v9, v111, v12 op_sel:[0,1,0] op_sel_hi:[0,1,0]
	v_fma_mix_f32 v81, v6, v90, v180 op_sel_hi:[0,1,0]
	v_fma_mix_f32 v81, v7, v90, v81 op_sel:[0,1,0] op_sel_hi:[0,1,0]
	v_add_f32_dpp v12, v12, v12 row_ror:1 row_mask:0xf bank_mask:0xf bound_ctrl:1
	v_fma_mix_f32 v81, v8, v91, v81 op_sel_hi:[0,1,0]
	v_fma_mix_f32 v81, v9, v91, v81 op_sel:[0,1,0] op_sel_hi:[0,1,0]
	v_add_f32_dpp v12, v12, v12 row_ror:2 row_mask:0xf bank_mask:0xf bound_ctrl:1
	v_pk_fma_f32 v[48:49], v[118:119], v[72:73], v[6:7] op_sel:[0,1,0]
	v_pk_fma_f32 v[50:51], v[120:121], v[72:73], v[8:9] op_sel:[0,1,0]
	v_add_f32_dpp v12, v12, v12 row_ror:4 row_mask:0xf bank_mask:0xf bound_ctrl:1
	v_add_f32_dpp v134, v134, v134 row_ror:4 row_mask:0xf bank_mask:0xa
	v_add_f32_dpp v134, v130, v130 row_ror:12 row_mask:0xf bank_mask:0x5
	v_add_f32_dpp v135, v135, v135 row_ror:4 row_mask:0xf bank_mask:0xa
	v_add_f32_dpp v12, v12, v12 row_ror:8 row_mask:0xf bank_mask:0xf bound_ctrl:1
	v_pk_fma_f32 v[6:7], v[114:115], v[12:13], v[48:49] op_sel_hi:[1,0,1] neg_lo:[1,0,0] neg_hi:[1,0,0]
	v_pk_fma_f32 v[8:9], v[116:117], v[12:13], v[50:51] op_sel_hi:[1,0,1] neg_lo:[1,0,0] neg_hi:[1,0,0]
	v_pk_mul_f32 v[6:7], v[6:7], v[106:107]
	v_pk_mul_f32 v[8:9], v[8:9], v[108:109]
	s_waitcnt lgkmcnt(0)
	s_nop 0
	ds_read_b128 v[88:91], v10 offset:43264
	ds_read_b128 v[96:99], v10 offset:43776
	ds_read_b128 v[92:95], v10 offset:43520
	v_fma_mix_f32 v12, v6, v20, v180 op_sel_hi:[0,1,0]
	v_fma_mix_f32 v12, v7, v20, v12 op_sel:[0,1,0] op_sel_hi:[0,1,0]
	v_fma_mix_f32 v12, v8, v21, v12 op_sel_hi:[0,1,0]
	v_fma_mix_f32 v12, v9, v21, v12 op_sel:[0,1,0] op_sel_hi:[0,1,0]
	v_fma_mix_f32 v82, v6, v112, v180 op_sel_hi:[0,1,0]
	v_fma_mix_f32 v82, v7, v112, v82 op_sel:[0,1,0] op_sel_hi:[0,1,0]
	v_add_f32_dpp v12, v12, v12 row_ror:1 row_mask:0xf bank_mask:0xf bound_ctrl:1
	v_fma_mix_f32 v82, v8, v113, v82 op_sel_hi:[0,1,0]
	v_fma_mix_f32 v82, v9, v113, v82 op_sel:[0,1,0] op_sel_hi:[0,1,0]
	v_add_f32_dpp v12, v12, v12 row_ror:2 row_mask:0xf bank_mask:0xf bound_ctrl:1
	v_pk_fma_f32 v[48:49], v[28:29], v[66:67], v[6:7] op_sel_hi:[1,0,1]
	v_pk_fma_f32 v[50:51], v[30:31], v[66:67], v[8:9] op_sel_hi:[1,0,1]
	v_add_f32_dpp v12, v12, v12 row_ror:4 row_mask:0xf bank_mask:0xf bound_ctrl:1
	v_add_f32_dpp v135, v131, v131 row_ror:12 row_mask:0xf bank_mask:0x5
	v_add_f32_dpp v136, v136, v136 row_ror:4 row_mask:0xf bank_mask:0xa
	v_add_f32_dpp v136, v132, v132 row_ror:12 row_mask:0xf bank_mask:0x5
	v_add_f32_dpp v12, v12, v12 row_ror:8 row_mask:0xf bank_mask:0xf bound_ctrl:1
	v_pk_fma_f32 v[6:7], v[24:25], v[12:13], v[48:49] op_sel_hi:[1,0,1] neg_lo:[1,0,0] neg_hi:[1,0,0]
	v_pk_fma_f32 v[8:9], v[26:27], v[12:13], v[50:51] op_sel_hi:[1,0,1] neg_lo:[1,0,0] neg_hi:[1,0,0]
	ds_read_b128 v[110:113], v10 offset:44288
	ds_read_b128 v[106:109], v10 offset:44032
	ds_read_b128 v[118:121], v10 offset:44800
	ds_read_b128 v[114:117], v10 offset:44544
	ds_read_b128 v[70:73], v11 offset:2816
	v_fma_mix_f32 v12, v6, v36, v180 op_sel_hi:[0,1,0]
	v_fma_mix_f32 v12, v7, v36, v12 op_sel:[0,1,0] op_sel_hi:[0,1,0]
	v_fma_mix_f32 v12, v8, v37, v12 op_sel_hi:[0,1,0]
	v_fma_mix_f32 v12, v9, v37, v12 op_sel:[0,1,0] op_sel_hi:[0,1,0]
	v_fma_mix_f32 v83, v6, v22, v180 op_sel_hi:[0,1,0]
	v_fma_mix_f32 v83, v7, v22, v83 op_sel:[0,1,0] op_sel_hi:[0,1,0]
	v_add_f32_dpp v12, v12, v12 row_ror:1 row_mask:0xf bank_mask:0xf bound_ctrl:1
	v_fma_mix_f32 v83, v8, v23, v83 op_sel_hi:[0,1,0]
	v_fma_mix_f32 v83, v9, v23, v83 op_sel:[0,1,0] op_sel_hi:[0,1,0]
	v_add_f32_dpp v12, v12, v12 row_ror:2 row_mask:0xf bank_mask:0xf bound_ctrl:1
	v_pk_fma_f32 v[48:49], v[44:45], v[66:67], v[6:7] op_sel:[0,1,0]
	v_pk_fma_f32 v[50:51], v[46:47], v[66:67], v[8:9] op_sel:[0,1,0]
	v_add_f32_dpp v12, v12, v12 row_ror:4 row_mask:0xf bank_mask:0xf bound_ctrl:1
	v_add_f32_dpp v137, v137, v137 row_ror:4 row_mask:0xf bank_mask:0xa
	v_add_f32_dpp v137, v133, v133 row_ror:12 row_mask:0xf bank_mask:0x5
	v_add_f32_dpp v12, v12, v12 row_ror:8 row_mask:0xf bank_mask:0xf bound_ctrl:1
	v_pk_fma_f32 v[6:7], v[40:41], v[12:13], v[48:49] op_sel_hi:[1,0,1] neg_lo:[1,0,0] neg_hi:[1,0,0]
	v_pk_fma_f32 v[8:9], v[42:43], v[12:13], v[50:51] op_sel_hi:[1,0,1] neg_lo:[1,0,0] neg_hi:[1,0,0]
	s_waitcnt lgkmcnt(1)
	s_nop 0
	ds_read_b128 v[20:23], v10 offset:45312
	ds_read_b128 v[28:31], v10 offset:45824
	ds_read_b128 v[24:27], v10 offset:45568
	v_fma_mix_f32 v12, v6, v88, v180 op_sel_hi:[0,1,0]
	v_fma_mix_f32 v12, v7, v88, v12 op_sel:[0,1,0] op_sel_hi:[0,1,0]
	v_fma_mix_f32 v12, v8, v89, v12 op_sel_hi:[0,1,0]
	v_fma_mix_f32 v12, v9, v89, v12 op_sel:[0,1,0] op_sel_hi:[0,1,0]
	v_fma_mix_f32 v100, v6, v38, v180 op_sel_hi:[0,1,0]
	v_fma_mix_f32 v100, v7, v38, v100 op_sel:[0,1,0] op_sel_hi:[0,1,0]
	v_add_f32_dpp v12, v12, v12 row_ror:1 row_mask:0xf bank_mask:0xf bound_ctrl:1
	v_fma_mix_f32 v100, v8, v39, v100 op_sel_hi:[0,1,0]
	v_fma_mix_f32 v100, v9, v39, v100 op_sel:[0,1,0] op_sel_hi:[0,1,0]
	v_add_f32_dpp v12, v12, v12 row_ror:2 row_mask:0xf bank_mask:0xf bound_ctrl:1
	v_pk_fma_f32 v[48:49], v[96:97], v[68:69], v[6:7] op_sel_hi:[1,0,1]
	v_pk_fma_f32 v[50:51], v[98:99], v[68:69], v[8:9] op_sel_hi:[1,0,1]
	v_add_f32_dpp v12, v12, v12 row_ror:4 row_mask:0xf bank_mask:0xf bound_ctrl:1
	v_cndmask_b32_e64 v62, v136, v134, s[38:39]
	v_cndmask_b32_e64 v63, v134, v136, s[38:39]
	v_add_f32_dpp v12, v12, v12 row_ror:8 row_mask:0xf bank_mask:0xf bound_ctrl:1
	v_pk_fma_f32 v[6:7], v[92:93], v[12:13], v[48:49] op_sel_hi:[1,0,1] neg_lo:[1,0,0] neg_hi:[1,0,0]
	v_pk_fma_f32 v[8:9], v[94:95], v[12:13], v[50:51] op_sel_hi:[1,0,1] neg_lo:[1,0,0] neg_hi:[1,0,0]
	ds_read_b128 v[36:39], v10 offset:46336
	ds_read_b128 v[44:47], v10 offset:46848
	ds_read_b128 v[40:43], v10 offset:46592
	v_fma_mix_f32 v12, v6, v110, v180 op_sel_hi:[0,1,0]
	v_fma_mix_f32 v12, v7, v110, v12 op_sel:[0,1,0] op_sel_hi:[0,1,0]
	v_fma_mix_f32 v12, v8, v111, v12 op_sel_hi:[0,1,0]
	v_fma_mix_f32 v12, v9, v111, v12 op_sel:[0,1,0] op_sel_hi:[0,1,0]
	v_fma_mix_f32 v101, v6, v90, v180 op_sel_hi:[0,1,0]
	v_fma_mix_f32 v101, v7, v90, v101 op_sel:[0,1,0] op_sel_hi:[0,1,0]
	v_add_f32_dpp v12, v12, v12 row_ror:1 row_mask:0xf bank_mask:0xf bound_ctrl:1
	v_fma_mix_f32 v101, v8, v91, v101 op_sel_hi:[0,1,0]
	v_fma_mix_f32 v101, v9, v91, v101 op_sel:[0,1,0] op_sel_hi:[0,1,0]
	v_add_f32_dpp v12, v12, v12 row_ror:2 row_mask:0xf bank_mask:0xf bound_ctrl:1
	v_pk_fma_f32 v[48:49], v[118:119], v[68:69], v[6:7] op_sel:[0,1,0]
	v_pk_fma_f32 v[50:51], v[120:121], v[68:69], v[8:9] op_sel:[0,1,0]
	v_add_f32_dpp v12, v12, v12 row_ror:4 row_mask:0xf bank_mask:0xf bound_ctrl:1
	v_cndmask_b32_e64 v64, v137, v135, s[38:39]
	v_cndmask_b32_e64 v65, v135, v137, s[38:39]
	v_add_f32_dpp v12, v12, v12 row_ror:8 row_mask:0xf bank_mask:0xf bound_ctrl:1
	v_pk_fma_f32 v[6:7], v[114:115], v[12:13], v[48:49] op_sel_hi:[1,0,1] neg_lo:[1,0,0] neg_hi:[1,0,0]
	v_pk_fma_f32 v[8:9], v[116:117], v[12:13], v[50:51] op_sel_hi:[1,0,1] neg_lo:[1,0,0] neg_hi:[1,0,0]
	v_pk_mul_f32 v[6:7], v[6:7], v[106:107]
	v_pk_mul_f32 v[8:9], v[8:9], v[108:109]
	s_waitcnt lgkmcnt(0)
	s_nop 0
	ds_read_b128 v[88:91], v10 offset:47360
	ds_read_b128 v[96:99], v10 offset:47872
	ds_read_b128 v[92:95], v10 offset:47616
	v_fma_mix_f32 v12, v6, v20, v180 op_sel_hi:[0,1,0]
	v_fma_mix_f32 v12, v7, v20, v12 op_sel:[0,1,0] op_sel_hi:[0,1,0]
	v_fma_mix_f32 v12, v8, v21, v12 op_sel_hi:[0,1,0]
	v_fma_mix_f32 v12, v9, v21, v12 op_sel:[0,1,0] op_sel_hi:[0,1,0]
	v_fma_mix_f32 v102, v6, v112, v180 op_sel_hi:[0,1,0]
	v_fma_mix_f32 v102, v7, v112, v102 op_sel:[0,1,0] op_sel_hi:[0,1,0]
	v_add_f32_dpp v12, v12, v12 row_ror:1 row_mask:0xf bank_mask:0xf bound_ctrl:1
	v_fma_mix_f32 v102, v8, v113, v102 op_sel_hi:[0,1,0]
	v_fma_mix_f32 v102, v9, v113, v102 op_sel:[0,1,0] op_sel_hi:[0,1,0]
	v_add_f32_dpp v12, v12, v12 row_ror:2 row_mask:0xf bank_mask:0xf bound_ctrl:1
	v_pk_fma_f32 v[48:49], v[28:29], v[70:71], v[6:7] op_sel_hi:[1,0,1]
	v_pk_fma_f32 v[50:51], v[30:31], v[70:71], v[8:9] op_sel_hi:[1,0,1]
	v_add_f32_dpp v12, v12, v12 row_ror:4 row_mask:0xf bank_mask:0xf bound_ctrl:1
	v_add_f32_dpp v62, v63, v62 quad_perm:[2,3,0,1] row_mask:0xf bank_mask:0xf bound_ctrl:1
	v_add_f32_dpp v63, v65, v64 quad_perm:[2,3,0,1] row_mask:0xf bank_mask:0xf bound_ctrl:1
	v_add_f32_dpp v12, v12, v12 row_ror:8 row_mask:0xf bank_mask:0xf bound_ctrl:1
	v_pk_fma_f32 v[6:7], v[24:25], v[12:13], v[48:49] op_sel_hi:[1,0,1] neg_lo:[1,0,0] neg_hi:[1,0,0]
	v_pk_fma_f32 v[8:9], v[26:27], v[12:13], v[50:51] op_sel_hi:[1,0,1] neg_lo:[1,0,0] neg_hi:[1,0,0]
	ds_read_b128 v[110:113], v10 offset:48384
	ds_read_b128 v[106:109], v10 offset:48128
	ds_read_b128 v[118:121], v10 offset:48896
	ds_read_b128 v[114:117], v10 offset:48640
	ds_read_b128 v[66:69], v11 offset:3072
	v_fma_mix_f32 v12, v6, v36, v180 op_sel_hi:[0,1,0]
	v_fma_mix_f32 v12, v7, v36, v12 op_sel:[0,1,0] op_sel_hi:[0,1,0]
	v_fma_mix_f32 v12, v8, v37, v12 op_sel_hi:[0,1,0]
	v_fma_mix_f32 v12, v9, v37, v12 op_sel:[0,1,0] op_sel_hi:[0,1,0]
	v_fma_mix_f32 v103, v6, v22, v180 op_sel_hi:[0,1,0]
	v_fma_mix_f32 v103, v7, v22, v103 op_sel:[0,1,0] op_sel_hi:[0,1,0]
	v_add_f32_dpp v12, v12, v12 row_ror:1 row_mask:0xf bank_mask:0xf bound_ctrl:1
	v_fma_mix_f32 v103, v8, v23, v103 op_sel_hi:[0,1,0]
	v_fma_mix_f32 v103, v9, v23, v103 op_sel:[0,1,0] op_sel_hi:[0,1,0]
	v_add_f32_dpp v12, v12, v12 row_ror:2 row_mask:0xf bank_mask:0xf bound_ctrl:1
	v_pk_fma_f32 v[48:49], v[44:45], v[70:71], v[6:7] op_sel:[0,1,0]
	v_pk_fma_f32 v[50:51], v[46:47], v[70:71], v[8:9] op_sel:[0,1,0]
	v_add_f32_dpp v12, v12, v12 row_ror:4 row_mask:0xf bank_mask:0xf bound_ctrl:1
	v_cndmask_b32_e64 v65, v63, v62, s[40:41]
	v_cndmask_b32_e64 v62, v62, v63, s[40:41]
	v_add_f32_dpp v12, v12, v12 row_ror:8 row_mask:0xf bank_mask:0xf bound_ctrl:1
	v_pk_fma_f32 v[6:7], v[40:41], v[12:13], v[48:49] op_sel_hi:[1,0,1] neg_lo:[1,0,0] neg_hi:[1,0,0]
	v_pk_fma_f32 v[8:9], v[42:43], v[12:13], v[50:51] op_sel_hi:[1,0,1] neg_lo:[1,0,0] neg_hi:[1,0,0]
	s_waitcnt lgkmcnt(1)
	s_nop 0
	ds_read_b128 v[20:23], v10 offset:49408
	ds_read_b128 v[28:31], v10 offset:49920
	ds_read_b128 v[24:27], v10 offset:49664
	v_fma_mix_f32 v12, v6, v88, v180 op_sel_hi:[0,1,0]
	v_fma_mix_f32 v12, v7, v88, v12 op_sel:[0,1,0] op_sel_hi:[0,1,0]
	v_fma_mix_f32 v12, v8, v89, v12 op_sel_hi:[0,1,0]
	v_fma_mix_f32 v12, v9, v89, v12 op_sel:[0,1,0] op_sel_hi:[0,1,0]
	v_fma_mix_f32 v104, v6, v38, v180 op_sel_hi:[0,1,0]
	v_fma_mix_f32 v104, v7, v38, v104 op_sel:[0,1,0] op_sel_hi:[0,1,0]
	v_add_f32_dpp v12, v12, v12 row_ror:1 row_mask:0xf bank_mask:0xf bound_ctrl:1
	v_fma_mix_f32 v104, v8, v39, v104 op_sel_hi:[0,1,0]
	v_fma_mix_f32 v104, v9, v39, v104 op_sel:[0,1,0] op_sel_hi:[0,1,0]
	v_add_f32_dpp v12, v12, v12 row_ror:2 row_mask:0xf bank_mask:0xf bound_ctrl:1
	v_pk_fma_f32 v[48:49], v[96:97], v[72:73], v[6:7] op_sel_hi:[1,0,1]
	v_pk_fma_f32 v[50:51], v[98:99], v[72:73], v[8:9] op_sel_hi:[1,0,1]
	v_add_f32_dpp v12, v12, v12 row_ror:4 row_mask:0xf bank_mask:0xf bound_ctrl:1
	v_add_f32_dpp v62, v62, v65 quad_perm:[1,0,3,2] row_mask:0xf bank_mask:0xf bound_ctrl:1
	v_cvt_pk_bf16_f32 v62, v62, v62
	v_add_f32_dpp v12, v12, v12 row_ror:8 row_mask:0xf bank_mask:0xf bound_ctrl:1
	v_pk_fma_f32 v[6:7], v[92:93], v[12:13], v[48:49] op_sel_hi:[1,0,1] neg_lo:[1,0,0] neg_hi:[1,0,0]
	v_pk_fma_f32 v[8:9], v[94:95], v[12:13], v[50:51] op_sel_hi:[1,0,1] neg_lo:[1,0,0] neg_hi:[1,0,0]
	ds_read_b128 v[36:39], v10 offset:50432
	ds_read_b128 v[44:47], v10 offset:50944
	ds_read_b128 v[40:43], v10 offset:50688
	v_fma_mix_f32 v12, v6, v110, v180 op_sel_hi:[0,1,0]
	v_fma_mix_f32 v12, v7, v110, v12 op_sel:[0,1,0] op_sel_hi:[0,1,0]
	v_fma_mix_f32 v12, v8, v111, v12 op_sel_hi:[0,1,0]
	v_fma_mix_f32 v12, v9, v111, v12 op_sel:[0,1,0] op_sel_hi:[0,1,0]
	v_fma_mix_f32 v105, v6, v90, v180 op_sel_hi:[0,1,0]
	v_fma_mix_f32 v105, v7, v90, v105 op_sel:[0,1,0] op_sel_hi:[0,1,0]
	v_add_f32_dpp v12, v12, v12 row_ror:1 row_mask:0xf bank_mask:0xf bound_ctrl:1
	v_fma_mix_f32 v105, v8, v91, v105 op_sel_hi:[0,1,0]
	v_fma_mix_f32 v105, v9, v91, v105 op_sel:[0,1,0] op_sel_hi:[0,1,0]
	v_add_f32_dpp v12, v12, v12 row_ror:2 row_mask:0xf bank_mask:0xf bound_ctrl:1
	v_pk_fma_f32 v[48:49], v[118:119], v[72:73], v[6:7] op_sel:[0,1,0]
	v_pk_fma_f32 v[50:51], v[120:121], v[72:73], v[8:9] op_sel:[0,1,0]
	v_add_f32_dpp v12, v12, v12 row_ror:4 row_mask:0xf bank_mask:0xf bound_ctrl:1
	global_store_short v[2:3], v62, off
	v_lshl_add_u64 v[2:3], v[2:3], 0, s[84:85]
	v_add_f32_dpp v12, v12, v12 row_ror:8 row_mask:0xf bank_mask:0xf bound_ctrl:1
	v_pk_fma_f32 v[6:7], v[114:115], v[12:13], v[48:49] op_sel_hi:[1,0,1] neg_lo:[1,0,0] neg_hi:[1,0,0]
	v_pk_fma_f32 v[8:9], v[116:117], v[12:13], v[50:51] op_sel_hi:[1,0,1] neg_lo:[1,0,0] neg_hi:[1,0,0]
	v_pk_mul_f32 v[6:7], v[6:7], v[106:107]
	v_pk_mul_f32 v[8:9], v[8:9], v[108:109]
	s_waitcnt lgkmcnt(0)
	s_nop 0
	ds_read_b128 v[88:91], v10 offset:51456
	ds_read_b128 v[96:99], v10 offset:51968
	ds_read_b128 v[92:95], v10 offset:51712
	v_fma_mix_f32 v12, v6, v20, v180 op_sel_hi:[0,1,0]
	v_fma_mix_f32 v12, v7, v20, v12 op_sel:[0,1,0] op_sel_hi:[0,1,0]
	v_fma_mix_f32 v12, v8, v21, v12 op_sel_hi:[0,1,0]
	v_fma_mix_f32 v12, v9, v21, v12 op_sel:[0,1,0] op_sel_hi:[0,1,0]
	v_fma_mix_f32 v61, v6, v112, v180 op_sel_hi:[0,1,0]
	v_fma_mix_f32 v61, v7, v112, v61 op_sel:[0,1,0] op_sel_hi:[0,1,0]
	v_add_f32_dpp v12, v12, v12 row_ror:1 row_mask:0xf bank_mask:0xf bound_ctrl:1
	v_fma_mix_f32 v61, v8, v113, v61 op_sel_hi:[0,1,0]
	v_fma_mix_f32 v61, v9, v113, v61 op_sel:[0,1,0] op_sel_hi:[0,1,0]
	v_add_f32_dpp v12, v12, v12 row_ror:2 row_mask:0xf bank_mask:0xf bound_ctrl:1
	v_pk_fma_f32 v[48:49], v[28:29], v[66:67], v[6:7] op_sel_hi:[1,0,1]
	v_pk_fma_f32 v[50:51], v[30:31], v[66:67], v[8:9] op_sel_hi:[1,0,1]
	v_add_f32_dpp v12, v12, v12 row_ror:4 row_mask:0xf bank_mask:0xf bound_ctrl:1
	s_nop 1
	s_nop 0
	v_add_f32_dpp v12, v12, v12 row_ror:8 row_mask:0xf bank_mask:0xf bound_ctrl:1
	v_pk_fma_f32 v[6:7], v[24:25], v[12:13], v[48:49] op_sel_hi:[1,0,1] neg_lo:[1,0,0] neg_hi:[1,0,0]
	v_pk_fma_f32 v[8:9], v[26:27], v[12:13], v[50:51] op_sel_hi:[1,0,1] neg_lo:[1,0,0] neg_hi:[1,0,0]
	ds_read_b128 v[110:113], v10 offset:52480
	ds_read_b128 v[106:109], v10 offset:52224
	ds_read_b128 v[118:121], v10 offset:52992
	ds_read_b128 v[114:117], v10 offset:52736
	ds_read_b128 v[70:73], v11 offset:3328
	v_fma_mix_f32 v12, v6, v36, v180 op_sel_hi:[0,1,0]
	v_fma_mix_f32 v12, v7, v36, v12 op_sel:[0,1,0] op_sel_hi:[0,1,0]
	v_fma_mix_f32 v12, v8, v37, v12 op_sel_hi:[0,1,0]
	v_fma_mix_f32 v12, v9, v37, v12 op_sel:[0,1,0] op_sel_hi:[0,1,0]
	v_fma_mix_f32 v122, v6, v22, v180 op_sel_hi:[0,1,0]
	v_fma_mix_f32 v122, v7, v22, v122 op_sel:[0,1,0] op_sel_hi:[0,1,0]
	v_add_f32_dpp v12, v12, v12 row_ror:1 row_mask:0xf bank_mask:0xf bound_ctrl:1
	v_fma_mix_f32 v122, v8, v23, v122 op_sel_hi:[0,1,0]
	v_fma_mix_f32 v122, v9, v23, v122 op_sel:[0,1,0] op_sel_hi:[0,1,0]
	v_add_f32_dpp v12, v12, v12 row_ror:2 row_mask:0xf bank_mask:0xf bound_ctrl:1
	v_pk_fma_f32 v[48:49], v[44:45], v[66:67], v[6:7] op_sel:[0,1,0]
	v_pk_fma_f32 v[50:51], v[46:47], v[66:67], v[8:9] op_sel:[0,1,0]
	v_add_f32_dpp v12, v12, v12 row_ror:4 row_mask:0xf bank_mask:0xf bound_ctrl:1
	v_add_f32_dpp v83, v83, v83 row_ror:8 row_mask:0xf bank_mask:0xc
	v_add_f32_dpp v83, v52, v52 row_ror:8 row_mask:0xf bank_mask:0x3
	v_add_f32_dpp v100, v100, v100 row_ror:8 row_mask:0xf bank_mask:0xc
	v_add_f32_dpp v12, v12, v12 row_ror:8 row_mask:0xf bank_mask:0xf bound_ctrl:1
	v_pk_fma_f32 v[6:7], v[40:41], v[12:13], v[48:49] op_sel_hi:[1,0,1] neg_lo:[1,0,0] neg_hi:[1,0,0]
	v_pk_fma_f32 v[8:9], v[42:43], v[12:13], v[50:51] op_sel_hi:[1,0,1] neg_lo:[1,0,0] neg_hi:[1,0,0]
	s_waitcnt lgkmcnt(1)
	s_nop 0
	ds_read_b128 v[20:23], v10 offset:53504
	ds_read_b128 v[28:31], v10 offset:54016
	ds_read_b128 v[24:27], v10 offset:53760
	v_fma_mix_f32 v12, v6, v88, v180 op_sel_hi:[0,1,0]
	v_fma_mix_f32 v12, v7, v88, v12 op_sel:[0,1,0] op_sel_hi:[0,1,0]
	v_fma_mix_f32 v12, v8, v89, v12 op_sel_hi:[0,1,0]
	v_fma_mix_f32 v12, v9, v89, v12 op_sel:[0,1,0] op_sel_hi:[0,1,0]
	v_fma_mix_f32 v123, v6, v38, v180 op_sel_hi:[0,1,0]
	v_fma_mix_f32 v123, v7, v38, v123 op_sel:[0,1,0] op_sel_hi:[0,1,0]
	v_add_f32_dpp v12, v12, v12 row_ror:1 row_mask:0xf bank_mask:0xf bound_ctrl:1
	v_fma_mix_f32 v123, v8, v39, v123 op_sel_hi:[0,1,0]
	v_fma_mix_f32 v123, v9, v39, v123 op_sel:[0,1,0] op_sel_hi:[0,1,0]
	v_add_f32_dpp v12, v12, v12 row_ror:2 row_mask:0xf bank_mask:0xf bound_ctrl:1
	v_pk_fma_f32 v[48:49], v[96:97], v[68:69], v[6:7] op_sel_hi:[1,0,1]
	v_pk_fma_f32 v[50:51], v[98:99], v[68:69], v[8:9] op_sel_hi:[1,0,1]
	v_add_f32_dpp v12, v12, v12 row_ror:4 row_mask:0xf bank_mask:0xf bound_ctrl:1
	v_add_f32_dpp v100, v53, v53 row_ror:8 row_mask:0xf bank_mask:0x3
	v_add_f32_dpp v101, v101, v101 row_ror:8 row_mask:0xf bank_mask:0xc
	v_add_f32_dpp v101, v54, v54 row_ror:8 row_mask:0xf bank_mask:0x3
	v_add_f32_dpp v12, v12, v12 row_ror:8 row_mask:0xf bank_mask:0xf bound_ctrl:1
	v_pk_fma_f32 v[6:7], v[92:93], v[12:13], v[48:49] op_sel_hi:[1,0,1] neg_lo:[1,0,0] neg_hi:[1,0,0]
	v_pk_fma_f32 v[8:9], v[94:95], v[12:13], v[50:51] op_sel_hi:[1,0,1] neg_lo:[1,0,0] neg_hi:[1,0,0]
	ds_read_b128 v[36:39], v10 offset:54528
	ds_read_b128 v[44:47], v10 offset:55040
	ds_read_b128 v[40:43], v10 offset:54784
	v_fma_mix_f32 v12, v6, v110, v180 op_sel_hi:[0,1,0]
	v_fma_mix_f32 v12, v7, v110, v12 op_sel:[0,1,0] op_sel_hi:[0,1,0]
	v_fma_mix_f32 v12, v8, v111, v12 op_sel_hi:[0,1,0]
	v_fma_mix_f32 v12, v9, v111, v12 op_sel:[0,1,0] op_sel_hi:[0,1,0]
	v_fma_mix_f32 v124, v6, v90, v180 op_sel_hi:[0,1,0]
	v_fma_mix_f32 v124, v7, v90, v124 op_sel:[0,1,0] op_sel_hi:[0,1,0]
	v_add_f32_dpp v12, v12, v12 row_ror:1 row_mask:0xf bank_mask:0xf bound_ctrl:1
	v_fma_mix_f32 v124, v8, v91, v124 op_sel_hi:[0,1,0]
	v_fma_mix_f32 v124, v9, v91, v124 op_sel:[0,1,0] op_sel_hi:[0,1,0]
	v_add_f32_dpp v12, v12, v12 row_ror:2 row_mask:0xf bank_mask:0xf bound_ctrl:1
	v_pk_fma_f32 v[48:49], v[118:119], v[68:69], v[6:7] op_sel:[0,1,0]
	v_pk_fma_f32 v[50:51], v[120:121], v[68:69], v[8:9] op_sel:[0,1,0]
	v_add_f32_dpp v12, v12, v12 row_ror:4 row_mask:0xf bank_mask:0xf bound_ctrl:1
	v_add_f32_dpp v102, v102, v102 row_ror:8 row_mask:0xf bank_mask:0xc
	v_add_f32_dpp v102, v55, v55 row_ror:8 row_mask:0xf bank_mask:0x3
	v_add_f32_dpp v103, v103, v103 row_ror:8 row_mask:0xf bank_mask:0xc
	v_add_f32_dpp v12, v12, v12 row_ror:8 row_mask:0xf bank_mask:0xf bound_ctrl:1
	v_pk_fma_f32 v[6:7], v[114:115], v[12:13], v[48:49] op_sel_hi:[1,0,1] neg_lo:[1,0,0] neg_hi:[1,0,0]
	v_pk_fma_f32 v[8:9], v[116:117], v[12:13], v[50:51] op_sel_hi:[1,0,1] neg_lo:[1,0,0] neg_hi:[1,0,0]
	v_pk_mul_f32 v[6:7], v[6:7], v[106:107]
	v_pk_mul_f32 v[8:9], v[8:9], v[108:109]
	s_waitcnt lgkmcnt(0)
	s_nop 0
	ds_read_b128 v[88:91], v10 offset:55552
	ds_read_b128 v[96:99], v10 offset:56064
	ds_read_b128 v[92:95], v10 offset:55808
	v_fma_mix_f32 v12, v6, v20, v180 op_sel_hi:[0,1,0]
	v_fma_mix_f32 v12, v7, v20, v12 op_sel:[0,1,0] op_sel_hi:[0,1,0]
	v_fma_mix_f32 v12, v8, v21, v12 op_sel_hi:[0,1,0]
	v_fma_mix_f32 v12, v9, v21, v12 op_sel:[0,1,0] op_sel_hi:[0,1,0]
	v_fma_mix_f32 v125, v6, v112, v180 op_sel_hi:[0,1,0]
	v_fma_mix_f32 v125, v7, v112, v125 op_sel:[0,1,0] op_sel_hi:[0,1,0]
	v_add_f32_dpp v12, v12, v12 row_ror:1 row_mask:0xf bank_mask:0xf bound_ctrl:1
	v_fma_mix_f32 v125, v8, v113, v125 op_sel_hi:[0,1,0]
	v_fma_mix_f32 v125, v9, v113, v125 op_sel:[0,1,0] op_sel_hi:[0,1,0]
	v_add_f32_dpp v12, v12, v12 row_ror:2 row_mask:0xf bank_mask:0xf bound_ctrl:1
	v_pk_fma_f32 v[48:49], v[28:29], v[70:71], v[6:7] op_sel_hi:[1,0,1]
	v_pk_fma_f32 v[50:51], v[30:31], v[70:71], v[8:9] op_sel_hi:[1,0,1]
	v_add_f32_dpp v12, v12, v12 row_ror:4 row_mask:0xf bank_mask:0xf bound_ctrl:1
	v_add_f32_dpp v103, v56, v56 row_ror:8 row_mask:0xf bank_mask:0x3
	v_add_f32_dpp v104, v104, v104 row_ror:8 row_mask:0xf bank_mask:0xc
	v_add_f32_dpp v104, v57, v57 row_ror:8 row_mask:0xf bank_mask:0x3
	v_add_f32_dpp v12, v12, v12 row_ror:8 row_mask:0xf bank_mask:0xf bound_ctrl:1
	v_pk_fma_f32 v[6:7], v[24:25], v[12:13], v[48:49] op_sel_hi:[1,0,1] neg_lo:[1,0,0] neg_hi:[1,0,0]
	v_pk_fma_f32 v[8:9], v[26:27], v[12:13], v[50:51] op_sel_hi:[1,0,1] neg_lo:[1,0,0] neg_hi:[1,0,0]
	ds_read_b128 v[110:113], v10 offset:56576
	ds_read_b128 v[106:109], v10 offset:56320
	ds_read_b128 v[118:121], v10 offset:57088
	ds_read_b128 v[114:117], v10 offset:56832
	ds_read_b128 v[66:69], v11 offset:3584
	v_fma_mix_f32 v12, v6, v36, v180 op_sel_hi:[0,1,0]
	v_fma_mix_f32 v12, v7, v36, v12 op_sel:[0,1,0] op_sel_hi:[0,1,0]
	v_fma_mix_f32 v12, v8, v37, v12 op_sel_hi:[0,1,0]
	v_fma_mix_f32 v12, v9, v37, v12 op_sel:[0,1,0] op_sel_hi:[0,1,0]
	v_fma_mix_f32 v126, v6, v22, v180 op_sel_hi:[0,1,0]
	v_fma_mix_f32 v126, v7, v22, v126 op_sel:[0,1,0] op_sel_hi:[0,1,0]
	v_add_f32_dpp v12, v12, v12 row_ror:1 row_mask:0xf bank_mask:0xf bound_ctrl:1
	v_fma_mix_f32 v126, v8, v23, v126 op_sel_hi:[0,1,0]
	v_fma_mix_f32 v126, v9, v23, v126 op_sel:[0,1,0] op_sel_hi:[0,1,0]
	v_add_f32_dpp v12, v12, v12 row_ror:2 row_mask:0xf bank_mask:0xf bound_ctrl:1
	v_pk_fma_f32 v[48:49], v[44:45], v[70:71], v[6:7] op_sel:[0,1,0]
	v_pk_fma_f32 v[50:51], v[46:47], v[70:71], v[8:9] op_sel:[0,1,0]
	v_add_f32_dpp v12, v12, v12 row_ror:4 row_mask:0xf bank_mask:0xf bound_ctrl:1
	v_add_f32_dpp v105, v105, v105 row_ror:8 row_mask:0xf bank_mask:0xc
	v_add_f32_dpp v105, v81, v81 row_ror:8 row_mask:0xf bank_mask:0x3
	v_add_f32_dpp v12, v12, v12 row_ror:8 row_mask:0xf bank_mask:0xf bound_ctrl:1
	v_pk_fma_f32 v[6:7], v[40:41], v[12:13], v[48:49] op_sel_hi:[1,0,1] neg_lo:[1,0,0] neg_hi:[1,0,0]
	v_pk_fma_f32 v[8:9], v[42:43], v[12:13], v[50:51] op_sel_hi:[1,0,1] neg_lo:[1,0,0] neg_hi:[1,0,0]
	s_waitcnt lgkmcnt(1)
	s_nop 0
	ds_read_b128 v[20:23], v10 offset:57600
	ds_read_b128 v[28:31], v10 offset:58112
	ds_read_b128 v[24:27], v10 offset:57856
	v_fma_mix_f32 v12, v6, v88, v180 op_sel_hi:[0,1,0]
	v_fma_mix_f32 v12, v7, v88, v12 op_sel:[0,1,0] op_sel_hi:[0,1,0]
	v_fma_mix_f32 v12, v8, v89, v12 op_sel_hi:[0,1,0]
	v_fma_mix_f32 v12, v9, v89, v12 op_sel:[0,1,0] op_sel_hi:[0,1,0]
	v_fma_mix_f32 v127, v6, v38, v180 op_sel_hi:[0,1,0]
	v_fma_mix_f32 v127, v7, v38, v127 op_sel:[0,1,0] op_sel_hi:[0,1,0]
	v_add_f32_dpp v12, v12, v12 row_ror:1 row_mask:0xf bank_mask:0xf bound_ctrl:1
	v_fma_mix_f32 v127, v8, v39, v127 op_sel_hi:[0,1,0]
	v_fma_mix_f32 v127, v9, v39, v127 op_sel:[0,1,0] op_sel_hi:[0,1,0]
	v_add_f32_dpp v12, v12, v12 row_ror:2 row_mask:0xf bank_mask:0xf bound_ctrl:1
	v_pk_fma_f32 v[48:49], v[96:97], v[72:73], v[6:7] op_sel_hi:[1,0,1]
	v_pk_fma_f32 v[50:51], v[98:99], v[72:73], v[8:9] op_sel_hi:[1,0,1]
	v_add_f32_dpp v12, v12, v12 row_ror:4 row_mask:0xf bank_mask:0xf bound_ctrl:1
	v_add_f32_dpp v61, v61, v61 row_ror:8 row_mask:0xf bank_mask:0xc
	v_add_f32_dpp v61, v82, v82 row_ror:8 row_mask:0xf bank_mask:0x3
	v_add_f32_dpp v12, v12, v12 row_ror:8 row_mask:0xf bank_mask:0xf bound_ctrl:1
	v_pk_fma_f32 v[6:7], v[92:93], v[12:13], v[48:49] op_sel_hi:[1,0,1] neg_lo:[1,0,0] neg_hi:[1,0,0]
	v_pk_fma_f32 v[8:9], v[94:95], v[12:13], v[50:51] op_sel_hi:[1,0,1] neg_lo:[1,0,0] neg_hi:[1,0,0]
	ds_read_b128 v[36:39], v10 offset:58624
	ds_read_b128 v[44:47], v10 offset:59136
	ds_read_b128 v[40:43], v10 offset:58880
	v_fma_mix_f32 v12, v6, v110, v180 op_sel_hi:[0,1,0]
	v_fma_mix_f32 v12, v7, v110, v12 op_sel:[0,1,0] op_sel_hi:[0,1,0]
	v_fma_mix_f32 v12, v8, v111, v12 op_sel_hi:[0,1,0]
	v_fma_mix_f32 v12, v9, v111, v12 op_sel:[0,1,0] op_sel_hi:[0,1,0]
	v_fma_mix_f32 v128, v6, v90, v180 op_sel_hi:[0,1,0]
	v_fma_mix_f32 v128, v7, v90, v128 op_sel:[0,1,0] op_sel_hi:[0,1,0]
	v_add_f32_dpp v12, v12, v12 row_ror:1 row_mask:0xf bank_mask:0xf bound_ctrl:1
	v_fma_mix_f32 v128, v8, v91, v128 op_sel_hi:[0,1,0]
	v_fma_mix_f32 v128, v9, v91, v128 op_sel:[0,1,0] op_sel_hi:[0,1,0]
	v_add_f32_dpp v12, v12, v12 row_ror:2 row_mask:0xf bank_mask:0xf bound_ctrl:1
	v_pk_fma_f32 v[48:49], v[118:119], v[72:73], v[6:7] op_sel:[0,1,0]
	v_pk_fma_f32 v[50:51], v[120:121], v[72:73], v[8:9] op_sel:[0,1,0]
	v_add_f32_dpp v12, v12, v12 row_ror:4 row_mask:0xf bank_mask:0xf bound_ctrl:1
	v_add_f32_dpp v103, v103, v103 row_ror:4 row_mask:0xf bank_mask:0xa
	v_add_f32_dpp v103, v83, v83 row_ror:12 row_mask:0xf bank_mask:0x5
	v_add_f32_dpp v104, v104, v104 row_ror:4 row_mask:0xf bank_mask:0xa
	v_add_f32_dpp v12, v12, v12 row_ror:8 row_mask:0xf bank_mask:0xf bound_ctrl:1
	v_pk_fma_f32 v[6:7], v[114:115], v[12:13], v[48:49] op_sel_hi:[1,0,1] neg_lo:[1,0,0] neg_hi:[1,0,0]
	v_pk_fma_f32 v[8:9], v[116:117], v[12:13], v[50:51] op_sel_hi:[1,0,1] neg_lo:[1,0,0] neg_hi:[1,0,0]
	v_pk_mul_f32 v[6:7], v[6:7], v[106:107]
	v_pk_mul_f32 v[8:9], v[8:9], v[108:109]
	s_waitcnt lgkmcnt(0)
	s_nop 0
	ds_read_b128 v[88:91], v10 offset:59648
	ds_read_b128 v[96:99], v10 offset:60160
	ds_read_b128 v[92:95], v10 offset:59904
	v_fma_mix_f32 v12, v6, v20, v180 op_sel_hi:[0,1,0]
	v_fma_mix_f32 v12, v7, v20, v12 op_sel:[0,1,0] op_sel_hi:[0,1,0]
	v_fma_mix_f32 v12, v8, v21, v12 op_sel_hi:[0,1,0]
	v_fma_mix_f32 v12, v9, v21, v12 op_sel:[0,1,0] op_sel_hi:[0,1,0]
	v_fma_mix_f32 v129, v6, v112, v180 op_sel_hi:[0,1,0]
	v_fma_mix_f32 v129, v7, v112, v129 op_sel:[0,1,0] op_sel_hi:[0,1,0]
	v_add_f32_dpp v12, v12, v12 row_ror:1 row_mask:0xf bank_mask:0xf bound_ctrl:1
	v_fma_mix_f32 v129, v8, v113, v129 op_sel_hi:[0,1,0]
	v_fma_mix_f32 v129, v9, v113, v129 op_sel:[0,1,0] op_sel_hi:[0,1,0]
	v_add_f32_dpp v12, v12, v12 row_ror:2 row_mask:0xf bank_mask:0xf bound_ctrl:1
	v_pk_fma_f32 v[48:49], v[28:29], v[66:67], v[6:7] op_sel_hi:[1,0,1]
	v_pk_fma_f32 v[50:51], v[30:31], v[66:67], v[8:9] op_sel_hi:[1,0,1]
	v_add_f32_dpp v12, v12, v12 row_ror:4 row_mask:0xf bank_mask:0xf bound_ctrl:1
	v_add_f32_dpp v104, v100, v100 row_ror:12 row_mask:0xf bank_mask:0x5
	v_add_f32_dpp v105, v105, v105 row_ror:4 row_mask:0xf bank_mask:0xa
	v_add_f32_dpp v105, v101, v101 row_ror:12 row_mask:0xf bank_mask:0x5
	v_add_f32_dpp v12, v12, v12 row_ror:8 row_mask:0xf bank_mask:0xf bound_ctrl:1
	v_pk_fma_f32 v[6:7], v[24:25], v[12:13], v[48:49] op_sel_hi:[1,0,1] neg_lo:[1,0,0] neg_hi:[1,0,0]
	v_pk_fma_f32 v[8:9], v[26:27], v[12:13], v[50:51] op_sel_hi:[1,0,1] neg_lo:[1,0,0] neg_hi:[1,0,0]
	ds_read_b128 v[110:113], v10 offset:60672
	ds_read_b128 v[106:109], v10 offset:60416
	ds_read_b128 v[118:121], v10 offset:61184
	ds_read_b128 v[114:117], v10 offset:60928
	ds_read_b128 v[70:73], v11 offset:3840
	v_fma_mix_f32 v12, v6, v36, v180 op_sel_hi:[0,1,0]
	v_fma_mix_f32 v12, v7, v36, v12 op_sel:[0,1,0] op_sel_hi:[0,1,0]
	v_fma_mix_f32 v12, v8, v37, v12 op_sel_hi:[0,1,0]
	v_fma_mix_f32 v12, v9, v37, v12 op_sel:[0,1,0] op_sel_hi:[0,1,0]
	v_fma_mix_f32 v130, v6, v22, v180 op_sel_hi:[0,1,0]
	v_fma_mix_f32 v130, v7, v22, v130 op_sel:[0,1,0] op_sel_hi:[0,1,0]
	v_add_f32_dpp v12, v12, v12 row_ror:1 row_mask:0xf bank_mask:0xf bound_ctrl:1
	v_fma_mix_f32 v130, v8, v23, v130 op_sel_hi:[0,1,0]
	v_fma_mix_f32 v130, v9, v23, v130 op_sel:[0,1,0] op_sel_hi:[0,1,0]
	v_add_f32_dpp v12, v12, v12 row_ror:2 row_mask:0xf bank_mask:0xf bound_ctrl:1
	v_pk_fma_f32 v[48:49], v[44:45], v[66:67], v[6:7] op_sel:[0,1,0]
	v_pk_fma_f32 v[50:51], v[46:47], v[66:67], v[8:9] op_sel:[0,1,0]
	v_add_f32_dpp v12, v12, v12 row_ror:4 row_mask:0xf bank_mask:0xf bound_ctrl:1
	v_add_f32_dpp v61, v61, v61 row_ror:4 row_mask:0xf bank_mask:0xa
	v_add_f32_dpp v61, v102, v102 row_ror:12 row_mask:0xf bank_mask:0x5
	v_add_f32_dpp v12, v12, v12 row_ror:8 row_mask:0xf bank_mask:0xf bound_ctrl:1
	v_pk_fma_f32 v[6:7], v[40:41], v[12:13], v[48:49] op_sel_hi:[1,0,1] neg_lo:[1,0,0] neg_hi:[1,0,0]
	v_pk_fma_f32 v[8:9], v[42:43], v[12:13], v[50:51] op_sel_hi:[1,0,1] neg_lo:[1,0,0] neg_hi:[1,0,0]
	s_waitcnt lgkmcnt(1)
	s_nop 0
	ds_read_b128 v[20:23], v10 offset:61696
	ds_read_b128 v[28:31], v10 offset:62208
	ds_read_b128 v[24:27], v10 offset:61952
	v_fma_mix_f32 v12, v6, v88, v180 op_sel_hi:[0,1,0]
	v_fma_mix_f32 v12, v7, v88, v12 op_sel:[0,1,0] op_sel_hi:[0,1,0]
	v_fma_mix_f32 v12, v8, v89, v12 op_sel_hi:[0,1,0]
	v_fma_mix_f32 v12, v9, v89, v12 op_sel:[0,1,0] op_sel_hi:[0,1,0]
	v_fma_mix_f32 v131, v6, v38, v180 op_sel_hi:[0,1,0]
	v_fma_mix_f32 v131, v7, v38, v131 op_sel:[0,1,0] op_sel_hi:[0,1,0]
	v_add_f32_dpp v12, v12, v12 row_ror:1 row_mask:0xf bank_mask:0xf bound_ctrl:1
	v_fma_mix_f32 v131, v8, v39, v131 op_sel_hi:[0,1,0]
	v_fma_mix_f32 v131, v9, v39, v131 op_sel:[0,1,0] op_sel_hi:[0,1,0]
	v_add_f32_dpp v12, v12, v12 row_ror:2 row_mask:0xf bank_mask:0xf bound_ctrl:1
	v_pk_fma_f32 v[48:49], v[96:97], v[68:69], v[6:7] op_sel_hi:[1,0,1]
	v_pk_fma_f32 v[50:51], v[98:99], v[68:69], v[8:9] op_sel_hi:[1,0,1]
	v_add_f32_dpp v12, v12, v12 row_ror:4 row_mask:0xf bank_mask:0xf bound_ctrl:1
	v_cndmask_b32_e64 v62, v105, v103, s[38:39]
	v_cndmask_b32_e64 v63, v103, v105, s[38:39]
	v_add_f32_dpp v12, v12, v12 row_ror:8 row_mask:0xf bank_mask:0xf bound_ctrl:1
	v_pk_fma_f32 v[6:7], v[92:93], v[12:13], v[48:49] op_sel_hi:[1,0,1] neg_lo:[1,0,0] neg_hi:[1,0,0]
	v_pk_fma_f32 v[8:9], v[94:95], v[12:13], v[50:51] op_sel_hi:[1,0,1] neg_lo:[1,0,0] neg_hi:[1,0,0]
	ds_read_b128 v[36:39], v10 offset:62720
	ds_read_b128 v[44:47], v10 offset:63232
	ds_read_b128 v[40:43], v10 offset:62976
	v_fma_mix_f32 v12, v6, v110, v180 op_sel_hi:[0,1,0]
	v_fma_mix_f32 v12, v7, v110, v12 op_sel:[0,1,0] op_sel_hi:[0,1,0]
	v_fma_mix_f32 v12, v8, v111, v12 op_sel_hi:[0,1,0]
	v_fma_mix_f32 v12, v9, v111, v12 op_sel:[0,1,0] op_sel_hi:[0,1,0]
	v_fma_mix_f32 v132, v6, v90, v180 op_sel_hi:[0,1,0]
	v_fma_mix_f32 v132, v7, v90, v132 op_sel:[0,1,0] op_sel_hi:[0,1,0]
	v_add_f32_dpp v12, v12, v12 row_ror:1 row_mask:0xf bank_mask:0xf bound_ctrl:1
	v_fma_mix_f32 v132, v8, v91, v132 op_sel_hi:[0,1,0]
	v_fma_mix_f32 v132, v9, v91, v132 op_sel:[0,1,0] op_sel_hi:[0,1,0]
	v_add_f32_dpp v12, v12, v12 row_ror:2 row_mask:0xf bank_mask:0xf bound_ctrl:1
	v_pk_fma_f32 v[48:49], v[118:119], v[68:69], v[6:7] op_sel:[0,1,0]
	v_pk_fma_f32 v[50:51], v[120:121], v[68:69], v[8:9] op_sel:[0,1,0]
	v_add_f32_dpp v12, v12, v12 row_ror:4 row_mask:0xf bank_mask:0xf bound_ctrl:1
	v_cndmask_b32_e64 v64, v61, v104, s[38:39]
	v_cndmask_b32_e64 v65, v104, v61, s[38:39]
	v_add_f32_dpp v12, v12, v12 row_ror:8 row_mask:0xf bank_mask:0xf bound_ctrl:1
	v_pk_fma_f32 v[6:7], v[114:115], v[12:13], v[48:49] op_sel_hi:[1,0,1] neg_lo:[1,0,0] neg_hi:[1,0,0]
	v_pk_fma_f32 v[8:9], v[116:117], v[12:13], v[50:51] op_sel_hi:[1,0,1] neg_lo:[1,0,0] neg_hi:[1,0,0]
	v_pk_mul_f32 v[6:7], v[6:7], v[106:107]
	v_pk_mul_f32 v[8:9], v[8:9], v[108:109]
	s_waitcnt lgkmcnt(0)
	s_nop 0
	ds_read_b128 v[88:91], v10 offset:63744
	ds_read_b128 v[96:99], v10 offset:64256
	ds_read_b128 v[92:95], v10 offset:64000
	v_fma_mix_f32 v12, v6, v20, v180 op_sel_hi:[0,1,0]
	v_fma_mix_f32 v12, v7, v20, v12 op_sel:[0,1,0] op_sel_hi:[0,1,0]
	v_fma_mix_f32 v12, v8, v21, v12 op_sel_hi:[0,1,0]
	v_fma_mix_f32 v12, v9, v21, v12 op_sel:[0,1,0] op_sel_hi:[0,1,0]
	v_fma_mix_f32 v133, v6, v112, v180 op_sel_hi:[0,1,0]
	v_fma_mix_f32 v133, v7, v112, v133 op_sel:[0,1,0] op_sel_hi:[0,1,0]
	v_add_f32_dpp v12, v12, v12 row_ror:1 row_mask:0xf bank_mask:0xf bound_ctrl:1
	v_fma_mix_f32 v133, v8, v113, v133 op_sel_hi:[0,1,0]
	v_fma_mix_f32 v133, v9, v113, v133 op_sel:[0,1,0] op_sel_hi:[0,1,0]
	v_add_f32_dpp v12, v12, v12 row_ror:2 row_mask:0xf bank_mask:0xf bound_ctrl:1
	v_pk_fma_f32 v[48:49], v[28:29], v[70:71], v[6:7] op_sel_hi:[1,0,1]
	v_pk_fma_f32 v[50:51], v[30:31], v[70:71], v[8:9] op_sel_hi:[1,0,1]
	v_add_f32_dpp v12, v12, v12 row_ror:4 row_mask:0xf bank_mask:0xf bound_ctrl:1
	v_add_f32_dpp v62, v63, v62 quad_perm:[2,3,0,1] row_mask:0xf bank_mask:0xf bound_ctrl:1
	v_add_f32_dpp v63, v65, v64 quad_perm:[2,3,0,1] row_mask:0xf bank_mask:0xf bound_ctrl:1
	v_add_f32_dpp v12, v12, v12 row_ror:8 row_mask:0xf bank_mask:0xf bound_ctrl:1
	v_pk_fma_f32 v[6:7], v[24:25], v[12:13], v[48:49] op_sel_hi:[1,0,1] neg_lo:[1,0,0] neg_hi:[1,0,0]
	v_pk_fma_f32 v[8:9], v[26:27], v[12:13], v[50:51] op_sel_hi:[1,0,1] neg_lo:[1,0,0] neg_hi:[1,0,0]
	ds_read_b128 v[110:113], v10 offset:64768
	ds_read_b128 v[106:109], v10 offset:64512
	ds_read_b128 v[118:121], v10 offset:65280
	ds_read_b128 v[114:117], v10 offset:65024
	v_fma_mix_f32 v12, v6, v36, v180 op_sel_hi:[0,1,0]
	v_fma_mix_f32 v12, v7, v36, v12 op_sel:[0,1,0] op_sel_hi:[0,1,0]
	v_fma_mix_f32 v12, v8, v37, v12 op_sel_hi:[0,1,0]
	v_fma_mix_f32 v12, v9, v37, v12 op_sel:[0,1,0] op_sel_hi:[0,1,0]
	v_fma_mix_f32 v134, v6, v22, v180 op_sel_hi:[0,1,0]
	v_fma_mix_f32 v134, v7, v22, v134 op_sel:[0,1,0] op_sel_hi:[0,1,0]
	v_add_f32_dpp v12, v12, v12 row_ror:1 row_mask:0xf bank_mask:0xf bound_ctrl:1
	v_fma_mix_f32 v134, v8, v23, v134 op_sel_hi:[0,1,0]
	v_fma_mix_f32 v134, v9, v23, v134 op_sel:[0,1,0] op_sel_hi:[0,1,0]
	v_add_f32_dpp v12, v12, v12 row_ror:2 row_mask:0xf bank_mask:0xf bound_ctrl:1
	v_pk_fma_f32 v[48:49], v[44:45], v[70:71], v[6:7] op_sel:[0,1,0]
	v_pk_fma_f32 v[50:51], v[46:47], v[70:71], v[8:9] op_sel:[0,1,0]
	v_add_f32_dpp v12, v12, v12 row_ror:4 row_mask:0xf bank_mask:0xf bound_ctrl:1
	v_cndmask_b32_e64 v65, v63, v62, s[40:41]
	v_cndmask_b32_e64 v62, v62, v63, s[40:41]
	v_add_f32_dpp v12, v12, v12 row_ror:8 row_mask:0xf bank_mask:0xf bound_ctrl:1
	v_pk_fma_f32 v[6:7], v[40:41], v[12:13], v[48:49] op_sel_hi:[1,0,1] neg_lo:[1,0,0] neg_hi:[1,0,0]
	v_pk_fma_f32 v[8:9], v[42:43], v[12:13], v[50:51] op_sel_hi:[1,0,1] neg_lo:[1,0,0] neg_hi:[1,0,0]
	s_waitcnt lgkmcnt(0)
	s_nop 0
	v_fma_mix_f32 v12, v6, v88, v180 op_sel_hi:[0,1,0]
	v_fma_mix_f32 v12, v7, v88, v12 op_sel:[0,1,0] op_sel_hi:[0,1,0]
	v_fma_mix_f32 v12, v8, v89, v12 op_sel_hi:[0,1,0]
	v_fma_mix_f32 v12, v9, v89, v12 op_sel:[0,1,0] op_sel_hi:[0,1,0]
	v_fma_mix_f32 v135, v6, v38, v180 op_sel_hi:[0,1,0]
	v_fma_mix_f32 v135, v7, v38, v135 op_sel:[0,1,0] op_sel_hi:[0,1,0]
	v_add_f32_dpp v12, v12, v12 row_ror:1 row_mask:0xf bank_mask:0xf bound_ctrl:1
	v_fma_mix_f32 v135, v8, v39, v135 op_sel_hi:[0,1,0]
	v_fma_mix_f32 v135, v9, v39, v135 op_sel:[0,1,0] op_sel_hi:[0,1,0]
	v_add_f32_dpp v12, v12, v12 row_ror:2 row_mask:0xf bank_mask:0xf bound_ctrl:1
	v_pk_fma_f32 v[48:49], v[96:97], v[72:73], v[6:7] op_sel_hi:[1,0,1]
	v_pk_fma_f32 v[50:51], v[98:99], v[72:73], v[8:9] op_sel_hi:[1,0,1]
	v_add_f32_dpp v12, v12, v12 row_ror:4 row_mask:0xf bank_mask:0xf bound_ctrl:1
	v_add_f32_dpp v62, v62, v65 quad_perm:[1,0,3,2] row_mask:0xf bank_mask:0xf bound_ctrl:1
	v_cvt_pk_bf16_f32 v62, v62, v62
	v_add_f32_dpp v12, v12, v12 row_ror:8 row_mask:0xf bank_mask:0xf bound_ctrl:1
	v_pk_fma_f32 v[6:7], v[92:93], v[12:13], v[48:49] op_sel_hi:[1,0,1] neg_lo:[1,0,0] neg_hi:[1,0,0]
	v_pk_fma_f32 v[8:9], v[94:95], v[12:13], v[50:51] op_sel_hi:[1,0,1] neg_lo:[1,0,0] neg_hi:[1,0,0]
	s_waitcnt lgkmcnt(0)
	s_barrier
	v_xor_b32_e32 v10, 0x10000, v10
	v_xor_b32_e32 v11, 0x1000, v11
	ds_read_b128 v[66:69], v11 offset:0
	ds_read_b128 v[20:23], v10 offset:256
	ds_read_b128 v[28:31], v10 offset:768
	ds_read_b128 v[24:27], v10 offset:512
	ds_read_b128 v[36:39], v10 offset:1280
	ds_read_b128 v[44:47], v10 offset:1792
	ds_read_b128 v[40:43], v10 offset:1536
	v_fma_mix_f32 v12, v6, v110, v180 op_sel_hi:[0,1,0]
	v_fma_mix_f32 v12, v7, v110, v12 op_sel:[0,1,0] op_sel_hi:[0,1,0]
	v_fma_mix_f32 v12, v8, v111, v12 op_sel_hi:[0,1,0]
	v_fma_mix_f32 v12, v9, v111, v12 op_sel:[0,1,0] op_sel_hi:[0,1,0]
	v_fma_mix_f32 v136, v6, v90, v180 op_sel_hi:[0,1,0]
	v_fma_mix_f32 v136, v7, v90, v136 op_sel:[0,1,0] op_sel_hi:[0,1,0]
	v_add_f32_dpp v12, v12, v12 row_ror:1 row_mask:0xf bank_mask:0xf bound_ctrl:1
	v_fma_mix_f32 v136, v8, v91, v136 op_sel_hi:[0,1,0]
	v_fma_mix_f32 v136, v9, v91, v136 op_sel:[0,1,0] op_sel_hi:[0,1,0]
	v_add_f32_dpp v12, v12, v12 row_ror:2 row_mask:0xf bank_mask:0xf bound_ctrl:1
	v_pk_fma_f32 v[48:49], v[118:119], v[72:73], v[6:7] op_sel:[0,1,0]
	v_pk_fma_f32 v[50:51], v[120:121], v[72:73], v[8:9] op_sel:[0,1,0]
	v_add_f32_dpp v12, v12, v12 row_ror:4 row_mask:0xf bank_mask:0xf bound_ctrl:1
	global_store_short v[2:3], v62, off
	v_lshl_add_u64 v[2:3], v[2:3], 0, s[84:85]
	v_add_f32_dpp v12, v12, v12 row_ror:8 row_mask:0xf bank_mask:0xf bound_ctrl:1
	v_pk_fma_f32 v[6:7], v[114:115], v[12:13], v[48:49] op_sel_hi:[1,0,1] neg_lo:[1,0,0] neg_hi:[1,0,0]
	v_pk_fma_f32 v[8:9], v[116:117], v[12:13], v[50:51] op_sel_hi:[1,0,1] neg_lo:[1,0,0] neg_hi:[1,0,0]
	v_pk_mul_f32 v[6:7], v[6:7], v[106:107]
	v_pk_mul_f32 v[8:9], v[8:9], v[108:109]
	v_fma_mix_f32 v137, v6, v112, v180 op_sel_hi:[0,1,0]
	v_fma_mix_f32 v137, v7, v112, v137 op_sel:[0,1,0] op_sel_hi:[0,1,0]
	v_fma_mix_f32 v137, v8, v113, v137 op_sel_hi:[0,1,0]
	v_fma_mix_f32 v137, v9, v113, v137 op_sel:[0,1,0] op_sel_hi:[0,1,0]
	v_mov_b32_e64 v170, v2
	v_mov_b32_e64 v171, v3
	s_mov_b64 s[100:101], -1
	s_nop 0
	s_cmp_lg_u32 s28, 0x800000
	s_cbranch_scc1 .Lscan_cons_chunk
	v_add_f32_dpp v130, v130, v130 row_ror:8 row_mask:0xf bank_mask:0xc
	v_add_f32_dpp v130, v122, v122 row_ror:8 row_mask:0xf bank_mask:0x3
	v_add_f32_dpp v131, v131, v131 row_ror:8 row_mask:0xf bank_mask:0xc
	v_add_f32_dpp v131, v123, v123 row_ror:8 row_mask:0xf bank_mask:0x3
	v_add_f32_dpp v132, v132, v132 row_ror:8 row_mask:0xf bank_mask:0xc
	v_add_f32_dpp v132, v124, v124 row_ror:8 row_mask:0xf bank_mask:0x3
	v_add_f32_dpp v133, v133, v133 row_ror:8 row_mask:0xf bank_mask:0xc
	v_add_f32_dpp v133, v125, v125 row_ror:8 row_mask:0xf bank_mask:0x3
	v_add_f32_dpp v134, v134, v134 row_ror:8 row_mask:0xf bank_mask:0xc
	v_add_f32_dpp v134, v126, v126 row_ror:8 row_mask:0xf bank_mask:0x3
	v_add_f32_dpp v135, v135, v135 row_ror:8 row_mask:0xf bank_mask:0xc
	v_add_f32_dpp v135, v127, v127 row_ror:8 row_mask:0xf bank_mask:0x3
	v_add_f32_dpp v136, v136, v136 row_ror:8 row_mask:0xf bank_mask:0xc
	v_add_f32_dpp v136, v128, v128 row_ror:8 row_mask:0xf bank_mask:0x3
	v_add_f32_dpp v137, v137, v137 row_ror:8 row_mask:0xf bank_mask:0xc
	v_add_f32_dpp v137, v129, v129 row_ror:8 row_mask:0xf bank_mask:0x3
	v_add_f32_dpp v134, v134, v134 row_ror:4 row_mask:0xf bank_mask:0xa
	v_add_f32_dpp v134, v130, v130 row_ror:12 row_mask:0xf bank_mask:0x5
	v_add_f32_dpp v135, v135, v135 row_ror:4 row_mask:0xf bank_mask:0xa
	v_add_f32_dpp v135, v131, v131 row_ror:12 row_mask:0xf bank_mask:0x5
	v_add_f32_dpp v136, v136, v136 row_ror:4 row_mask:0xf bank_mask:0xa
	v_add_f32_dpp v136, v132, v132 row_ror:12 row_mask:0xf bank_mask:0x5
	v_add_f32_dpp v137, v137, v137 row_ror:4 row_mask:0xf bank_mask:0xa
	v_add_f32_dpp v137, v133, v133 row_ror:12 row_mask:0xf bank_mask:0x5
	v_cndmask_b32_e64 v62, v136, v134, s[38:39]
	v_cndmask_b32_e64 v63, v134, v136, s[38:39]
	v_cndmask_b32_e64 v64, v137, v135, s[38:39]
	v_cndmask_b32_e64 v65, v135, v137, s[38:39]
	v_add_f32_dpp v62, v63, v62 quad_perm:[2,3,0,1] row_mask:0xf bank_mask:0xf bound_ctrl:1
	s_nop 0
	v_add_f32_dpp v63, v65, v64 quad_perm:[2,3,0,1] row_mask:0xf bank_mask:0xf bound_ctrl:1
	v_cndmask_b32_e64 v65, v63, v62, s[40:41]
	v_cndmask_b32_e64 v62, v62, v63, s[40:41]
	s_nop 1
	v_add_f32_dpp v62, v62, v65 quad_perm:[1,0,3,2] row_mask:0xf bank_mask:0xf bound_ctrl:1
	v_cvt_pk_bf16_f32 v62, v62, v62
	global_store_short v[2:3], v62, off
	s_branch .LBB0_53
.LBB0_59:
	v_readlane_b32 s10, v241, 22
	v_readlane_b32 s11, v241, 23
	v_or_b32_e32 v66, s37, v14
	v_lshlrev_b32_e32 v66, 2, v66
	s_and_b64 s[16:17], s[42:43], exec
	s_mov_b32 s12, 0x10000
	s_cselect_b32 s12, s12, 0xffff0000
	s_movk_i32 s13, 0x400
	s_cselect_b32 s13, s13, 0xfffffc00
	s_cselect_b32 s4, 0, 0x2000000
	s_add_u32 s28, s30, 0xaaf0000
	s_addc_u32 s29, s31, 0
	s_add_u32 s28, s28, s4
	s_addc_u32 s29, s29, 0
	s_add_u32 s34, s28, 0x4000000
	s_addc_u32 s35, s29, 0
	s_add_u32 s8, s30, 0x19af0000
	s_addc_u32 s9, s31, 0
	s_add_u32 s14, s30, 0x17af0000
	s_addc_u32 s15, s31, 0
	global_load_dwordx4 v[106:109], v66, s[10:11]
	v_lshlrev_b32_e32 v67, 2, v61
	v_sub_u32_e32 v68, 0x1fff, v67
	v_cndmask_b32_e64 v67, v68, v67, s[42:43]
	v_add_u32_e32 v67, s80, v67
	v_lshlrev_b32_e32 v67, 10, v67
	v_or_b32_e32 v68, s37, v14
	v_lshl_add_u32 v110, v68, 1, v67
	s_lshl_b32 s5, s64, 4
	s_add_i32 s5, s5, s37
	v_add_u32_e32 v68, s5, v15
	v_lshl_add_u32 v114, v68, 1, v67
	v_add_u32_e32 v111, s13, v110
	v_add_u32_e32 v115, s13, v114
	v_add_u32_e32 v112, s13, v111
	v_add_u32_e32 v116, s13, v115
	v_add_u32_e32 v113, s13, v112
	v_add_u32_e32 v117, s13, v116
	v_lshlrev_b32_e32 v119, 12, v61
	v_lshl_or_b32 v119, v15, 4, v119
	v_lshlrev_b32_e32 v123, 8, v61
	v_lshl_or_b32 v123, v15, 4, v123
	v_add_u32_e32 v123, 0x22000, v123
	global_load_dwordx2 v[16:17], v110, s[44:45]
	global_load_dwordx2 v[18:19], v110, s[46:47]
	global_load_dwordx2 v[20:21], v110, s[8:9]
	global_load_dwordx2 v[22:23], v110, s[34:35]
	global_load_dwordx2 v[24:25], v110, s[28:29]
	global_load_ushort v26, v114, s[14:15]
	global_load_dwordx2 v[28:29], v111, s[44:45]
	global_load_dwordx2 v[30:31], v111, s[46:47]
	global_load_dwordx2 v[32:33], v111, s[8:9]
	global_load_dwordx2 v[34:35], v111, s[34:35]
	global_load_dwordx2 v[36:37], v111, s[28:29]
	global_load_ushort v38, v115, s[14:15]
	global_load_dwordx2 v[40:41], v112, s[44:45]
	global_load_dwordx2 v[42:43], v112, s[46:47]
	global_load_dwordx2 v[44:45], v112, s[8:9]
	global_load_dwordx2 v[46:47], v112, s[34:35]
	global_load_dwordx2 v[48:49], v112, s[28:29]
	global_load_ushort v50, v116, s[14:15]
	global_load_dwordx2 v[52:53], v113, s[44:45]
	global_load_dwordx2 v[54:55], v113, s[46:47]
	global_load_dwordx2 v[56:57], v113, s[8:9]
	global_load_dwordx2 v[58:59], v113, s[34:35]
	global_load_dwordx2 v[60:61], v113, s[28:29]
	global_load_ushort v62, v117, s[14:15]
	v_add_u32_e32 v110, s12, v110
	v_add_u32_e32 v114, s12, v114
	v_add_u32_e32 v111, s12, v111
	v_add_u32_e32 v115, s12, v115
	v_add_u32_e32 v112, s12, v112
	v_add_u32_e32 v116, s12, v116
	v_add_u32_e32 v113, s12, v113
	v_add_u32_e32 v117, s12, v117
	s_waitcnt vmcnt(0)
	v_cvt_f32_f16_e32 v124, v24
	v_cvt_f32_f16_sdwa v125, v24 dst_sel:DWORD dst_unused:UNUSED_PAD src0_sel:WORD_1
	v_cvt_f32_f16_e32 v126, v25
	v_cvt_f32_f16_sdwa v127, v25 dst_sel:DWORD dst_unused:UNUSED_PAD src0_sel:WORD_1
	v_cvt_f32_f16_e32 v128, v36
	v_cvt_f32_f16_sdwa v129, v36 dst_sel:DWORD dst_unused:UNUSED_PAD src0_sel:WORD_1
	v_cvt_f32_f16_e32 v130, v37
	v_cvt_f32_f16_sdwa v131, v37 dst_sel:DWORD dst_unused:UNUSED_PAD src0_sel:WORD_1
	v_cvt_f32_f16_e32 v132, v48
	v_cvt_f32_f16_sdwa v133, v48 dst_sel:DWORD dst_unused:UNUSED_PAD src0_sel:WORD_1
	v_cvt_f32_f16_e32 v134, v49
	v_cvt_f32_f16_sdwa v135, v49 dst_sel:DWORD dst_unused:UNUSED_PAD src0_sel:WORD_1
	v_cvt_f32_f16_e32 v136, v60
	v_cvt_f32_f16_sdwa v137, v60 dst_sel:DWORD dst_unused:UNUSED_PAD src0_sel:WORD_1
	v_cvt_f32_f16_e32 v138, v61
	v_cvt_f32_f16_sdwa v139, v61 dst_sel:DWORD dst_unused:UNUSED_PAD src0_sel:WORD_1
	v_pk_add_f32 v[128:129], v[128:129], v[124:125]
	v_pk_add_f32 v[130:131], v[130:131], v[126:127]
	v_pk_add_f32 v[132:133], v[132:133], v[128:129]
	v_pk_add_f32 v[134:135], v[134:135], v[130:131]
	v_pk_add_f32 v[136:137], v[136:137], v[132:133]
	v_pk_add_f32 v[138:139], v[138:139], v[134:135]
	v_exp_f32_e64 v140, -v124
	v_exp_f32_e64 v141, -v125
	v_exp_f32_e64 v142, -v126
	v_exp_f32_e64 v143, -v127
	v_exp_f32_e64 v144, -v128
	v_exp_f32_e64 v145, -v129
	v_exp_f32_e64 v146, -v130
	v_exp_f32_e64 v147, -v131
	v_exp_f32_e64 v148, -v132
	v_exp_f32_e64 v149, -v133
	v_exp_f32_e64 v150, -v134
	v_exp_f32_e64 v151, -v135
	v_exp_f32_e64 v152, -v136
	v_exp_f32_e64 v153, -v137
	v_exp_f32_e64 v154, -v138
	v_exp_f32_e64 v155, -v139
	v_exp_f32_e32 v156, v124
	v_exp_f32_e32 v157, v125
	v_exp_f32_e32 v158, v126
	v_exp_f32_e32 v159, v127
	v_exp_f32_e32 v160, v128
	v_exp_f32_e32 v161, v129
	v_exp_f32_e32 v162, v130
	v_exp_f32_e32 v163, v131
	v_exp_f32_e32 v164, v132
	v_exp_f32_e32 v165, v133
	v_exp_f32_e32 v166, v134
	v_exp_f32_e32 v167, v135
	v_exp_f32_e32 v168, v136
	v_exp_f32_e32 v169, v137
	v_exp_f32_e32 v170, v138
	v_exp_f32_e32 v171, v139
	v_cvt_f32_f16_e32 v68, v22
	v_cvt_f32_f16_sdwa v69, v22 dst_sel:DWORD dst_unused:UNUSED_PAD src0_sel:WORD_1
	v_cvt_f32_f16_e32 v70, v23
	v_cvt_f32_f16_sdwa v71, v23 dst_sel:DWORD dst_unused:UNUSED_PAD src0_sel:WORD_1
	v_lshlrev_b32_e32 v72, 16, v20
	v_and_b32_e32 v73, 0xffff0000, v20
	v_lshlrev_b32_e32 v74, 16, v21
	v_and_b32_e32 v75, 0xffff0000, v21
	v_lshlrev_b32_e32 v76, 16, v18
	v_and_b32_e32 v77, 0xffff0000, v18
	v_lshlrev_b32_e32 v78, 16, v19
	v_and_b32_e32 v79, 0xffff0000, v19
	v_lshlrev_b32_e32 v80, 16, v16
	v_and_b32_e32 v81, 0xffff0000, v16
	v_lshlrev_b32_e32 v82, 16, v17
	v_and_b32_e32 v83, 0xffff0000, v17
	v_pk_mul_f32 v[84:85], v[72:73], v[68:69]
	v_pk_mul_f32 v[86:87], v[74:75], v[70:71]
	v_pk_add_f32 v[88:89], v[68:69], -1.0 op_sel_hi:[1,0]
	v_pk_add_f32 v[90:91], v[70:71], -1.0 op_sel_hi:[1,0]
	v_pk_fma_f32 v[88:89], v[106:107], v[88:89], 1.0 op_sel_hi:[1,1,0]
	v_pk_fma_f32 v[90:91], v[108:109], v[90:91], 1.0 op_sel_hi:[1,1,0]
	v_pk_mul_f32 v[84:85], v[84:85], v[156:157]
	v_pk_mul_f32 v[86:87], v[86:87], v[158:159]
	v_pk_mul_f32 v[88:89], v[88:89], v[76:77]
	v_pk_mul_f32 v[90:91], v[90:91], v[78:79]
	ds_write_b128 v119, v[84:87] offset:512
	v_pk_mul_f32 v[88:89], v[88:89], v[156:157]
	v_pk_mul_f32 v[90:91], v[90:91], v[158:159]
	v_pk_mul_f32 v[80:81], v[80:81], v[140:141]
	v_pk_mul_f32 v[82:83], v[82:83], v[142:143]
	ds_write_b128 v119, v[88:91] offset:768
	v_lshlrev_b32_e32 v96, 16, v26
	v_cvt_pk_f16_f32 v92, v72, v73
	v_cvt_pk_f16_f32 v93, v74, v75
	v_cvt_pk_f16_f32 v94, v80, v81
	v_cvt_pk_f16_f32 v95, v82, v83
	ds_write_b128 v119, v[92:95] offset:256
	v_cvt_f32_f16_e32 v68, v34
	v_cvt_f32_f16_sdwa v69, v34 dst_sel:DWORD dst_unused:UNUSED_PAD src0_sel:WORD_1
	v_cvt_f32_f16_e32 v70, v35
	v_cvt_f32_f16_sdwa v71, v35 dst_sel:DWORD dst_unused:UNUSED_PAD src0_sel:WORD_1
	v_lshlrev_b32_e32 v72, 16, v32
	v_and_b32_e32 v73, 0xffff0000, v32
	v_lshlrev_b32_e32 v74, 16, v33
	v_and_b32_e32 v75, 0xffff0000, v33
	v_lshlrev_b32_e32 v76, 16, v30
	v_and_b32_e32 v77, 0xffff0000, v30
	v_lshlrev_b32_e32 v78, 16, v31
	v_and_b32_e32 v79, 0xffff0000, v31
	v_lshlrev_b32_e32 v80, 16, v28
	v_and_b32_e32 v81, 0xffff0000, v28
	v_lshlrev_b32_e32 v82, 16, v29
	v_and_b32_e32 v83, 0xffff0000, v29
	v_pk_mul_f32 v[84:85], v[72:73], v[68:69]
	v_pk_mul_f32 v[86:87], v[74:75], v[70:71]
	v_pk_add_f32 v[88:89], v[68:69], -1.0 op_sel_hi:[1,0]
	v_pk_add_f32 v[90:91], v[70:71], -1.0 op_sel_hi:[1,0]
	v_pk_fma_f32 v[88:89], v[106:107], v[88:89], 1.0 op_sel_hi:[1,1,0]
	v_pk_fma_f32 v[90:91], v[108:109], v[90:91], 1.0 op_sel_hi:[1,1,0]
	v_pk_mul_f32 v[84:85], v[84:85], v[160:161]
	v_pk_mul_f32 v[86:87], v[86:87], v[162:163]
	v_pk_mul_f32 v[88:89], v[88:89], v[76:77]
	v_pk_mul_f32 v[90:91], v[90:91], v[78:79]
	ds_write_b128 v119, v[84:87] offset:1536
	v_pk_mul_f32 v[88:89], v[88:89], v[160:161]
	v_pk_mul_f32 v[90:91], v[90:91], v[162:163]
	v_pk_mul_f32 v[72:73], v[72:73], v[140:141]
	v_pk_mul_f32 v[74:75], v[74:75], v[142:143]
	v_pk_mul_f32 v[80:81], v[80:81], v[144:145]
	v_pk_mul_f32 v[82:83], v[82:83], v[146:147]
	ds_write_b128 v119, v[88:91] offset:1792
	v_lshlrev_b32_e32 v97, 16, v38
	v_cvt_pk_f16_f32 v92, v72, v73
	v_cvt_pk_f16_f32 v93, v74, v75
	v_cvt_pk_f16_f32 v94, v80, v81
	v_cvt_pk_f16_f32 v95, v82, v83
	ds_write_b128 v119, v[92:95] offset:1280
	v_cvt_f32_f16_e32 v68, v46
	v_cvt_f32_f16_sdwa v69, v46 dst_sel:DWORD dst_unused:UNUSED_PAD src0_sel:WORD_1
	v_cvt_f32_f16_e32 v70, v47
	v_cvt_f32_f16_sdwa v71, v47 dst_sel:DWORD dst_unused:UNUSED_PAD src0_sel:WORD_1
	v_lshlrev_b32_e32 v72, 16, v44
	v_and_b32_e32 v73, 0xffff0000, v44
	v_lshlrev_b32_e32 v74, 16, v45
	v_and_b32_e32 v75, 0xffff0000, v45
	v_lshlrev_b32_e32 v76, 16, v42
	v_and_b32_e32 v77, 0xffff0000, v42
	v_lshlrev_b32_e32 v78, 16, v43
	v_and_b32_e32 v79, 0xffff0000, v43
	v_lshlrev_b32_e32 v80, 16, v40
	v_and_b32_e32 v81, 0xffff0000, v40
	v_lshlrev_b32_e32 v82, 16, v41
	v_and_b32_e32 v83, 0xffff0000, v41
	v_pk_mul_f32 v[84:85], v[72:73], v[68:69]
	v_pk_mul_f32 v[86:87], v[74:75], v[70:71]
	v_pk_add_f32 v[88:89], v[68:69], -1.0 op_sel_hi:[1,0]
	v_pk_add_f32 v[90:91], v[70:71], -1.0 op_sel_hi:[1,0]
	v_pk_fma_f32 v[88:89], v[106:107], v[88:89], 1.0 op_sel_hi:[1,1,0]
	v_pk_fma_f32 v[90:91], v[108:109], v[90:91], 1.0 op_sel_hi:[1,1,0]
	v_pk_mul_f32 v[84:85], v[84:85], v[164:165]
	v_pk_mul_f32 v[86:87], v[86:87], v[166:167]
	v_pk_mul_f32 v[88:89], v[88:89], v[76:77]
	v_pk_mul_f32 v[90:91], v[90:91], v[78:79]
	ds_write_b128 v119, v[84:87] offset:2560
	v_pk_mul_f32 v[88:89], v[88:89], v[164:165]
	v_pk_mul_f32 v[90:91], v[90:91], v[166:167]
	v_pk_mul_f32 v[72:73], v[72:73], v[144:145]
	v_pk_mul_f32 v[74:75], v[74:75], v[146:147]
	v_pk_mul_f32 v[80:81], v[80:81], v[148:149]
	v_pk_mul_f32 v[82:83], v[82:83], v[150:151]
	ds_write_b128 v119, v[88:91] offset:2816
	v_lshlrev_b32_e32 v98, 16, v50
	v_cvt_pk_f16_f32 v92, v72, v73
	v_cvt_pk_f16_f32 v93, v74, v75
	v_cvt_pk_f16_f32 v94, v80, v81
	v_cvt_pk_f16_f32 v95, v82, v83
	ds_write_b128 v119, v[92:95] offset:2304
	v_cvt_f32_f16_e32 v68, v58
	v_cvt_f32_f16_sdwa v69, v58 dst_sel:DWORD dst_unused:UNUSED_PAD src0_sel:WORD_1
	v_cvt_f32_f16_e32 v70, v59
	v_cvt_f32_f16_sdwa v71, v59 dst_sel:DWORD dst_unused:UNUSED_PAD src0_sel:WORD_1
	v_lshlrev_b32_e32 v72, 16, v56
	v_and_b32_e32 v73, 0xffff0000, v56
	v_lshlrev_b32_e32 v74, 16, v57
	v_and_b32_e32 v75, 0xffff0000, v57
	v_lshlrev_b32_e32 v76, 16, v54
	v_and_b32_e32 v77, 0xffff0000, v54
	v_lshlrev_b32_e32 v78, 16, v55
	v_and_b32_e32 v79, 0xffff0000, v55
	v_lshlrev_b32_e32 v80, 16, v52
	v_and_b32_e32 v81, 0xffff0000, v52
	v_lshlrev_b32_e32 v82, 16, v53
	v_and_b32_e32 v83, 0xffff0000, v53
	v_pk_mul_f32 v[84:85], v[72:73], v[68:69]
	v_pk_mul_f32 v[86:87], v[74:75], v[70:71]
	v_pk_add_f32 v[88:89], v[68:69], -1.0 op_sel_hi:[1,0]
	v_pk_add_f32 v[90:91], v[70:71], -1.0 op_sel_hi:[1,0]
	v_pk_fma_f32 v[88:89], v[106:107], v[88:89], 1.0 op_sel_hi:[1,1,0]
	v_pk_fma_f32 v[90:91], v[108:109], v[90:91], 1.0 op_sel_hi:[1,1,0]
	v_pk_mul_f32 v[84:85], v[84:85], v[168:169]
	v_pk_mul_f32 v[86:87], v[86:87], v[170:171]
	v_pk_mul_f32 v[88:89], v[88:89], v[76:77]
	v_pk_mul_f32 v[90:91], v[90:91], v[78:79]
	ds_write_b128 v119, v[84:87] offset:3584
	v_pk_mul_f32 v[88:89], v[88:89], v[168:169]
	v_pk_mul_f32 v[90:91], v[90:91], v[170:171]
	v_pk_mul_f32 v[72:73], v[72:73], v[148:149]
	v_pk_mul_f32 v[74:75], v[74:75], v[150:151]
	ds_write_b128 v119, v[88:91] offset:3840
	v_lshlrev_b32_e32 v99, 16, v62
	v_cvt_pk_f16_f32 v92, v72, v73
	v_cvt_pk_f16_f32 v93, v74, v75
	v_cvt_pk_f16_f32 v94, v80, v81
	v_cvt_pk_f16_f32 v95, v82, v83
	ds_write_b128 v119, v[92:95] offset:3328
	ds_write_b128 v119, v[152:155] offset:3072
	ds_write_b128 v123, v[96:99]
	global_load_dwordx2 v[16:17], v110, s[44:45]
	global_load_dwordx2 v[18:19], v110, s[46:47]
	global_load_dwordx2 v[20:21], v110, s[8:9]
	global_load_dwordx2 v[22:23], v110, s[34:35]
	global_load_dwordx2 v[24:25], v110, s[28:29]
	global_load_ushort v26, v114, s[14:15]
	global_load_dwordx2 v[28:29], v111, s[44:45]
	global_load_dwordx2 v[30:31], v111, s[46:47]
	global_load_dwordx2 v[32:33], v111, s[8:9]
	global_load_dwordx2 v[34:35], v111, s[34:35]
	global_load_dwordx2 v[36:37], v111, s[28:29]
	global_load_ushort v38, v115, s[14:15]
	global_load_dwordx2 v[40:41], v112, s[44:45]
	global_load_dwordx2 v[42:43], v112, s[46:47]
	global_load_dwordx2 v[44:45], v112, s[8:9]
	global_load_dwordx2 v[46:47], v112, s[34:35]
	global_load_dwordx2 v[48:49], v112, s[28:29]
	global_load_ushort v50, v116, s[14:15]
	global_load_dwordx2 v[52:53], v113, s[44:45]
	global_load_dwordx2 v[54:55], v113, s[46:47]
	global_load_dwordx2 v[56:57], v113, s[8:9]
	global_load_dwordx2 v[58:59], v113, s[34:35]
	global_load_dwordx2 v[60:61], v113, s[28:29]
	global_load_ushort v62, v117, s[14:15]
	v_add_u32_e32 v110, s12, v110
	v_add_u32_e32 v114, s12, v114
	v_add_u32_e32 v111, s12, v111
	v_add_u32_e32 v115, s12, v115
	v_add_u32_e32 v112, s12, v112
	v_add_u32_e32 v116, s12, v116
	v_add_u32_e32 v113, s12, v113
	v_add_u32_e32 v117, s12, v117
	s_waitcnt lgkmcnt(0)
	s_barrier
	s_mov_b32 s6, 0
	s_nop 0
	s_nop 0
	s_nop 0
	s_nop 0
	s_nop 0
	s_nop 0
	s_nop 0
	s_nop 0
	s_nop 0
	s_nop 0
	s_nop 0
	s_nop 0
	s_nop 0
	s_nop 0
	s_nop 0
.Lprod_loop:
	s_cmp_eq_u32 s6, 0x7f
	s_cbranch_scc1 .Lprod_bar
	s_nop 0
	v_xor_b32_e32 v119, 0x10000, v119
	v_xor_b32_e32 v123, 0x1000, v123
	s_waitcnt vmcnt(0)
	s_nop 0
	v_cvt_f32_f16_e64 v124, v24
	v_cvt_f32_f16_sdwa v125, v24 dst_sel:DWORD dst_unused:UNUSED_PAD src0_sel:WORD_1
	v_cvt_f32_f16_e64 v126, v25
	v_cvt_f32_f16_sdwa v127, v25 dst_sel:DWORD dst_unused:UNUSED_PAD src0_sel:WORD_1
	v_cvt_f32_f16_e64 v128, v36
	v_cvt_f32_f16_sdwa v129, v36 dst_sel:DWORD dst_unused:UNUSED_PAD src0_sel:WORD_1
	v_cvt_f32_f16_e64 v130, v37
	v_cvt_f32_f16_sdwa v131, v37 dst_sel:DWORD dst_unused:UNUSED_PAD src0_sel:WORD_1
	v_cvt_f32_f16_e64 v132, v48
	v_cvt_f32_f16_sdwa v133, v48 dst_sel:DWORD dst_unused:UNUSED_PAD src0_sel:WORD_1
	v_cvt_f32_f16_e64 v134, v49
	v_cvt_f32_f16_sdwa v135, v49 dst_sel:DWORD dst_unused:UNUSED_PAD src0_sel:WORD_1
	v_cvt_f32_f16_e64 v136, v60
	v_cvt_f32_f16_sdwa v137, v60 dst_sel:DWORD dst_unused:UNUSED_PAD src0_sel:WORD_1
	v_cvt_f32_f16_e64 v138, v61
	v_cvt_f32_f16_sdwa v139, v61 dst_sel:DWORD dst_unused:UNUSED_PAD src0_sel:WORD_1
	v_pk_add_f32 v[128:129], v[128:129], v[124:125]
	v_pk_add_f32 v[130:131], v[130:131], v[126:127]
	v_pk_add_f32 v[132:133], v[132:133], v[128:129]
	v_pk_add_f32 v[134:135], v[134:135], v[130:131]
	v_pk_add_f32 v[136:137], v[136:137], v[132:133]
	v_pk_add_f32 v[138:139], v[138:139], v[134:135]
	v_exp_f32_e64 v140, -v124
	v_exp_f32_e64 v141, -v125
	v_exp_f32_e64 v142, -v126
	v_exp_f32_e64 v143, -v127
	v_exp_f32_e64 v144, -v128
	v_exp_f32_e64 v145, -v129
	v_exp_f32_e64 v146, -v130
	v_exp_f32_e64 v147, -v131
	v_exp_f32_e64 v148, -v132
	v_exp_f32_e64 v149, -v133
	v_exp_f32_e64 v150, -v134
	v_exp_f32_e64 v151, -v135
	v_exp_f32_e64 v152, -v136
	v_exp_f32_e64 v153, -v137
	v_exp_f32_e64 v154, -v138
	v_exp_f32_e64 v155, -v139
	v_exp_f32_e64 v156, v124
	v_exp_f32_e64 v157, v125
	v_exp_f32_e64 v158, v126
	v_exp_f32_e64 v159, v127
	v_exp_f32_e64 v160, v128
	v_exp_f32_e64 v161, v129
	v_exp_f32_e64 v162, v130
	v_exp_f32_e64 v163, v131
	v_exp_f32_e64 v164, v132
	v_exp_f32_e64 v165, v133
	v_exp_f32_e64 v166, v134
	v_exp_f32_e64 v167, v135
	v_exp_f32_e64 v168, v136
	v_exp_f32_e64 v169, v137
	v_exp_f32_e64 v170, v138
	v_exp_f32_e64 v171, v139
	v_cvt_f32_f16_e64 v68, v22
	v_cvt_f32_f16_sdwa v69, v22 dst_sel:DWORD dst_unused:UNUSED_PAD src0_sel:WORD_1
	v_cvt_f32_f16_e64 v70, v23
	v_cvt_f32_f16_sdwa v71, v23 dst_sel:DWORD dst_unused:UNUSED_PAD src0_sel:WORD_1
	v_lshlrev_b32_e64 v72, 16, v20
	v_and_b32_e32 v73, 0xffff0000, v20
	v_lshlrev_b32_e64 v74, 16, v21
	v_and_b32_e32 v75, 0xffff0000, v21
	v_lshlrev_b32_e64 v76, 16, v18
	v_and_b32_e32 v77, 0xffff0000, v18
	v_lshlrev_b32_e64 v78, 16, v19
	v_and_b32_e32 v79, 0xffff0000, v19
	v_lshlrev_b32_e64 v80, 16, v16
	v_and_b32_e32 v81, 0xffff0000, v16
	v_lshlrev_b32_e64 v82, 16, v17
	v_and_b32_e32 v83, 0xffff0000, v17
	v_pk_mul_f32 v[84:85], v[72:73], v[68:69]
	v_pk_mul_f32 v[86:87], v[74:75], v[70:71]
	v_pk_add_f32 v[88:89], v[68:69], -1.0 op_sel_hi:[1,0]
	v_pk_add_f32 v[90:91], v[70:71], -1.0 op_sel_hi:[1,0]
	v_pk_fma_f32 v[88:89], v[106:107], v[88:89], 1.0 op_sel_hi:[1,1,0]
	v_pk_fma_f32 v[90:91], v[108:109], v[90:91], 1.0 op_sel_hi:[1,1,0]
	v_pk_mul_f32 v[84:85], v[84:85], v[156:157]
	v_pk_mul_f32 v[86:87], v[86:87], v[158:159]
	v_pk_mul_f32 v[88:89], v[88:89], v[76:77]
	v_pk_mul_f32 v[90:91], v[90:91], v[78:79]
	ds_write_b128 v119, v[84:87] offset:512
	v_pk_mul_f32 v[88:89], v[88:89], v[156:157]
	v_pk_mul_f32 v[90:91], v[90:91], v[158:159]
	v_pk_mul_f32 v[80:81], v[80:81], v[140:141]
	v_pk_mul_f32 v[82:83], v[82:83], v[142:143]
	ds_write_b128 v119, v[88:91] offset:768
	v_lshlrev_b32_e64 v96, 16, v26
	v_cvt_pk_f16_f32 v92, v72, v73
	v_cvt_pk_f16_f32 v93, v74, v75
	v_cvt_pk_f16_f32 v94, v80, v81
	v_cvt_pk_f16_f32 v95, v82, v83
	ds_write_b128 v119, v[92:95] offset:256
	v_cvt_f32_f16_e64 v68, v34
	v_cvt_f32_f16_sdwa v69, v34 dst_sel:DWORD dst_unused:UNUSED_PAD src0_sel:WORD_1
	v_cvt_f32_f16_e64 v70, v35
	v_cvt_f32_f16_sdwa v71, v35 dst_sel:DWORD dst_unused:UNUSED_PAD src0_sel:WORD_1
	v_lshlrev_b32_e64 v72, 16, v32
	v_and_b32_e32 v73, 0xffff0000, v32
	v_lshlrev_b32_e64 v74, 16, v33
	v_and_b32_e32 v75, 0xffff0000, v33
	v_lshlrev_b32_e64 v76, 16, v30
	v_and_b32_e32 v77, 0xffff0000, v30
	v_lshlrev_b32_e64 v78, 16, v31
	v_and_b32_e32 v79, 0xffff0000, v31
	v_lshlrev_b32_e64 v80, 16, v28
	v_and_b32_e32 v81, 0xffff0000, v28
	v_lshlrev_b32_e64 v82, 16, v29
	v_and_b32_e32 v83, 0xffff0000, v29
	v_pk_mul_f32 v[84:85], v[72:73], v[68:69]
	v_pk_mul_f32 v[86:87], v[74:75], v[70:71]
	v_pk_add_f32 v[88:89], v[68:69], -1.0 op_sel_hi:[1,0]
	v_pk_add_f32 v[90:91], v[70:71], -1.0 op_sel_hi:[1,0]
	v_pk_fma_f32 v[88:89], v[106:107], v[88:89], 1.0 op_sel_hi:[1,1,0]
	v_pk_fma_f32 v[90:91], v[108:109], v[90:91], 1.0 op_sel_hi:[1,1,0]
	v_pk_mul_f32 v[84:85], v[84:85], v[160:161]
	v_pk_mul_f32 v[86:87], v[86:87], v[162:163]
	v_pk_mul_f32 v[88:89], v[88:89], v[76:77]
	v_pk_mul_f32 v[90:91], v[90:91], v[78:79]
	ds_write_b128 v119, v[84:87] offset:1536
	v_pk_mul_f32 v[88:89], v[88:89], v[160:161]
	v_pk_mul_f32 v[90:91], v[90:91], v[162:163]
	v_pk_mul_f32 v[72:73], v[72:73], v[140:141]
	v_pk_mul_f32 v[74:75], v[74:75], v[142:143]
	v_pk_mul_f32 v[80:81], v[80:81], v[144:145]
	v_pk_mul_f32 v[82:83], v[82:83], v[146:147]
	ds_write_b128 v119, v[88:91] offset:1792
	v_lshlrev_b32_e64 v97, 16, v38
	v_cvt_pk_f16_f32 v92, v72, v73
	v_cvt_pk_f16_f32 v93, v74, v75
	v_cvt_pk_f16_f32 v94, v80, v81
	v_cvt_pk_f16_f32 v95, v82, v83
	ds_write_b128 v119, v[92:95] offset:1280
	v_cvt_f32_f16_e64 v68, v46
	v_cvt_f32_f16_sdwa v69, v46 dst_sel:DWORD dst_unused:UNUSED_PAD src0_sel:WORD_1
	v_cvt_f32_f16_e64 v70, v47
	v_cvt_f32_f16_sdwa v71, v47 dst_sel:DWORD dst_unused:UNUSED_PAD src0_sel:WORD_1
	v_lshlrev_b32_e64 v72, 16, v44
	v_and_b32_e32 v73, 0xffff0000, v44
	v_lshlrev_b32_e64 v74, 16, v45
	v_and_b32_e32 v75, 0xffff0000, v45
	v_lshlrev_b32_e64 v76, 16, v42
	v_and_b32_e32 v77, 0xffff0000, v42
	v_lshlrev_b32_e64 v78, 16, v43
	v_and_b32_e32 v79, 0xffff0000, v43
	v_lshlrev_b32_e64 v80, 16, v40
	v_and_b32_e32 v81, 0xffff0000, v40
	v_lshlrev_b32_e64 v82, 16, v41
	v_and_b32_e32 v83, 0xffff0000, v41
	v_pk_mul_f32 v[84:85], v[72:73], v[68:69]
	v_pk_mul_f32 v[86:87], v[74:75], v[70:71]
	v_pk_add_f32 v[88:89], v[68:69], -1.0 op_sel_hi:[1,0]
	v_pk_add_f32 v[90:91], v[70:71], -1.0 op_sel_hi:[1,0]
	v_pk_fma_f32 v[88:89], v[106:107], v[88:89], 1.0 op_sel_hi:[1,1,0]
	v_pk_fma_f32 v[90:91], v[108:109], v[90:91], 1.0 op_sel_hi:[1,1,0]
	v_pk_mul_f32 v[84:85], v[84:85], v[164:165]
	v_pk_mul_f32 v[86:87], v[86:87], v[166:167]
	v_pk_mul_f32 v[88:89], v[88:89], v[76:77]
	v_pk_mul_f32 v[90:91], v[90:91], v[78:79]
	ds_write_b128 v119, v[84:87] offset:2560
	v_pk_mul_f32 v[88:89], v[88:89], v[164:165]
	v_pk_mul_f32 v[90:91], v[90:91], v[166:167]
	v_pk_mul_f32 v[72:73], v[72:73], v[144:145]
	v_pk_mul_f32 v[74:75], v[74:75], v[146:147]
	v_pk_mul_f32 v[80:81], v[80:81], v[148:149]
	v_pk_mul_f32 v[82:83], v[82:83], v[150:151]
	ds_write_b128 v119, v[88:91] offset:2816
	v_lshlrev_b32_e64 v98, 16, v50
	v_cvt_pk_f16_f32 v92, v72, v73
	v_cvt_pk_f16_f32 v93, v74, v75
	v_cvt_pk_f16_f32 v94, v80, v81
	v_cvt_pk_f16_f32 v95, v82, v83
	ds_write_b128 v119, v[92:95] offset:2304
	v_cvt_f32_f16_e64 v68, v58
	v_cvt_f32_f16_sdwa v69, v58 dst_sel:DWORD dst_unused:UNUSED_PAD src0_sel:WORD_1
	v_cvt_f32_f16_e64 v70, v59
	v_cvt_f32_f16_sdwa v71, v59 dst_sel:DWORD dst_unused:UNUSED_PAD src0_sel:WORD_1
	v_lshlrev_b32_e64 v72, 16, v56
	v_and_b32_e32 v73, 0xffff0000, v56
	v_lshlrev_b32_e64 v74, 16, v57
	v_and_b32_e32 v75, 0xffff0000, v57
	v_lshlrev_b32_e64 v76, 16, v54
	v_and_b32_e32 v77, 0xffff0000, v54
	v_lshlrev_b32_e64 v78, 16, v55
	v_and_b32_e32 v79, 0xffff0000, v55
	v_lshlrev_b32_e64 v80, 16, v52
	v_and_b32_e32 v81, 0xffff0000, v52
	v_lshlrev_b32_e64 v82, 16, v53
	v_and_b32_e32 v83, 0xffff0000, v53
	v_pk_mul_f32 v[84:85], v[72:73], v[68:69]
	v_pk_mul_f32 v[86:87], v[74:75], v[70:71]
	v_pk_add_f32 v[88:89], v[68:69], -1.0 op_sel_hi:[1,0]
	v_pk_add_f32 v[90:91], v[70:71], -1.0 op_sel_hi:[1,0]
	v_pk_fma_f32 v[88:89], v[106:107], v[88:89], 1.0 op_sel_hi:[1,1,0]
	v_pk_fma_f32 v[90:91], v[108:109], v[90:91], 1.0 op_sel_hi:[1,1,0]
	v_pk_mul_f32 v[84:85], v[84:85], v[168:169]
	v_pk_mul_f32 v[86:87], v[86:87], v[170:171]
	v_pk_mul_f32 v[88:89], v[88:89], v[76:77]
	v_pk_mul_f32 v[90:91], v[90:91], v[78:79]
	ds_write_b128 v119, v[84:87] offset:3584
	v_pk_mul_f32 v[88:89], v[88:89], v[168:169]
	v_pk_mul_f32 v[90:91], v[90:91], v[170:171]
	v_pk_mul_f32 v[72:73], v[72:73], v[148:149]
	v_pk_mul_f32 v[74:75], v[74:75], v[150:151]
	ds_write_b128 v119, v[88:91] offset:3840
	v_lshlrev_b32_e64 v99, 16, v62
	v_cvt_pk_f16_f32 v92, v72, v73
	v_cvt_pk_f16_f32 v93, v74, v75
	v_cvt_pk_f16_f32 v94, v80, v81
	v_cvt_pk_f16_f32 v95, v82, v83
	ds_write_b128 v119, v[92:95] offset:3328
	ds_write_b128 v119, v[152:155] offset:3072
	ds_write_b128 v123, v[96:99]
	s_cmp_ge_u32 s6, 0x7e
	s_cbranch_scc1 .Lprod_bar
	s_nop 0
	global_load_dwordx2 v[16:17], v110, s[44:45]
	global_load_dwordx2 v[18:19], v110, s[46:47]
	global_load_dwordx2 v[20:21], v110, s[8:9]
	global_load_dwordx2 v[22:23], v110, s[34:35]
	global_load_dwordx2 v[24:25], v110, s[28:29]
	global_load_ushort v26, v114, s[14:15]
	global_load_dwordx2 v[28:29], v111, s[44:45]
	global_load_dwordx2 v[30:31], v111, s[46:47]
	global_load_dwordx2 v[32:33], v111, s[8:9]
	global_load_dwordx2 v[34:35], v111, s[34:35]
	global_load_dwordx2 v[36:37], v111, s[28:29]
	global_load_ushort v38, v115, s[14:15]
	global_load_dwordx2 v[40:41], v112, s[44:45]
	global_load_dwordx2 v[42:43], v112, s[46:47]
	global_load_dwordx2 v[44:45], v112, s[8:9]
	global_load_dwordx2 v[46:47], v112, s[34:35]
	global_load_dwordx2 v[48:49], v112, s[28:29]
	global_load_ushort v50, v116, s[14:15]
	global_load_dwordx2 v[52:53], v113, s[44:45]
	global_load_dwordx2 v[54:55], v113, s[46:47]
	global_load_dwordx2 v[56:57], v113, s[8:9]
	global_load_dwordx2 v[58:59], v113, s[34:35]
	global_load_dwordx2 v[60:61], v113, s[28:29]
	global_load_ushort v62, v117, s[14:15]
	v_add_u32_e64 v110, s12, v110
	v_add_u32_e64 v114, s12, v114
	v_add_u32_e64 v111, s12, v111
	v_add_u32_e64 v115, s12, v115
	v_add_u32_e64 v112, s12, v112
	v_add_u32_e64 v116, s12, v116
	v_add_u32_e64 v113, s12, v113
	v_add_u32_e64 v117, s12, v117
